# v25 plus the mid-block s_setprio 0/1 pair removed in all 7 K-loops (priority stays raised across the 32-MFMA block)
# speedup vs baseline: 1.0139x; 1.0003x over previous
.LBB0_131:
	s_add_u32 s60, s57, 0xffffff80
	s_addc_u32 s61, s58, -1
	s_cmp_eq_u32 s59, 60
	s_cselect_b32 s36, s17, s57
	s_cselect_b32 s37, s7, s58
	s_cselect_b32 s39, s21, s56
	s_cselect_b32 s38, s33, s55
	s_add_u32 s30, s36, 0x80
	s_addc_u32 s31, s37, 0
	s_add_u32 s34, s38, 0x80
	s_addc_u32 s35, s39, 0
	s_add_i32 s62, 0, 0x10000
	s_add_i32 s63, 0, 0x14000
	v_add_u32_e32 v152, s62, v1
	v_add_u32_e32 v168, s63, v1
	ds_read_b128 v[140:143], v152
	ds_read_b128 v[144:147], v152 offset:1024
	ds_read_b128 v[148:151], v152 offset:2048
	ds_read_b128 v[152:155], v152 offset:3072
	ds_read_b128 v[156:159], v168
	ds_read_b128 v[160:163], v168 offset:1024
	ds_read_b128 v[164:167], v168 offset:2048
	ds_read_b128 v[168:171], v168 offset:3072
	s_add_u32 s60, s60, 0x100000
	s_addc_u32 s61, s61, 0
	v_lshl_add_u64 v[204:205], s[60:61], 0, v[2:3]
	s_add_i32 m0, s29, 0xc000
	ds_read_b128 v[172:175], v5
	ds_read_b128 v[176:179], v5 offset:1024
	ds_read_b128 v[180:183], v5 offset:2048
	ds_read_b128 v[184:187], v5 offset:3072
	ds_read_b128 v[188:191], v5 offset:4096
	ds_read_b128 v[192:195], v5 offset:5120
	ds_read_b128 v[196:199], v5 offset:6144
	ds_read_b128 v[200:203], v5 offset:7168
	global_load_lds_dwordx4 v[204:205], off
	v_lshl_add_u64 v[204:205], s[60:61], 0, v[136:137]
	s_add_i32 m0, s29, 0xe000
	s_nop 0
	global_load_lds_dwordx4 v[204:205], off
	s_waitcnt vmcnt(8)
	s_waitcnt lgkmcnt(0)
	s_barrier
	s_setprio 1
	v_mfma_f32_16x16x32_bf16 v[130:133], v[140:143], v[172:175], v[130:133]
	v_mfma_f32_16x16x32_bf16 v[126:129], v[148:151], v[172:175], v[126:129]
	v_mfma_f32_16x16x32_bf16 v[114:117], v[140:143], v[180:183], v[114:117]
	v_mfma_f32_16x16x32_bf16 v[110:113], v[148:151], v[180:183], v[110:113]
	v_mfma_f32_16x16x32_bf16 v[98:101], v[140:143], v[188:191], v[98:101]
	v_mfma_f32_16x16x32_bf16 v[94:97], v[148:151], v[188:191], v[94:97]
	v_mfma_f32_16x16x32_bf16 v[82:85], v[140:143], v[196:199], v[82:85]
	v_mfma_f32_16x16x32_bf16 v[78:81], v[148:151], v[196:199], v[78:81]
	v_mfma_f32_16x16x32_bf16 v[130:133], v[144:147], v[176:179], v[130:133]
	v_mfma_f32_16x16x32_bf16 v[126:129], v[152:155], v[176:179], v[126:129]
	v_mfma_f32_16x16x32_bf16 v[114:117], v[144:147], v[184:187], v[114:117]
	v_mfma_f32_16x16x32_bf16 v[110:113], v[152:155], v[184:187], v[110:113]
	v_mfma_f32_16x16x32_bf16 v[98:101], v[144:147], v[192:195], v[98:101]
	v_mfma_f32_16x16x32_bf16 v[94:97], v[152:155], v[192:195], v[94:97]
	v_mfma_f32_16x16x32_bf16 v[82:85], v[144:147], v[200:203], v[82:85]
	v_mfma_f32_16x16x32_bf16 v[78:81], v[152:155], v[200:203], v[78:81]
	v_mfma_f32_16x16x32_bf16 v[122:125], v[156:159], v[172:175], v[122:125]
	v_mfma_f32_16x16x32_bf16 v[118:121], v[164:167], v[172:175], v[118:121]
	v_mfma_f32_16x16x32_bf16 v[106:109], v[156:159], v[180:183], v[106:109]
	v_mfma_f32_16x16x32_bf16 v[102:105], v[164:167], v[180:183], v[102:105]
	v_mfma_f32_16x16x32_bf16 v[90:93], v[156:159], v[188:191], v[90:93]
	v_mfma_f32_16x16x32_bf16 v[86:89], v[164:167], v[188:191], v[86:89]
	v_mfma_f32_16x16x32_bf16 v[74:77], v[156:159], v[196:199], v[74:77]
	v_mfma_f32_16x16x32_bf16 v[70:73], v[164:167], v[196:199], v[70:73]
	v_mfma_f32_16x16x32_bf16 v[122:125], v[160:163], v[176:179], v[122:125]
	v_mfma_f32_16x16x32_bf16 v[118:121], v[168:171], v[176:179], v[118:121]
	v_mfma_f32_16x16x32_bf16 v[106:109], v[160:163], v[184:187], v[106:109]
	v_mfma_f32_16x16x32_bf16 v[102:105], v[168:171], v[184:187], v[102:105]
	v_mfma_f32_16x16x32_bf16 v[90:93], v[160:163], v[192:195], v[90:93]
	v_mfma_f32_16x16x32_bf16 v[86:89], v[168:171], v[192:195], v[86:89]
	v_mfma_f32_16x16x32_bf16 v[74:77], v[160:163], v[200:203], v[74:77]
	v_mfma_f32_16x16x32_bf16 v[70:73], v[168:171], v[200:203], v[70:73]
	s_setprio 0
	s_barrier
	s_add_i32 s60, s62, s42
	v_lshl_add_u64 v[204:205], s[38:39], 0, v[134:135]
	s_mov_b32 m0, s60
	ds_read_b128 v[172:175], v5 offset:16384
	ds_read_b128 v[176:179], v5 offset:17408
	ds_read_b128 v[180:183], v5 offset:18432
	ds_read_b128 v[184:187], v5 offset:19456
	ds_read_b128 v[188:191], v5 offset:20480
	ds_read_b128 v[192:195], v5 offset:21504
	ds_read_b128 v[196:199], v5 offset:22528
	ds_read_b128 v[200:203], v5 offset:23552
	global_load_lds_dwordx4 v[204:205], off
	s_add_i32 m0, s60, 0x2000
	v_lshl_add_u64 v[204:205], s[38:39], 0, v[138:139]
	s_add_u32 s38, s38, 0x100000
	s_addc_u32 s39, s39, 0
	s_add_i32 s60, s63, s42
	global_load_lds_dwordx4 v[204:205], off
	v_lshl_add_u64 v[204:205], s[38:39], 0, v[134:135]
	s_mov_b32 m0, s60
	s_nop 0
	global_load_lds_dwordx4 v[204:205], off
	v_lshl_add_u64 v[204:205], s[38:39], 0, v[138:139]
	s_add_i32 m0, s60, 0x2000
	s_nop 0
	global_load_lds_dwordx4 v[204:205], off
	v_lshl_add_u64 v[204:205], s[36:37], 0, v[2:3]
	s_mov_b32 m0, s29
	s_nop 0
	global_load_lds_dwordx4 v[204:205], off
	v_lshl_add_u64 v[204:205], s[36:37], 0, v[136:137]
	s_mov_b32 m0, s43
	s_nop 0
	global_load_lds_dwordx4 v[204:205], off
	s_waitcnt vmcnt(8)
	s_waitcnt lgkmcnt(0)
	s_barrier
	s_setprio 1
	v_mfma_f32_16x16x32_bf16 v[66:69], v[140:143], v[172:175], v[66:69]
	v_mfma_f32_16x16x32_bf16 v[62:65], v[148:151], v[172:175], v[62:65]
	v_mfma_f32_16x16x32_bf16 v[50:53], v[140:143], v[180:183], v[50:53]
	v_mfma_f32_16x16x32_bf16 v[46:49], v[148:151], v[180:183], v[46:49]
	v_mfma_f32_16x16x32_bf16 v[34:37], v[140:143], v[188:191], v[34:37]
	v_mfma_f32_16x16x32_bf16 v[30:33], v[148:151], v[188:191], v[30:33]
	v_mfma_f32_16x16x32_bf16 v[18:21], v[140:143], v[196:199], v[18:21]
	v_mfma_f32_16x16x32_bf16 v[14:17], v[148:151], v[196:199], v[14:17]
	v_mfma_f32_16x16x32_bf16 v[66:69], v[144:147], v[176:179], v[66:69]
	v_mfma_f32_16x16x32_bf16 v[62:65], v[152:155], v[176:179], v[62:65]
	v_mfma_f32_16x16x32_bf16 v[50:53], v[144:147], v[184:187], v[50:53]
	v_mfma_f32_16x16x32_bf16 v[46:49], v[152:155], v[184:187], v[46:49]
	v_mfma_f32_16x16x32_bf16 v[34:37], v[144:147], v[192:195], v[34:37]
	v_mfma_f32_16x16x32_bf16 v[30:33], v[152:155], v[192:195], v[30:33]
	v_mfma_f32_16x16x32_bf16 v[18:21], v[144:147], v[200:203], v[18:21]
	v_mfma_f32_16x16x32_bf16 v[14:17], v[152:155], v[200:203], v[14:17]
	v_mfma_f32_16x16x32_bf16 v[58:61], v[156:159], v[172:175], v[58:61]
	v_mfma_f32_16x16x32_bf16 v[54:57], v[164:167], v[172:175], v[54:57]
	v_mfma_f32_16x16x32_bf16 v[42:45], v[156:159], v[180:183], v[42:45]
	v_mfma_f32_16x16x32_bf16 v[38:41], v[164:167], v[180:183], v[38:41]
	v_mfma_f32_16x16x32_bf16 v[26:29], v[156:159], v[188:191], v[26:29]
	v_mfma_f32_16x16x32_bf16 v[22:25], v[164:167], v[188:191], v[22:25]
	v_mfma_f32_16x16x32_bf16 v[10:13], v[156:159], v[196:199], v[10:13]
	v_mfma_f32_16x16x32_bf16 v[6:9], v[164:167], v[196:199], v[6:9]
	v_mfma_f32_16x16x32_bf16 v[58:61], v[160:163], v[176:179], v[58:61]
	v_mfma_f32_16x16x32_bf16 v[54:57], v[168:171], v[176:179], v[54:57]
	v_mfma_f32_16x16x32_bf16 v[42:45], v[160:163], v[184:187], v[42:45]
	v_mfma_f32_16x16x32_bf16 v[38:41], v[168:171], v[184:187], v[38:41]
	v_mfma_f32_16x16x32_bf16 v[26:29], v[160:163], v[192:195], v[26:29]
	v_mfma_f32_16x16x32_bf16 v[22:25], v[168:171], v[192:195], v[22:25]
	v_mfma_f32_16x16x32_bf16 v[10:13], v[160:163], v[200:203], v[10:13]
	v_mfma_f32_16x16x32_bf16 v[6:9], v[168:171], v[200:203], v[6:9]
	s_setprio 0
	s_barrier
	s_add_i32 s38, 0, 0x18000
	s_add_i32 s39, 0, 0x1c000
	v_add_u32_e32 v152, s38, v1
	v_add_u32_e32 v168, s39, v1
	ds_read_b128 v[140:143], v152
	ds_read_b128 v[144:147], v152 offset:1024
	ds_read_b128 v[148:151], v152 offset:2048
	ds_read_b128 v[152:155], v152 offset:3072
	ds_read_b128 v[156:159], v168
	ds_read_b128 v[160:163], v168 offset:1024
	ds_read_b128 v[164:167], v168 offset:2048
	ds_read_b128 v[168:171], v168 offset:3072
	s_add_u32 s36, s36, 0x100000
	s_addc_u32 s37, s37, 0
	s_mov_b32 m0, s48
	v_lshl_add_u64 v[204:205], s[36:37], 0, v[2:3]
	ds_read_b128 v[172:175], v5 offset:32768
	ds_read_b128 v[176:179], v5 offset:33792
	ds_read_b128 v[180:183], v5 offset:34816
	ds_read_b128 v[184:187], v5 offset:35840
	ds_read_b128 v[188:191], v5 offset:36864
	ds_read_b128 v[192:195], v5 offset:37888
	ds_read_b128 v[196:199], v5 offset:38912
	ds_read_b128 v[200:203], v5 offset:39936
	global_load_lds_dwordx4 v[204:205], off
	v_lshl_add_u64 v[204:205], s[36:37], 0, v[136:137]
	s_mov_b32 m0, s49
	s_nop 0
	global_load_lds_dwordx4 v[204:205], off
	s_waitcnt vmcnt(8)
	s_waitcnt lgkmcnt(0)
	s_barrier
	s_setprio 1
	v_mfma_f32_16x16x32_bf16 v[130:133], v[140:143], v[172:175], v[130:133]
	v_mfma_f32_16x16x32_bf16 v[126:129], v[148:151], v[172:175], v[126:129]
	v_mfma_f32_16x16x32_bf16 v[114:117], v[140:143], v[180:183], v[114:117]
	v_mfma_f32_16x16x32_bf16 v[110:113], v[148:151], v[180:183], v[110:113]
	v_mfma_f32_16x16x32_bf16 v[98:101], v[140:143], v[188:191], v[98:101]
	v_mfma_f32_16x16x32_bf16 v[94:97], v[148:151], v[188:191], v[94:97]
	v_mfma_f32_16x16x32_bf16 v[82:85], v[140:143], v[196:199], v[82:85]
	v_mfma_f32_16x16x32_bf16 v[78:81], v[148:151], v[196:199], v[78:81]
	v_mfma_f32_16x16x32_bf16 v[130:133], v[144:147], v[176:179], v[130:133]
	v_mfma_f32_16x16x32_bf16 v[126:129], v[152:155], v[176:179], v[126:129]
	v_mfma_f32_16x16x32_bf16 v[114:117], v[144:147], v[184:187], v[114:117]
	v_mfma_f32_16x16x32_bf16 v[110:113], v[152:155], v[184:187], v[110:113]
	v_mfma_f32_16x16x32_bf16 v[98:101], v[144:147], v[192:195], v[98:101]
	v_mfma_f32_16x16x32_bf16 v[94:97], v[152:155], v[192:195], v[94:97]
	v_mfma_f32_16x16x32_bf16 v[82:85], v[144:147], v[200:203], v[82:85]
	v_mfma_f32_16x16x32_bf16 v[78:81], v[152:155], v[200:203], v[78:81]
	v_mfma_f32_16x16x32_bf16 v[122:125], v[156:159], v[172:175], v[122:125]
	v_mfma_f32_16x16x32_bf16 v[118:121], v[164:167], v[172:175], v[118:121]
	v_mfma_f32_16x16x32_bf16 v[106:109], v[156:159], v[180:183], v[106:109]
	v_mfma_f32_16x16x32_bf16 v[102:105], v[164:167], v[180:183], v[102:105]
	v_mfma_f32_16x16x32_bf16 v[90:93], v[156:159], v[188:191], v[90:93]
	v_mfma_f32_16x16x32_bf16 v[86:89], v[164:167], v[188:191], v[86:89]
	v_mfma_f32_16x16x32_bf16 v[74:77], v[156:159], v[196:199], v[74:77]
	v_mfma_f32_16x16x32_bf16 v[70:73], v[164:167], v[196:199], v[70:73]
	v_mfma_f32_16x16x32_bf16 v[122:125], v[160:163], v[176:179], v[122:125]
	v_mfma_f32_16x16x32_bf16 v[118:121], v[168:171], v[176:179], v[118:121]
	v_mfma_f32_16x16x32_bf16 v[106:109], v[160:163], v[184:187], v[106:109]
	v_mfma_f32_16x16x32_bf16 v[102:105], v[168:171], v[184:187], v[102:105]
	v_mfma_f32_16x16x32_bf16 v[90:93], v[160:163], v[192:195], v[90:93]
	v_mfma_f32_16x16x32_bf16 v[86:89], v[168:171], v[192:195], v[86:89]
	v_mfma_f32_16x16x32_bf16 v[74:77], v[160:163], v[200:203], v[74:77]
	v_mfma_f32_16x16x32_bf16 v[70:73], v[168:171], v[200:203], v[70:73]
	s_setprio 0
	s_barrier
	s_add_i32 s36, s38, s42
	v_lshl_add_u64 v[204:205], s[34:35], 0, v[134:135]
	s_mov_b32 m0, s36
	ds_read_b128 v[172:175], v5 offset:49152
	ds_read_b128 v[176:179], v5 offset:50176
	ds_read_b128 v[180:183], v5 offset:51200
	ds_read_b128 v[184:187], v5 offset:52224
	ds_read_b128 v[188:191], v5 offset:53248
	ds_read_b128 v[192:195], v5 offset:54272
	ds_read_b128 v[196:199], v5 offset:55296
	ds_read_b128 v[200:203], v5 offset:56320
	global_load_lds_dwordx4 v[204:205], off
	s_add_i32 m0, s36, 0x2000
	v_lshl_add_u64 v[204:205], s[34:35], 0, v[138:139]
	s_add_u32 s34, s34, 0x100000
	s_addc_u32 s35, s35, 0
	s_add_i32 s36, s39, s42
	global_load_lds_dwordx4 v[204:205], off
	v_lshl_add_u64 v[204:205], s[34:35], 0, v[134:135]
	s_mov_b32 m0, s36
	s_nop 0
	global_load_lds_dwordx4 v[204:205], off
	v_lshl_add_u64 v[204:205], s[34:35], 0, v[138:139]
	s_add_i32 m0, s36, 0x2000
	s_nop 0
	global_load_lds_dwordx4 v[204:205], off
	v_lshl_add_u64 v[204:205], s[30:31], 0, v[2:3]
	s_mov_b32 m0, s52
	s_nop 0
	global_load_lds_dwordx4 v[204:205], off
	v_lshl_add_u64 v[204:205], s[30:31], 0, v[136:137]
	s_mov_b32 m0, s53
	s_nop 0
	global_load_lds_dwordx4 v[204:205], off
	s_waitcnt vmcnt(8)
	s_waitcnt lgkmcnt(0)
	s_barrier
	s_setprio 1
	v_mfma_f32_16x16x32_bf16 v[66:69], v[140:143], v[172:175], v[66:69]
	v_mfma_f32_16x16x32_bf16 v[62:65], v[148:151], v[172:175], v[62:65]
	v_mfma_f32_16x16x32_bf16 v[50:53], v[140:143], v[180:183], v[50:53]
	v_mfma_f32_16x16x32_bf16 v[46:49], v[148:151], v[180:183], v[46:49]
	v_mfma_f32_16x16x32_bf16 v[34:37], v[140:143], v[188:191], v[34:37]
	v_mfma_f32_16x16x32_bf16 v[30:33], v[148:151], v[188:191], v[30:33]
	v_mfma_f32_16x16x32_bf16 v[18:21], v[140:143], v[196:199], v[18:21]
	v_mfma_f32_16x16x32_bf16 v[14:17], v[148:151], v[196:199], v[14:17]
	v_mfma_f32_16x16x32_bf16 v[66:69], v[144:147], v[176:179], v[66:69]
	v_mfma_f32_16x16x32_bf16 v[62:65], v[152:155], v[176:179], v[62:65]
	v_mfma_f32_16x16x32_bf16 v[50:53], v[144:147], v[184:187], v[50:53]
	v_mfma_f32_16x16x32_bf16 v[46:49], v[152:155], v[184:187], v[46:49]
	v_mfma_f32_16x16x32_bf16 v[34:37], v[144:147], v[192:195], v[34:37]
	v_mfma_f32_16x16x32_bf16 v[30:33], v[152:155], v[192:195], v[30:33]
	v_mfma_f32_16x16x32_bf16 v[18:21], v[144:147], v[200:203], v[18:21]
	v_mfma_f32_16x16x32_bf16 v[14:17], v[152:155], v[200:203], v[14:17]
	v_mfma_f32_16x16x32_bf16 v[58:61], v[156:159], v[172:175], v[58:61]
	v_mfma_f32_16x16x32_bf16 v[54:57], v[164:167], v[172:175], v[54:57]
	v_mfma_f32_16x16x32_bf16 v[42:45], v[156:159], v[180:183], v[42:45]
	v_mfma_f32_16x16x32_bf16 v[38:41], v[164:167], v[180:183], v[38:41]
	v_mfma_f32_16x16x32_bf16 v[26:29], v[156:159], v[188:191], v[26:29]
	v_mfma_f32_16x16x32_bf16 v[22:25], v[164:167], v[188:191], v[22:25]
	v_mfma_f32_16x16x32_bf16 v[10:13], v[156:159], v[196:199], v[10:13]
	v_mfma_f32_16x16x32_bf16 v[6:9], v[164:167], v[196:199], v[6:9]
	v_mfma_f32_16x16x32_bf16 v[58:61], v[160:163], v[176:179], v[58:61]
	v_mfma_f32_16x16x32_bf16 v[54:57], v[168:171], v[176:179], v[54:57]
	v_mfma_f32_16x16x32_bf16 v[42:45], v[160:163], v[184:187], v[42:45]
	v_mfma_f32_16x16x32_bf16 v[38:41], v[168:171], v[184:187], v[38:41]
	v_mfma_f32_16x16x32_bf16 v[26:29], v[160:163], v[192:195], v[26:29]
	v_mfma_f32_16x16x32_bf16 v[22:25], v[168:171], v[192:195], v[22:25]
	v_mfma_f32_16x16x32_bf16 v[10:13], v[160:163], v[200:203], v[10:13]
	v_mfma_f32_16x16x32_bf16 v[6:9], v[168:171], v[200:203], v[6:9]
	s_setprio 0
	s_barrier
	s_add_i32 s59, s59, 2
	s_add_u32 s55, s55, 0x100
	s_addc_u32 s56, s56, 0
	s_add_u32 s57, s57, 0x100
	s_addc_u32 s58, s58, 0
	s_cmp_gt_u32 s59, 61
	s_cbranch_scc0 .LBB0_131
	s_and_b64 vcc, exec, s[8:9]
	s_cbranch_vccz .LBB0_134
	s_barrier

.LBB0_251:
	s_add_u32 s56, s52, 0xffffff80
	s_addc_u32 s57, s53, -1
	s_cmp_eq_u32 s54, 60
	s_cselect_b32 s28, s2, s52
	s_cselect_b32 s29, s1, s53
	s_cselect_b32 s31, s11, s33
	s_cselect_b32 s30, s15, s19
	s_add_u32 s24, s28, 0x80
	s_addc_u32 s25, s29, 0
	s_add_u32 s26, s30, 0x80
	s_addc_u32 s27, s31, 0
	s_add_i32 s55, 0, 0x10000
	s_add_i32 s58, 0, 0x14000
	v_add_u32_e32 v152, s55, v1
	v_add_u32_e32 v168, s58, v1
	ds_read_b128 v[140:143], v152
	ds_read_b128 v[144:147], v152 offset:1024
	ds_read_b128 v[148:151], v152 offset:2048
	ds_read_b128 v[152:155], v152 offset:3072
	ds_read_b128 v[156:159], v168
	ds_read_b128 v[160:163], v168 offset:1024
	ds_read_b128 v[164:167], v168 offset:2048
	ds_read_b128 v[168:171], v168 offset:3072
	s_add_u32 s56, s56, 0x100000
	s_addc_u32 s57, s57, 0
	v_lshl_add_u64 v[204:205], s[56:57], 0, v[138:139]
	s_add_i32 m0, s23, 0xc000
	ds_read_b128 v[172:175], v5
	ds_read_b128 v[176:179], v5 offset:1024
	ds_read_b128 v[180:183], v5 offset:2048
	ds_read_b128 v[184:187], v5 offset:3072
	ds_read_b128 v[188:191], v5 offset:4096
	ds_read_b128 v[192:195], v5 offset:5120
	ds_read_b128 v[196:199], v5 offset:6144
	ds_read_b128 v[200:203], v5 offset:7168
	global_load_lds_dwordx4 v[204:205], off
	v_lshl_add_u64 v[204:205], s[56:57], 0, v[134:135]
	s_add_i32 m0, s23, 0xe000
	s_nop 0
	global_load_lds_dwordx4 v[204:205], off
	s_waitcnt vmcnt(8)
	s_waitcnt lgkmcnt(0)
	s_barrier
	s_setprio 1
	v_mfma_f32_16x16x32_bf16 v[6:9], v[140:143], v[172:175], v[6:9]
	v_mfma_f32_16x16x32_bf16 v[10:13], v[148:151], v[172:175], v[10:13]
	v_mfma_f32_16x16x32_bf16 v[22:25], v[140:143], v[180:183], v[22:25]
	v_mfma_f32_16x16x32_bf16 v[26:29], v[148:151], v[180:183], v[26:29]
	v_mfma_f32_16x16x32_bf16 v[38:41], v[140:143], v[188:191], v[38:41]
	v_mfma_f32_16x16x32_bf16 v[42:45], v[148:151], v[188:191], v[42:45]
	v_mfma_f32_16x16x32_bf16 v[54:57], v[140:143], v[196:199], v[54:57]
	v_mfma_f32_16x16x32_bf16 v[58:61], v[148:151], v[196:199], v[58:61]
	v_mfma_f32_16x16x32_bf16 v[6:9], v[144:147], v[176:179], v[6:9]
	v_mfma_f32_16x16x32_bf16 v[10:13], v[152:155], v[176:179], v[10:13]
	v_mfma_f32_16x16x32_bf16 v[22:25], v[144:147], v[184:187], v[22:25]
	v_mfma_f32_16x16x32_bf16 v[26:29], v[152:155], v[184:187], v[26:29]
	v_mfma_f32_16x16x32_bf16 v[38:41], v[144:147], v[192:195], v[38:41]
	v_mfma_f32_16x16x32_bf16 v[42:45], v[152:155], v[192:195], v[42:45]
	v_mfma_f32_16x16x32_bf16 v[54:57], v[144:147], v[200:203], v[54:57]
	v_mfma_f32_16x16x32_bf16 v[58:61], v[152:155], v[200:203], v[58:61]
	v_mfma_f32_16x16x32_bf16 v[14:17], v[156:159], v[172:175], v[14:17]
	v_mfma_f32_16x16x32_bf16 v[18:21], v[164:167], v[172:175], v[18:21]
	v_mfma_f32_16x16x32_bf16 v[30:33], v[156:159], v[180:183], v[30:33]
	v_mfma_f32_16x16x32_bf16 v[34:37], v[164:167], v[180:183], v[34:37]
	v_mfma_f32_16x16x32_bf16 v[46:49], v[156:159], v[188:191], v[46:49]
	v_mfma_f32_16x16x32_bf16 v[50:53], v[164:167], v[188:191], v[50:53]
	v_mfma_f32_16x16x32_bf16 v[62:65], v[156:159], v[196:199], v[62:65]
	v_mfma_f32_16x16x32_bf16 v[66:69], v[164:167], v[196:199], v[66:69]
	v_mfma_f32_16x16x32_bf16 v[14:17], v[160:163], v[176:179], v[14:17]
	v_mfma_f32_16x16x32_bf16 v[18:21], v[168:171], v[176:179], v[18:21]
	v_mfma_f32_16x16x32_bf16 v[30:33], v[160:163], v[184:187], v[30:33]
	v_mfma_f32_16x16x32_bf16 v[34:37], v[168:171], v[184:187], v[34:37]
	v_mfma_f32_16x16x32_bf16 v[46:49], v[160:163], v[192:195], v[46:49]
	v_mfma_f32_16x16x32_bf16 v[50:53], v[168:171], v[192:195], v[50:53]
	v_mfma_f32_16x16x32_bf16 v[62:65], v[160:163], v[200:203], v[62:65]
	v_mfma_f32_16x16x32_bf16 v[66:69], v[168:171], v[200:203], v[66:69]
	s_setprio 0
	s_barrier
	s_add_i32 s55, s55, s37
	v_lshl_add_u64 v[204:205], s[30:31], 0, v[136:137]
	s_mov_b32 m0, s55
	ds_read_b128 v[172:175], v5 offset:16384
	ds_read_b128 v[176:179], v5 offset:17408
	ds_read_b128 v[180:183], v5 offset:18432
	ds_read_b128 v[184:187], v5 offset:19456
	ds_read_b128 v[188:191], v5 offset:20480
	ds_read_b128 v[192:195], v5 offset:21504
	ds_read_b128 v[196:199], v5 offset:22528
	ds_read_b128 v[200:203], v5 offset:23552
	global_load_lds_dwordx4 v[204:205], off
	s_add_i32 m0, s55, 0x2000
	v_lshl_add_u64 v[204:205], s[30:31], 0, v[2:3]
	s_add_u32 s30, s30, 0x100000
	s_addc_u32 s31, s31, 0
	s_add_i32 s55, s58, s37
	global_load_lds_dwordx4 v[204:205], off
	v_lshl_add_u64 v[204:205], s[30:31], 0, v[136:137]
	s_mov_b32 m0, s55
	s_nop 0
	global_load_lds_dwordx4 v[204:205], off
	v_lshl_add_u64 v[204:205], s[30:31], 0, v[2:3]
	s_add_i32 m0, s55, 0x2000
	s_nop 0
	global_load_lds_dwordx4 v[204:205], off
	v_lshl_add_u64 v[204:205], s[28:29], 0, v[138:139]
	s_mov_b32 m0, s23
	s_nop 0
	global_load_lds_dwordx4 v[204:205], off
	v_lshl_add_u64 v[204:205], s[28:29], 0, v[134:135]
	s_mov_b32 m0, s40
	s_nop 0
	global_load_lds_dwordx4 v[204:205], off
	s_waitcnt vmcnt(8)
	s_waitcnt lgkmcnt(0)
	s_barrier
	s_setprio 1
	v_mfma_f32_16x16x32_bf16 v[70:73], v[140:143], v[172:175], v[70:73]
	v_mfma_f32_16x16x32_bf16 v[74:77], v[148:151], v[172:175], v[74:77]
	v_mfma_f32_16x16x32_bf16 v[86:89], v[140:143], v[180:183], v[86:89]
	v_mfma_f32_16x16x32_bf16 v[90:93], v[148:151], v[180:183], v[90:93]
	v_mfma_f32_16x16x32_bf16 v[102:105], v[140:143], v[188:191], v[102:105]
	v_mfma_f32_16x16x32_bf16 v[106:109], v[148:151], v[188:191], v[106:109]
	v_mfma_f32_16x16x32_bf16 v[130:133], v[140:143], v[196:199], v[130:133]
	v_mfma_f32_16x16x32_bf16 v[126:129], v[148:151], v[196:199], v[126:129]
	v_mfma_f32_16x16x32_bf16 v[70:73], v[144:147], v[176:179], v[70:73]
	v_mfma_f32_16x16x32_bf16 v[74:77], v[152:155], v[176:179], v[74:77]
	v_mfma_f32_16x16x32_bf16 v[86:89], v[144:147], v[184:187], v[86:89]
	v_mfma_f32_16x16x32_bf16 v[90:93], v[152:155], v[184:187], v[90:93]
	v_mfma_f32_16x16x32_bf16 v[102:105], v[144:147], v[192:195], v[102:105]
	v_mfma_f32_16x16x32_bf16 v[106:109], v[152:155], v[192:195], v[106:109]
	v_mfma_f32_16x16x32_bf16 v[130:133], v[144:147], v[200:203], v[130:133]
	v_mfma_f32_16x16x32_bf16 v[126:129], v[152:155], v[200:203], v[126:129]
	v_mfma_f32_16x16x32_bf16 v[78:81], v[156:159], v[172:175], v[78:81]
	v_mfma_f32_16x16x32_bf16 v[82:85], v[164:167], v[172:175], v[82:85]
	v_mfma_f32_16x16x32_bf16 v[94:97], v[156:159], v[180:183], v[94:97]
	v_mfma_f32_16x16x32_bf16 v[98:101], v[164:167], v[180:183], v[98:101]
	v_mfma_f32_16x16x32_bf16 v[110:113], v[156:159], v[188:191], v[110:113]
	v_mfma_f32_16x16x32_bf16 v[114:117], v[164:167], v[188:191], v[114:117]
	v_mfma_f32_16x16x32_bf16 v[122:125], v[156:159], v[196:199], v[122:125]
	v_mfma_f32_16x16x32_bf16 v[118:121], v[164:167], v[196:199], v[118:121]
	v_mfma_f32_16x16x32_bf16 v[78:81], v[160:163], v[176:179], v[78:81]
	v_mfma_f32_16x16x32_bf16 v[82:85], v[168:171], v[176:179], v[82:85]
	v_mfma_f32_16x16x32_bf16 v[94:97], v[160:163], v[184:187], v[94:97]
	v_mfma_f32_16x16x32_bf16 v[98:101], v[168:171], v[184:187], v[98:101]
	v_mfma_f32_16x16x32_bf16 v[110:113], v[160:163], v[192:195], v[110:113]
	v_mfma_f32_16x16x32_bf16 v[114:117], v[168:171], v[192:195], v[114:117]
	v_mfma_f32_16x16x32_bf16 v[122:125], v[160:163], v[200:203], v[122:125]
	v_mfma_f32_16x16x32_bf16 v[118:121], v[168:171], v[200:203], v[118:121]
	s_setprio 0
	s_barrier
	s_add_i32 s30, 0, 0x18000
	s_add_i32 s31, 0, 0x1c000
	v_add_u32_e32 v152, s30, v1
	v_add_u32_e32 v168, s31, v1
	ds_read_b128 v[140:143], v152
	ds_read_b128 v[144:147], v152 offset:1024
	ds_read_b128 v[148:151], v152 offset:2048
	ds_read_b128 v[152:155], v152 offset:3072
	ds_read_b128 v[156:159], v168
	ds_read_b128 v[160:163], v168 offset:1024
	ds_read_b128 v[164:167], v168 offset:2048
	ds_read_b128 v[168:171], v168 offset:3072
	s_add_u32 s28, s28, 0x100000
	s_addc_u32 s29, s29, 0
	s_mov_b32 m0, s41
	v_lshl_add_u64 v[204:205], s[28:29], 0, v[138:139]
	ds_read_b128 v[172:175], v5 offset:32768
	ds_read_b128 v[176:179], v5 offset:33792
	ds_read_b128 v[180:183], v5 offset:34816
	ds_read_b128 v[184:187], v5 offset:35840
	ds_read_b128 v[188:191], v5 offset:36864
	ds_read_b128 v[192:195], v5 offset:37888
	ds_read_b128 v[196:199], v5 offset:38912
	ds_read_b128 v[200:203], v5 offset:39936
	global_load_lds_dwordx4 v[204:205], off
	v_lshl_add_u64 v[204:205], s[28:29], 0, v[134:135]
	s_mov_b32 m0, s42
	s_nop 0
	global_load_lds_dwordx4 v[204:205], off
	s_waitcnt vmcnt(8)
	s_waitcnt lgkmcnt(0)
	s_barrier
	s_setprio 1
	v_mfma_f32_16x16x32_bf16 v[6:9], v[140:143], v[172:175], v[6:9]
	v_mfma_f32_16x16x32_bf16 v[10:13], v[148:151], v[172:175], v[10:13]
	v_mfma_f32_16x16x32_bf16 v[22:25], v[140:143], v[180:183], v[22:25]
	v_mfma_f32_16x16x32_bf16 v[26:29], v[148:151], v[180:183], v[26:29]
	v_mfma_f32_16x16x32_bf16 v[38:41], v[140:143], v[188:191], v[38:41]
	v_mfma_f32_16x16x32_bf16 v[42:45], v[148:151], v[188:191], v[42:45]
	v_mfma_f32_16x16x32_bf16 v[54:57], v[140:143], v[196:199], v[54:57]
	v_mfma_f32_16x16x32_bf16 v[58:61], v[148:151], v[196:199], v[58:61]
	v_mfma_f32_16x16x32_bf16 v[6:9], v[144:147], v[176:179], v[6:9]
	v_mfma_f32_16x16x32_bf16 v[10:13], v[152:155], v[176:179], v[10:13]
	v_mfma_f32_16x16x32_bf16 v[22:25], v[144:147], v[184:187], v[22:25]
	v_mfma_f32_16x16x32_bf16 v[26:29], v[152:155], v[184:187], v[26:29]
	v_mfma_f32_16x16x32_bf16 v[38:41], v[144:147], v[192:195], v[38:41]
	v_mfma_f32_16x16x32_bf16 v[42:45], v[152:155], v[192:195], v[42:45]
	v_mfma_f32_16x16x32_bf16 v[54:57], v[144:147], v[200:203], v[54:57]
	v_mfma_f32_16x16x32_bf16 v[58:61], v[152:155], v[200:203], v[58:61]
	v_mfma_f32_16x16x32_bf16 v[14:17], v[156:159], v[172:175], v[14:17]
	v_mfma_f32_16x16x32_bf16 v[18:21], v[164:167], v[172:175], v[18:21]
	v_mfma_f32_16x16x32_bf16 v[30:33], v[156:159], v[180:183], v[30:33]
	v_mfma_f32_16x16x32_bf16 v[34:37], v[164:167], v[180:183], v[34:37]
	v_mfma_f32_16x16x32_bf16 v[46:49], v[156:159], v[188:191], v[46:49]
	v_mfma_f32_16x16x32_bf16 v[50:53], v[164:167], v[188:191], v[50:53]
	v_mfma_f32_16x16x32_bf16 v[62:65], v[156:159], v[196:199], v[62:65]
	v_mfma_f32_16x16x32_bf16 v[66:69], v[164:167], v[196:199], v[66:69]
	v_mfma_f32_16x16x32_bf16 v[14:17], v[160:163], v[176:179], v[14:17]
	v_mfma_f32_16x16x32_bf16 v[18:21], v[168:171], v[176:179], v[18:21]
	v_mfma_f32_16x16x32_bf16 v[30:33], v[160:163], v[184:187], v[30:33]
	v_mfma_f32_16x16x32_bf16 v[34:37], v[168:171], v[184:187], v[34:37]
	v_mfma_f32_16x16x32_bf16 v[46:49], v[160:163], v[192:195], v[46:49]
	v_mfma_f32_16x16x32_bf16 v[50:53], v[168:171], v[192:195], v[50:53]
	v_mfma_f32_16x16x32_bf16 v[62:65], v[160:163], v[200:203], v[62:65]
	v_mfma_f32_16x16x32_bf16 v[66:69], v[168:171], v[200:203], v[66:69]
	s_setprio 0
	s_barrier
	s_add_i32 s28, s30, s37
	v_lshl_add_u64 v[204:205], s[26:27], 0, v[136:137]
	s_mov_b32 m0, s28
	ds_read_b128 v[172:175], v5 offset:49152
	ds_read_b128 v[176:179], v5 offset:50176
	ds_read_b128 v[180:183], v5 offset:51200
	ds_read_b128 v[184:187], v5 offset:52224
	ds_read_b128 v[188:191], v5 offset:53248
	ds_read_b128 v[192:195], v5 offset:54272
	ds_read_b128 v[196:199], v5 offset:55296
	ds_read_b128 v[200:203], v5 offset:56320
	global_load_lds_dwordx4 v[204:205], off
	s_add_i32 m0, s28, 0x2000
	v_lshl_add_u64 v[204:205], s[26:27], 0, v[2:3]
	s_add_u32 s26, s26, 0x100000
	s_addc_u32 s27, s27, 0
	s_add_i32 s28, s31, s37
	global_load_lds_dwordx4 v[204:205], off
	v_lshl_add_u64 v[204:205], s[26:27], 0, v[136:137]
	s_mov_b32 m0, s28
	s_nop 0
	global_load_lds_dwordx4 v[204:205], off
	v_lshl_add_u64 v[204:205], s[26:27], 0, v[2:3]
	s_add_i32 m0, s28, 0x2000
	s_nop 0
	global_load_lds_dwordx4 v[204:205], off
	v_lshl_add_u64 v[204:205], s[24:25], 0, v[138:139]
	s_mov_b32 m0, s49
	s_nop 0
	global_load_lds_dwordx4 v[204:205], off
	v_lshl_add_u64 v[204:205], s[24:25], 0, v[134:135]
	s_mov_b32 m0, s50
	s_nop 0
	global_load_lds_dwordx4 v[204:205], off
	s_waitcnt vmcnt(8)
	s_waitcnt lgkmcnt(0)
	s_barrier
	s_setprio 1
	v_mfma_f32_16x16x32_bf16 v[70:73], v[140:143], v[172:175], v[70:73]
	v_mfma_f32_16x16x32_bf16 v[74:77], v[148:151], v[172:175], v[74:77]
	v_mfma_f32_16x16x32_bf16 v[86:89], v[140:143], v[180:183], v[86:89]
	v_mfma_f32_16x16x32_bf16 v[90:93], v[148:151], v[180:183], v[90:93]
	v_mfma_f32_16x16x32_bf16 v[102:105], v[140:143], v[188:191], v[102:105]
	v_mfma_f32_16x16x32_bf16 v[106:109], v[148:151], v[188:191], v[106:109]
	v_mfma_f32_16x16x32_bf16 v[130:133], v[140:143], v[196:199], v[130:133]
	v_mfma_f32_16x16x32_bf16 v[126:129], v[148:151], v[196:199], v[126:129]
	v_mfma_f32_16x16x32_bf16 v[70:73], v[144:147], v[176:179], v[70:73]
	v_mfma_f32_16x16x32_bf16 v[74:77], v[152:155], v[176:179], v[74:77]
	v_mfma_f32_16x16x32_bf16 v[86:89], v[144:147], v[184:187], v[86:89]
	v_mfma_f32_16x16x32_bf16 v[90:93], v[152:155], v[184:187], v[90:93]
	v_mfma_f32_16x16x32_bf16 v[102:105], v[144:147], v[192:195], v[102:105]
	v_mfma_f32_16x16x32_bf16 v[106:109], v[152:155], v[192:195], v[106:109]
	v_mfma_f32_16x16x32_bf16 v[130:133], v[144:147], v[200:203], v[130:133]
	v_mfma_f32_16x16x32_bf16 v[126:129], v[152:155], v[200:203], v[126:129]
	v_mfma_f32_16x16x32_bf16 v[78:81], v[156:159], v[172:175], v[78:81]
	v_mfma_f32_16x16x32_bf16 v[82:85], v[164:167], v[172:175], v[82:85]
	v_mfma_f32_16x16x32_bf16 v[94:97], v[156:159], v[180:183], v[94:97]
	v_mfma_f32_16x16x32_bf16 v[98:101], v[164:167], v[180:183], v[98:101]
	v_mfma_f32_16x16x32_bf16 v[110:113], v[156:159], v[188:191], v[110:113]
	v_mfma_f32_16x16x32_bf16 v[114:117], v[164:167], v[188:191], v[114:117]
	v_mfma_f32_16x16x32_bf16 v[122:125], v[156:159], v[196:199], v[122:125]
	v_mfma_f32_16x16x32_bf16 v[118:121], v[164:167], v[196:199], v[118:121]
	v_mfma_f32_16x16x32_bf16 v[78:81], v[160:163], v[176:179], v[78:81]
	v_mfma_f32_16x16x32_bf16 v[82:85], v[168:171], v[176:179], v[82:85]
	v_mfma_f32_16x16x32_bf16 v[94:97], v[160:163], v[184:187], v[94:97]
	v_mfma_f32_16x16x32_bf16 v[98:101], v[168:171], v[184:187], v[98:101]
	v_mfma_f32_16x16x32_bf16 v[110:113], v[160:163], v[192:195], v[110:113]
	v_mfma_f32_16x16x32_bf16 v[114:117], v[168:171], v[192:195], v[114:117]
	v_mfma_f32_16x16x32_bf16 v[122:125], v[160:163], v[200:203], v[122:125]
	v_mfma_f32_16x16x32_bf16 v[118:121], v[168:171], v[200:203], v[118:121]
	s_setprio 0
	s_barrier
	s_add_i32 s54, s54, 2
	s_add_u32 s19, s19, 0x100
	s_addc_u32 s33, s33, 0
	s_add_u32 s52, s52, 0x100
	s_addc_u32 s53, s53, 0
	s_cmp_gt_u32 s54, 61
	s_cbranch_scc0 .LBB0_251
	v_mov_b32_e32 v141, v0
	s_lshl_b32 s1, s0, 8
	s_mov_b64 s[24:25], s[84:85]
	s_add_i32 s1, s1, s43
	v_and_or_b32 v140, v141, 15, s1
	v_lshrrev_b32_e32 v141, 1, v141
	s_add_u32 s26, s24, s6
	v_and_or_b32 v148, v141, 24, s48
	s_addc_u32 s27, s25, s7
	v_ashrrev_i32_e32 v141, 31, v140
	v_lshl_add_u64 v[142:143], v[140:141], 2, s[26:27]
	s_mov_b64 s[26:27], 0x10000
	v_lshl_add_u64 v[144:145], v[142:143], 0, s[26:27]
	v_add_co_u32_e32 v142, vcc, s91, v142
	global_load_dword v146, v[144:145], off offset:512
	s_nop 0
	v_addc_co_u32_e32 v143, vcc, 0, v143, vcc
	global_load_dword v142, v[142:143], off
	s_cmp_lt_i32 s22, 8
	s_mov_b64 s[26:27], -1
	global_load_dword v205, v[144:145], off offset:64
	global_load_dword v204, v[144:145], off offset:128
	global_load_dword v203, v[144:145], off offset:192
	global_load_dword v202, v[144:145], off offset:576
	global_load_dword v201, v[144:145], off offset:640
	global_load_dword v200, v[144:145], off offset:704
	s_waitcnt vmcnt(0)
	v_fmamk_f32 v146, v146, 0x39800000, v246
	v_mul_f32_e32 v147, 0x4b800000, v146
	v_fmamk_f32 v142, v142, 0x39800000, v246
	v_cmp_gt_f32_e32 vcc, s95, v142
	v_mul_f32_e32 v143, 0x4b800000, v142
	s_nop 0
	v_cndmask_b32_e32 v142, v142, v143, vcc
	v_rsq_f32_e32 v142, v142
	s_nop 0
	v_mul_f32_e32 v143, 0x45800000, v142
	v_cndmask_b32_e32 v142, v142, v143, vcc
	v_pk_mul_f32 v[8:9], v[8:9], v[142:143] op_sel_hi:[1,0]
	v_pk_mul_f32 v[6:7], v[6:7], v[142:143] op_sel_hi:[1,0]
	v_pk_mul_f32 v[12:13], v[12:13], v[142:143] op_sel_hi:[1,0]
	v_pk_mul_f32 v[10:11], v[10:11], v[142:143] op_sel_hi:[1,0]
	v_pk_mul_f32 v[16:17], v[16:17], v[142:143] op_sel_hi:[1,0]
	v_pk_mul_f32 v[14:15], v[14:15], v[142:143] op_sel_hi:[1,0]
	v_pk_mul_f32 v[20:21], v[20:21], v[142:143] op_sel_hi:[1,0]
	v_pk_mul_f32 v[18:19], v[18:19], v[142:143] op_sel_hi:[1,0]
	s_waitcnt vmcnt(0)
	v_fmamk_f32 v142, v205, 0x39800000, v246
	v_cmp_gt_f32_e32 vcc, s95, v142
	v_mul_f32_e32 v143, 0x4b800000, v142
	s_nop 0
	v_cndmask_b32_e32 v142, v142, v143, vcc
	v_rsq_f32_e32 v142, v142
	s_nop 0
	v_mul_f32_e32 v143, 0x45800000, v142
	v_cndmask_b32_e32 v142, v142, v143, vcc
	v_pk_mul_f32 v[24:25], v[24:25], v[142:143] op_sel_hi:[1,0]
	v_pk_mul_f32 v[22:23], v[22:23], v[142:143] op_sel_hi:[1,0]
	v_pk_mul_f32 v[28:29], v[28:29], v[142:143] op_sel_hi:[1,0]
	v_pk_mul_f32 v[26:27], v[26:27], v[142:143] op_sel_hi:[1,0]
	v_pk_mul_f32 v[32:33], v[32:33], v[142:143] op_sel_hi:[1,0]
	v_pk_mul_f32 v[30:31], v[30:31], v[142:143] op_sel_hi:[1,0]
	v_pk_mul_f32 v[36:37], v[36:37], v[142:143] op_sel_hi:[1,0]
	v_pk_mul_f32 v[34:35], v[34:35], v[142:143] op_sel_hi:[1,0]
	s_waitcnt vmcnt(0)
	v_fmamk_f32 v142, v204, 0x39800000, v246
	v_cmp_gt_f32_e32 vcc, s95, v142
	v_mul_f32_e32 v143, 0x4b800000, v142
	s_nop 0
	v_cndmask_b32_e32 v142, v142, v143, vcc
	v_rsq_f32_e32 v142, v142
	s_nop 0
	v_mul_f32_e32 v143, 0x45800000, v142
	v_cndmask_b32_e32 v142, v142, v143, vcc
	v_pk_mul_f32 v[40:41], v[40:41], v[142:143] op_sel_hi:[1,0]
	v_pk_mul_f32 v[38:39], v[38:39], v[142:143] op_sel_hi:[1,0]
	v_pk_mul_f32 v[44:45], v[44:45], v[142:143] op_sel_hi:[1,0]
	v_pk_mul_f32 v[42:43], v[42:43], v[142:143] op_sel_hi:[1,0]
	v_pk_mul_f32 v[48:49], v[48:49], v[142:143] op_sel_hi:[1,0]
	v_pk_mul_f32 v[46:47], v[46:47], v[142:143] op_sel_hi:[1,0]
	v_pk_mul_f32 v[52:53], v[52:53], v[142:143] op_sel_hi:[1,0]
	v_pk_mul_f32 v[50:51], v[50:51], v[142:143] op_sel_hi:[1,0]
	s_waitcnt vmcnt(0)
	v_fmamk_f32 v142, v203, 0x39800000, v246
	v_cmp_gt_f32_e32 vcc, s95, v142
	v_mul_f32_e32 v143, 0x4b800000, v142
	s_nop 0
	v_cndmask_b32_e32 v142, v142, v143, vcc
	v_rsq_f32_e32 v142, v142
	s_nop 0
	v_mul_f32_e32 v143, 0x45800000, v142
	v_cndmask_b32_e32 v142, v142, v143, vcc
	v_cmp_gt_f32_e32 vcc, s95, v146
	v_pk_mul_f32 v[56:57], v[56:57], v[142:143] op_sel_hi:[1,0]
	v_pk_mul_f32 v[54:55], v[54:55], v[142:143] op_sel_hi:[1,0]
	v_cndmask_b32_e32 v146, v146, v147, vcc
	v_rsq_f32_e32 v146, v146
	v_pk_mul_f32 v[60:61], v[60:61], v[142:143] op_sel_hi:[1,0]
	v_pk_mul_f32 v[58:59], v[58:59], v[142:143] op_sel_hi:[1,0]
	v_pk_mul_f32 v[64:65], v[64:65], v[142:143] op_sel_hi:[1,0]
	v_mul_f32_e32 v147, 0x45800000, v146
	v_cndmask_b32_e32 v146, v146, v147, vcc
	v_pk_mul_f32 v[72:73], v[72:73], v[146:147] op_sel_hi:[1,0]
	v_pk_mul_f32 v[70:71], v[70:71], v[146:147] op_sel_hi:[1,0]
	v_pk_mul_f32 v[76:77], v[76:77], v[146:147] op_sel_hi:[1,0]
	v_pk_mul_f32 v[74:75], v[74:75], v[146:147] op_sel_hi:[1,0]
	v_pk_mul_f32 v[80:81], v[80:81], v[146:147] op_sel_hi:[1,0]
	v_pk_mul_f32 v[78:79], v[78:79], v[146:147] op_sel_hi:[1,0]
	v_pk_mul_f32 v[84:85], v[84:85], v[146:147] op_sel_hi:[1,0]
	v_pk_mul_f32 v[82:83], v[82:83], v[146:147] op_sel_hi:[1,0]
	v_pk_mul_f32 v[62:63], v[62:63], v[142:143] op_sel_hi:[1,0]
	v_pk_mul_f32 v[68:69], v[68:69], v[142:143] op_sel_hi:[1,0]
	v_pk_mul_f32 v[66:67], v[66:67], v[142:143] op_sel_hi:[1,0]
	v_add_u32_e32 v142, 0x80, v140
	v_ashrrev_i32_e32 v143, 31, v142
	s_waitcnt vmcnt(0)
	v_fmamk_f32 v146, v202, 0x39800000, v246
	v_cmp_gt_f32_e32 vcc, s95, v146
	v_mul_f32_e32 v147, 0x4b800000, v146
	s_nop 0
	v_cndmask_b32_e32 v146, v146, v147, vcc
	v_rsq_f32_e32 v146, v146
	s_nop 0
	v_mul_f32_e32 v147, 0x45800000, v146
	v_cndmask_b32_e32 v146, v146, v147, vcc
	v_pk_mul_f32 v[88:89], v[88:89], v[146:147] op_sel_hi:[1,0]
	v_pk_mul_f32 v[86:87], v[86:87], v[146:147] op_sel_hi:[1,0]
	v_pk_mul_f32 v[92:93], v[92:93], v[146:147] op_sel_hi:[1,0]
	v_pk_mul_f32 v[90:91], v[90:91], v[146:147] op_sel_hi:[1,0]
	v_pk_mul_f32 v[96:97], v[96:97], v[146:147] op_sel_hi:[1,0]
	v_pk_mul_f32 v[94:95], v[94:95], v[146:147] op_sel_hi:[1,0]
	v_pk_mul_f32 v[100:101], v[100:101], v[146:147] op_sel_hi:[1,0]
	v_pk_mul_f32 v[98:99], v[98:99], v[146:147] op_sel_hi:[1,0]
	s_waitcnt vmcnt(0)
	v_fmamk_f32 v146, v201, 0x39800000, v246
	v_cmp_gt_f32_e32 vcc, s95, v146
	v_mul_f32_e32 v147, 0x4b800000, v146
	s_waitcnt vmcnt(0)
	v_fmamk_f32 v144, v200, 0x39800000, v246
	v_cndmask_b32_e32 v146, v146, v147, vcc
	v_rsq_f32_e32 v146, v146
	v_mul_f32_e32 v145, 0x4b800000, v144
	v_mul_f32_e32 v147, 0x45800000, v146
	v_cndmask_b32_e32 v146, v146, v147, vcc
	v_cmp_gt_f32_e32 vcc, s95, v144
	v_pk_mul_f32 v[104:105], v[104:105], v[146:147] op_sel_hi:[1,0]
	v_pk_mul_f32 v[102:103], v[102:103], v[146:147] op_sel_hi:[1,0]
	v_cndmask_b32_e32 v144, v144, v145, vcc
	v_rsq_f32_e32 v144, v144
	v_pk_mul_f32 v[108:109], v[108:109], v[146:147] op_sel_hi:[1,0]
	v_pk_mul_f32 v[106:107], v[106:107], v[146:147] op_sel_hi:[1,0]
	v_pk_mul_f32 v[112:113], v[112:113], v[146:147] op_sel_hi:[1,0]
	v_mul_f32_e32 v145, 0x45800000, v144
	v_cndmask_b32_e32 v144, v144, v145, vcc
	v_pk_mul_f32 v[110:111], v[110:111], v[146:147] op_sel_hi:[1,0]
	v_pk_mul_f32 v[116:117], v[116:117], v[146:147] op_sel_hi:[1,0]
	v_pk_mul_f32 v[114:115], v[114:115], v[146:147] op_sel_hi:[1,0]
	v_pk_mul_f32 v[132:133], v[132:133], v[144:145] op_sel_hi:[1,0]
	v_pk_mul_f32 v[130:131], v[130:131], v[144:145] op_sel_hi:[1,0]
	v_pk_mul_f32 v[128:129], v[128:129], v[144:145] op_sel_hi:[1,0]
	v_pk_mul_f32 v[126:127], v[126:127], v[144:145] op_sel_hi:[1,0]
	v_pk_mul_f32 v[124:125], v[124:125], v[144:145] op_sel_hi:[1,0]
	v_pk_mul_f32 v[122:123], v[122:123], v[144:145] op_sel_hi:[1,0]
	v_pk_mul_f32 v[120:121], v[120:121], v[144:145] op_sel_hi:[1,0]
	v_pk_mul_f32 v[118:119], v[118:119], v[144:145] op_sel_hi:[1,0]
	s_cbranch_scc1 .LBB0_254
	v_mul_f32_e32 v145, 0xbfb8aa3b, v7
	v_mul_f32_e32 v146, 0xbfb8aa3b, v8
	v_exp_f32_e32 v145, v145
	v_exp_f32_e32 v146, v146
	v_mul_f32_e32 v144, 0xbfb8aa3b, v6
	v_exp_f32_e32 v144, v144
	v_add_f32_e32 v145, 1.0, v145
	v_add_f32_e32 v146, 1.0, v146
	v_rcp_f32_e32 v145, v145
	v_rcp_f32_e32 v149, v146
	v_add_f32_e32 v144, 1.0, v144
	v_mul_f32_e32 v146, 0xbfb8aa3b, v9
	v_mul_f32_e32 v147, v7, v145
	v_mul_f32_e32 v195, v8, v149
	v_mul_f32_e32 v145, 0xbfb8aa3b, v10
	v_mul_f32_e32 v149, 0xbfb8aa3b, v11
	v_rcp_f32_e32 v144, v144
	v_exp_f32_e32 v150, v146
	v_exp_f32_e32 v145, v145
	v_exp_f32_e32 v149, v149
	v_mul_f32_e32 v146, v6, v144
	v_add_f32_e32 v144, 1.0, v150
	v_add_f32_e32 v145, 1.0, v145
	v_add_f32_e32 v149, 1.0, v149
	v_mul_f32_e32 v150, 0xbfb8aa3b, v12
	v_rcp_f32_e32 v144, v144
	v_rcp_f32_e32 v145, v145
	v_rcp_f32_e32 v149, v149
	v_exp_f32_e32 v150, v150
	v_mul_f32_e32 v209, v9, v144
	v_mul_f32_e32 v144, v10, v145
	v_mul_f32_e32 v145, v11, v149
	v_add_f32_e32 v149, 1.0, v150
	v_mul_f32_e32 v150, 0xbfb8aa3b, v13
	v_exp_f32_e32 v150, v150
	v_mul_f32_e32 v151, 0xbfb8aa3b, v14
	v_exp_f32_e32 v151, v151
	v_mul_f32_e32 v240, 0xbfb8aa3b, v99
	v_add_f32_e32 v150, 1.0, v150
	v_rcp_f32_e32 v150, v150
	v_add_f32_e32 v151, 1.0, v151
	v_rcp_f32_e32 v151, v151
	v_exp_f32_e32 v240, v240
	v_mul_f32_e32 v206, v13, v150
	v_mul_f32_e32 v150, 0xbfb8aa3b, v16
	v_mul_f32_e32 v194, v14, v151
	v_exp_f32_e32 v150, v150
	v_mul_f32_e32 v151, 0xbfb8aa3b, v17
	v_exp_f32_e32 v151, v151
	v_mul_f32_e32 v152, 0xbfb8aa3b, v15
	v_rcp_f32_e32 v149, v149
	v_exp_f32_e32 v152, v152
	v_add_f32_e32 v150, 1.0, v150
	v_rcp_f32_e32 v150, v150
	v_add_f32_e32 v151, 1.0, v151
	v_add_f32_e32 v242, 1.0, v240
	v_cvt_pk_bf16_f32 v240, v146, v147
	v_mul_f32_e32 v146, 0xbfb8aa3b, v100
	v_rcp_f32_e32 v151, v151
	v_exp_f32_e32 v146, v146
	v_mul_f32_e32 v147, 0xbfb8aa3b, v101
	v_exp_f32_e32 v147, v147
	v_mul_f32_e32 v205, v12, v149
	v_add_f32_e32 v149, 1.0, v152
	v_mul_f32_e32 v152, 0xbfb8aa3b, v18
	s_lshl_b32 s1, s22, 8
	v_rcp_f32_e32 v149, v149
	v_exp_f32_e32 v152, v152
	v_mul_f32_e32 v203, v16, v150
	v_mul_f32_e32 v150, 0xbfb8aa3b, v19
	v_cvt_pk_bf16_f32 v241, v195, v209
	v_rcp_f32_e32 v195, v242
	s_addk_i32 s1, 0xf800
	v_cvt_pk_bf16_f32 v242, v144, v145
	v_cvt_pk_bf16_f32 v243, v205, v206
	v_mul_f32_e32 v205, 0xbfb8aa3b, v102
	v_mul_f32_e32 v204, v17, v151
	v_exp_f32_e32 v150, v150
	v_mul_f32_e32 v151, 0xbfb8aa3b, v20
	v_add_f32_e32 v146, 1.0, v146
	v_or_b32_e32 v144, s1, v148
	v_mov_b32_e32 v145, v4
	v_exp_f32_e32 v205, v205
	v_exp_f32_e32 v151, v151
	v_rcp_f32_e32 v209, v146
	v_add_f32_e32 v146, 1.0, v147
	v_lshl_add_u64 v[144:145], v[144:145], 1, s[24:25]
	s_mov_b64 s[26:27], 0x1b480000
	v_rcp_f32_e32 v244, v146
	v_lshl_add_u64 v[146:147], v[144:145], 0, s[26:27]
	v_lshlrev_b64 v[144:145], 13, v[140:141]
	v_mul_f32_e32 v202, v15, v149
	v_add_f32_e32 v149, 1.0, v152
	v_lshl_add_u64 v[144:145], v[146:147], 0, v[144:145]
	v_rcp_f32_e32 v149, v149
	v_add_f32_e32 v150, 1.0, v150
	global_store_dwordx4 v[144:145], v[240:243], off nt
	v_add_f32_e32 v205, 1.0, v205
	v_rcp_f32_e32 v150, v150
	v_mul_f32_e32 v240, 0xbfb8aa3b, v103
	v_add_f32_e32 v151, 1.0, v151
	v_exp_f32_e32 v240, v240
	v_cvt_pk_bf16_f32 v202, v194, v202
	v_cvt_pk_bf16_f32 v203, v203, v204
	v_rcp_f32_e32 v204, v205
	v_rcp_f32_e32 v151, v151
	v_mul_f32_e32 v152, 0xbfb8aa3b, v21
	v_mul_f32_e32 v200, v18, v149
	v_exp_f32_e32 v152, v152
	v_mul_f32_e32 v201, v19, v150
	v_add_f32_e32 v205, 1.0, v240
	v_mul_f32_e32 v240, 0xbfb8aa3b, v105
	v_mul_f32_e32 v241, v102, v204
	v_cvt_pk_bf16_f32 v204, v200, v201
	v_mul_f32_e32 v200, 0xbfb8aa3b, v106
	v_mul_f32_e32 v192, v20, v151
	v_mul_f32_e32 v151, 0xbfb8aa3b, v23
	v_rcp_f32_e32 v205, v205
	v_exp_f32_e32 v240, v240
	v_exp_f32_e32 v200, v200
	v_exp_f32_e32 v151, v151
	v_mul_f32_e32 v150, 0xbfb8aa3b, v22
	v_add_f32_e32 v149, 1.0, v152
	v_exp_f32_e32 v150, v150
	v_rcp_f32_e32 v149, v149
	v_mul_f32_e32 v242, v103, v205
	v_add_f32_e32 v205, 1.0, v240
	v_mul_f32_e32 v201, 0xbfb8aa3b, v107
	v_add_f32_e32 v200, 1.0, v200
	v_add_f32_e32 v151, 1.0, v151
	v_exp_f32_e32 v201, v201
	v_rcp_f32_e32 v240, v205
	v_rcp_f32_e32 v200, v200
	v_rcp_f32_e32 v151, v151
	v_add_f32_e32 v150, 1.0, v150
	v_rcp_f32_e32 v150, v150
	v_mul_f32_e32 v197, v21, v149
	v_mul_f32_e32 v152, 0xbfb8aa3b, v24
	v_add_f32_e32 v201, 1.0, v201
	v_cvt_pk_bf16_f32 v205, v192, v197
	v_mul_f32_e32 v197, v105, v240
	v_mul_f32_e32 v240, v106, v200
	v_mul_f32_e32 v200, 0xbfb8aa3b, v109
	v_exp_f32_e32 v152, v152
	v_mul_f32_e32 v181, v23, v151
	v_mul_f32_e32 v151, 0xbfb8aa3b, v26
	v_rcp_f32_e32 v201, v201
	v_exp_f32_e32 v200, v200
	v_exp_f32_e32 v151, v151
	v_mul_f32_e32 v179, v22, v150
	v_mul_f32_e32 v150, 0xbfb8aa3b, v25
	v_exp_f32_e32 v150, v150
	v_add_f32_e32 v149, 1.0, v152
	v_mul_f32_e32 v152, 0xbfb8aa3b, v27
	v_mul_f32_e32 v243, v107, v201
	v_mul_f32_e32 v201, 0xbfb8aa3b, v110
	v_add_f32_e32 v200, 1.0, v200
	v_rcp_f32_e32 v149, v149
	v_add_f32_e32 v151, 1.0, v151
	v_exp_f32_e32 v152, v152
	v_exp_f32_e32 v201, v201
	v_rcp_f32_e32 v200, v200
	v_rcp_f32_e32 v151, v151
	v_add_f32_e32 v150, 1.0, v150
	v_rcp_f32_e32 v150, v150
	global_store_dwordx4 v[144:145], v[202:205], off offset:256 nt
	v_mul_f32_e32 v188, v24, v149
	v_add_f32_e32 v149, 1.0, v152
	v_mul_f32_e32 v202, 0xbfb8aa3b, v111
	v_add_f32_e32 v201, 1.0, v201
	v_exp_f32_e32 v202, v202
	v_mul_f32_e32 v204, v109, v200
	v_cvt_pk_bf16_f32 v200, v179, v181
	v_mul_f32_e32 v181, 0xbfb8aa3b, v113
	v_mul_f32_e32 v178, v26, v151
	v_mul_f32_e32 v151, 0xbfb8aa3b, v29
	v_rcp_f32_e32 v149, v149
	v_rcp_f32_e32 v201, v201
	v_exp_f32_e32 v181, v181
	v_exp_f32_e32 v151, v151
	v_mul_f32_e32 v179, 0xbfb8aa3b, v112
	v_mul_f32_e32 v189, v25, v150
	v_mul_f32_e32 v150, 0xbfb8aa3b, v28
	v_exp_f32_e32 v179, v179
	v_exp_f32_e32 v150, v150
	v_add_f32_e32 v202, 1.0, v202
	v_mul_f32_e32 v187, v27, v149
	v_mul_f32_e32 v205, v110, v201
	v_cvt_pk_bf16_f32 v201, v188, v189
	v_rcp_f32_e32 v188, v202
	v_add_f32_e32 v181, 1.0, v181
	v_cvt_pk_bf16_f32 v202, v178, v187
	v_mul_f32_e32 v178, 0xbfb8aa3b, v114
	v_add_f32_e32 v151, 1.0, v151
	v_rcp_f32_e32 v181, v181
	v_exp_f32_e32 v178, v178
	v_rcp_f32_e32 v151, v151
	v_add_f32_e32 v179, 1.0, v179
	v_add_f32_e32 v150, 1.0, v150
	v_rcp_f32_e32 v179, v179
	v_rcp_f32_e32 v150, v150
	v_mul_f32_e32 v245, v113, v181
	v_add_f32_e32 v181, 1.0, v178
	v_mul_f32_e32 v178, 0xbfb8aa3b, v115
	v_mul_f32_e32 v182, v29, v151
	v_mul_f32_e32 v151, 0xbfb8aa3b, v32
	v_exp_f32_e32 v248, v178
	v_or_b32_e32 v178, 16, v140
	v_exp_f32_e32 v151, v151
	v_mul_f32_e32 v206, v100, v209
	v_mul_f32_e32 v209, v101, v244
	v_mul_f32_e32 v244, v112, v179
	v_ashrrev_i32_e32 v179, 31, v178
	v_mul_f32_e32 v152, 0xbfb8aa3b, v30
	v_mul_f32_e32 v180, v28, v150
	v_mul_f32_e32 v150, 0xbfb8aa3b, v31
	v_lshlrev_b64 v[178:179], 13, v[178:179]
	v_exp_f32_e32 v152, v152
	v_exp_f32_e32 v150, v150
	v_mul_f32_e32 v187, v111, v188
	v_lshl_add_u64 v[188:189], v[146:147], 0, v[178:179]
	v_mul_f32_e32 v178, 0xbfb8aa3b, v116
	v_exp_f32_e32 v178, v178
	v_add_f32_e32 v151, 1.0, v151
	v_rcp_f32_e32 v151, v151
	v_add_f32_e32 v149, 1.0, v152
	v_add_f32_e32 v150, 1.0, v150
	v_rcp_f32_e32 v149, v149
	v_rcp_f32_e32 v150, v150
	v_add_f32_e32 v178, 1.0, v178
	v_rcp_f32_e32 v178, v178
	v_mul_f32_e32 v173, v32, v151
	v_mul_f32_e32 v151, 0xbfb8aa3b, v35
	v_exp_f32_e32 v151, v151
	v_mul_f32_e32 v152, 0xbfb8aa3b, v33
	v_mul_f32_e32 v170, v30, v149
	v_mul_f32_e32 v172, v31, v150
	v_mul_f32_e32 v150, 0xbfb8aa3b, v34
	v_exp_f32_e32 v152, v152
	v_exp_f32_e32 v150, v150
	v_cvt_pk_bf16_f32 v203, v180, v182
	global_store_dwordx4 v[188:189], v[200:203], off nt
	v_add_f32_e32 v151, 1.0, v151
	v_rcp_f32_e32 v151, v151
	v_mul_f32_e32 v201, v116, v178
	v_cvt_pk_bf16_f32 v178, v170, v172
	v_mul_f32_e32 v170, 0xbfb8aa3b, v130
	v_exp_f32_e32 v170, v170
	v_add_f32_e32 v149, 1.0, v152
	v_add_f32_e32 v150, 1.0, v150
	v_rcp_f32_e32 v149, v149
	v_rcp_f32_e32 v150, v150
	v_add_f32_e32 v170, 1.0, v170
	v_rcp_f32_e32 v179, v181
	v_rcp_f32_e32 v170, v170
	v_mul_f32_e32 v152, 0xbfb8aa3b, v36
	v_mul_f32_e32 v169, v35, v151
	v_mul_f32_e32 v151, 0xbfb8aa3b, v38
	v_exp_f32_e32 v152, v152
	v_exp_f32_e32 v151, v151
	v_add_f32_e32 v180, 1.0, v248
	v_mul_f32_e32 v181, 0xbfb8aa3b, v117
	v_mul_f32_e32 v183, v33, v149
	v_mul_f32_e32 v168, v34, v150
	v_mul_f32_e32 v150, 0xbfb8aa3b, v37
	v_rcp_f32_e32 v180, v180
	v_exp_f32_e32 v181, v181
	v_exp_f32_e32 v150, v150
	v_mul_f32_e32 v182, v114, v179
	v_cvt_pk_bf16_f32 v179, v173, v183
	v_mul_f32_e32 v183, v130, v170
	v_mul_f32_e32 v170, 0xbfb8aa3b, v126
	v_exp_f32_e32 v170, v170
	v_add_f32_e32 v149, 1.0, v152
	v_add_f32_e32 v151, 1.0, v151
	v_rcp_f32_e32 v149, v149
	v_rcp_f32_e32 v151, v151
	v_mul_f32_e32 v200, v115, v180
	v_add_f32_e32 v180, 1.0, v181
	v_add_f32_e32 v150, 1.0, v150
	v_rcp_f32_e32 v173, v180
	v_cvt_pk_bf16_f32 v180, v168, v169
	v_mul_f32_e32 v168, 0xbfb8aa3b, v132
	v_mul_f32_e32 v169, 0xbfb8aa3b, v133
	v_rcp_f32_e32 v150, v150
	v_exp_f32_e32 v168, v168
	v_exp_f32_e32 v169, v169
	v_add_f32_e32 v170, 1.0, v170
	v_rcp_f32_e32 v170, v170
	v_mul_f32_e32 v171, v36, v149
	v_mul_f32_e32 v149, v38, v151
	v_mul_f32_e32 v151, 0xbfb8aa3b, v40
	v_mul_f32_e32 v152, 0xbfb8aa3b, v39
	v_exp_f32_e32 v151, v151
	v_exp_f32_e32 v152, v152
	v_mul_f32_e32 v174, v37, v150
	v_add_f32_e32 v168, 1.0, v168
	v_cvt_pk_bf16_f32 v181, v171, v174
	v_add_f32_e32 v169, 1.0, v169
	v_mul_f32_e32 v171, 0xbfb8aa3b, v127
	v_rcp_f32_e32 v168, v168
	v_rcp_f32_e32 v169, v169
	v_exp_f32_e32 v171, v171
	v_mul_f32_e32 v203, v126, v170
	v_mul_f32_e32 v170, 0xbfb8aa3b, v129
	v_exp_f32_e32 v170, v170
	v_add_f32_e32 v151, 1.0, v151
	v_add_f32_e32 v150, 1.0, v152
	v_mul_f32_e32 v152, 0xbfb8aa3b, v41
	v_rcp_f32_e32 v151, v151
	v_exp_f32_e32 v152, v152
	v_mul_f32_e32 v174, v132, v168
	v_mul_f32_e32 v202, v133, v169
	v_add_f32_e32 v168, 1.0, v171
	v_mul_f32_e32 v169, 0xbfb8aa3b, v128
	v_exp_f32_e32 v169, v169
	v_rcp_f32_e32 v168, v168
	v_add_f32_e32 v170, 1.0, v170
	v_mul_f32_e32 v171, 0xbfb8aa3b, v122
	v_rcp_f32_e32 v170, v170
	v_exp_f32_e32 v171, v171
	v_mul_f32_e32 v153, 0xbfb8aa3b, v42
	v_mul_f32_e32 v154, v40, v151
	v_mul_f32_e32 v151, 0xbfb8aa3b, v43
	v_rcp_f32_e32 v150, v150
	v_add_f32_e32 v152, 1.0, v152
	v_exp_f32_e32 v156, v153
	v_exp_f32_e32 v151, v151
	v_rcp_f32_e32 v152, v152
	global_store_dwordx4 v[188:189], v[178:181], off offset:256 nt
	v_add_f32_e32 v169, 1.0, v169
	v_rcp_f32_e32 v169, v169
	v_mul_f32_e32 v178, v127, v168
	v_mul_f32_e32 v168, 0xbfb8aa3b, v123
	v_mul_f32_e32 v180, v129, v170
	v_add_f32_e32 v170, 1.0, v171
	v_exp_f32_e32 v171, v168
	v_mul_f32_e32 v153, v39, v150
	v_add_f32_e32 v150, 1.0, v156
	v_add_f32_e32 v151, 1.0, v151
	v_mul_f32_e32 v156, 0xbfb8aa3b, v45
	v_mul_f32_e32 v155, v41, v152
	v_mul_f32_e32 v152, 0xbfb8aa3b, v44
	v_rcp_f32_e32 v150, v150
	v_rcp_f32_e32 v151, v151
	v_exp_f32_e32 v158, v156
	v_exp_f32_e32 v152, v152
	v_mul_f32_e32 v179, v128, v169
	v_cvt_pk_bf16_f32 v168, v149, v153
	v_cvt_pk_bf16_f32 v169, v154, v155
	v_add_f32_e32 v154, 1.0, v171
	v_mul_f32_e32 v155, 0xbfb8aa3b, v125
	v_rcp_f32_e32 v153, v170
	v_rcp_f32_e32 v154, v154
	v_exp_f32_e32 v155, v155
	v_mul_f32_e32 v156, v42, v150
	v_mul_f32_e32 v157, v43, v151
	v_add_f32_e32 v150, 1.0, v158
	v_mul_f32_e32 v151, 0xbfb8aa3b, v46
	v_mul_f32_e32 v158, 0xbfb8aa3b, v47
	v_add_f32_e32 v152, 1.0, v152
	v_exp_f32_e32 v151, v151
	v_exp_f32_e32 v158, v158
	v_rcp_f32_e32 v152, v152
	v_mul_f32_e32 v185, 0xbfb8aa3b, v61
	v_mul_f32_e32 v181, v122, v153
	v_mul_f32_e32 v188, v123, v154
	v_add_f32_e32 v153, 1.0, v155
	v_mul_f32_e32 v154, 0xbfb8aa3b, v118
	v_rcp_f32_e32 v150, v150
	v_exp_f32_e32 v185, v185
	v_mul_f32_e32 v186, 0xbfb8aa3b, v62
	v_rcp_f32_e32 v153, v153
	v_exp_f32_e32 v154, v154
	v_mul_f32_e32 v184, 0xbfb8aa3b, v60
	v_exp_f32_e32 v186, v186
	v_add_f32_e32 v151, 1.0, v151
	v_add_f32_e32 v158, 1.0, v158
	v_mul_f32_e32 v159, 0xbfb8aa3b, v48
	v_exp_f32_e32 v184, v184
	v_mul_f32_e32 v210, 0xbfb8aa3b, v71
	v_mul_f32_e32 v155, 0xbfb8aa3b, v119
	v_mul_f32_e32 v152, v44, v152
	v_rcp_f32_e32 v151, v151
	v_rcp_f32_e32 v158, v158
	v_exp_f32_e32 v159, v159
	v_mul_f32_e32 v207, 0xbfb8aa3b, v69
	v_mul_f32_e32 v208, 0xbfb8aa3b, v70
	v_exp_f32_e32 v210, v210
	v_mul_f32_e32 v226, 0xbfb8aa3b, v85
	v_exp_f32_e32 v155, v155
	v_mul_f32_e32 v161, v45, v150
	v_add_f32_e32 v185, 1.0, v185
	v_exp_f32_e32 v207, v207
	v_exp_f32_e32 v208, v208
	v_exp_f32_e32 v226, v226
	v_mul_f32_e32 v227, 0xbfb8aa3b, v86
	v_cvt_pk_bf16_f32 v170, v156, v157
	v_mul_f32_e32 v156, v125, v153
	v_add_f32_e32 v153, 1.0, v154
	v_cvt_pk_bf16_f32 v171, v152, v161
	v_or_b32_e32 v152, 32, v140
	v_rcp_f32_e32 v190, v185
	v_add_f32_e32 v185, 1.0, v186
	v_mul_f32_e32 v225, 0xbfb8aa3b, v84
	v_exp_f32_e32 v227, v227
	v_mul_f32_e32 v236, 0xbfb8aa3b, v95
	v_rcp_f32_e32 v157, v153
	v_ashrrev_i32_e32 v153, 31, v152
	v_add_f32_e32 v184, 1.0, v184
	v_rcp_f32_e32 v191, v185
	v_mul_f32_e32 v185, 0xbfb8aa3b, v63
	v_exp_f32_e32 v225, v225
	v_mul_f32_e32 v234, 0xbfb8aa3b, v93
	v_mul_f32_e32 v235, 0xbfb8aa3b, v94
	v_exp_f32_e32 v236, v236
	v_lshlrev_b64 v[152:153], 13, v[152:153]
	v_mul_f32_e32 v150, v46, v151
	v_mul_f32_e32 v151, v47, v158
	v_add_f32_e32 v158, 1.0, v159
	v_mul_f32_e32 v159, 0xbfb8aa3b, v49
	v_mul_f32_e32 v160, 0xbfb8aa3b, v50
	v_mul_f32_e32 v162, 0xbfb8aa3b, v51
	v_mul_f32_e32 v163, 0xbfb8aa3b, v52
	v_mul_f32_e32 v164, 0xbfb8aa3b, v53
	v_rcp_f32_e32 v184, v184
	v_exp_f32_e32 v193, v185
	v_add_f32_e32 v210, 1.0, v210
	v_exp_f32_e32 v234, v234
	v_exp_f32_e32 v235, v235
	v_add_f32_e32 v189, 1.0, v155
	v_lshl_add_u64 v[154:155], v[146:147], 0, v[152:153]
	v_mul_f32_e32 v152, 0xbfb8aa3b, v120
	v_mul_f32_e32 v153, 0xbfb8aa3b, v121
	v_exp_f32_e32 v159, v159
	v_exp_f32_e32 v160, v160
	v_exp_f32_e32 v162, v162
	v_exp_f32_e32 v163, v163
	v_exp_f32_e32 v164, v164
	v_add_f32_e32 v207, 1.0, v207
	v_add_f32_e32 v208, 1.0, v208
	v_rcp_f32_e32 v211, v210
	v_mul_f32_e32 v210, 0xbfb8aa3b, v72
	v_add_f32_e32 v226, 1.0, v226
	v_exp_f32_e32 v152, v152
	v_exp_f32_e32 v153, v153
	v_rcp_f32_e32 v207, v207
	v_rcp_f32_e32 v208, v208
	v_exp_f32_e32 v212, v210
	v_rcp_f32_e32 v228, v226
	v_add_f32_e32 v226, 1.0, v227
	v_mul_f32_e32 v165, 0xbfb8aa3b, v54
	v_mul_f32_e32 v166, 0xbfb8aa3b, v55
	v_mul_f32_e32 v167, 0xbfb8aa3b, v56
	v_mul_f32_e32 v175, 0xbfb8aa3b, v57
	v_add_f32_e32 v225, 1.0, v225
	v_rcp_f32_e32 v229, v226
	v_mul_f32_e32 v226, 0xbfb8aa3b, v87
	v_add_f32_e32 v236, 1.0, v236
	v_exp_f32_e32 v165, v165
	v_exp_f32_e32 v166, v166
	v_exp_f32_e32 v167, v167
	v_exp_f32_e32 v175, v175
	v_mul_f32_e32 v176, 0xbfb8aa3b, v58
	v_mul_f32_e32 v177, 0xbfb8aa3b, v59
	v_mul_f32_e32 v185, v60, v184
	v_mul_f32_e32 v186, v61, v190
	v_mul_f32_e32 v184, v62, v191
	v_add_f32_e32 v190, 1.0, v193
	v_mul_f32_e32 v191, 0xbfb8aa3b, v64
	v_mul_f32_e32 v193, 0xbfb8aa3b, v65
	v_rcp_f32_e32 v225, v225
	v_exp_f32_e32 v230, v226
	v_add_f32_e32 v234, 1.0, v234
	v_add_f32_e32 v235, 1.0, v235
	v_rcp_f32_e32 v237, v236
	v_mul_f32_e32 v236, 0xbfb8aa3b, v96
	v_add_f32_e32 v159, 1.0, v159
	v_add_f32_e32 v160, 1.0, v160
	v_add_f32_e32 v162, 1.0, v162
	v_add_f32_e32 v163, 1.0, v163
	v_add_f32_e32 v164, 1.0, v164
	v_exp_f32_e32 v176, v176
	v_exp_f32_e32 v177, v177
	v_exp_f32_e32 v191, v191
	v_exp_f32_e32 v193, v193
	v_mul_f32_e32 v196, 0xbfb8aa3b, v66
	v_mul_f32_e32 v198, 0xbfb8aa3b, v67
	v_mul_f32_e32 v199, 0xbfb8aa3b, v68
	v_rcp_f32_e32 v234, v234
	v_rcp_f32_e32 v235, v235
	v_exp_f32_e32 v238, v236
	v_add_f32_e32 v152, 1.0, v152
	v_add_f32_e32 v153, 1.0, v153
	v_rcp_f32_e32 v158, v158
	v_rcp_f32_e32 v159, v159
	v_rcp_f32_e32 v160, v160
	v_rcp_f32_e32 v162, v162
	v_rcp_f32_e32 v163, v163
	v_rcp_f32_e32 v164, v164
	v_exp_f32_e32 v196, v196
	v_exp_f32_e32 v198, v198
	v_exp_f32_e32 v199, v199
	v_mul_f32_e32 v210, v69, v207
	v_mul_f32_e32 v207, v70, v208
	v_mul_f32_e32 v208, v71, v211
	v_add_f32_e32 v211, 1.0, v212
	v_mul_f32_e32 v212, 0xbfb8aa3b, v73
	v_mul_f32_e32 v213, 0xbfb8aa3b, v74
	v_mul_f32_e32 v216, 0xbfb8aa3b, v75
	v_mul_f32_e32 v217, 0xbfb8aa3b, v76
	v_mul_f32_e32 v218, 0xbfb8aa3b, v77
	v_rcp_f32_e32 v152, v152
	v_rcp_f32_e32 v153, v153
	v_exp_f32_e32 v212, v212
	v_exp_f32_e32 v213, v213
	v_exp_f32_e32 v216, v216
	v_exp_f32_e32 v217, v217
	v_exp_f32_e32 v218, v218
	v_mul_f32_e32 v219, 0xbfb8aa3b, v78
	v_mul_f32_e32 v220, 0xbfb8aa3b, v79
	v_mul_f32_e32 v221, 0xbfb8aa3b, v80
	v_mul_f32_e32 v222, 0xbfb8aa3b, v81
	v_mul_f32_e32 v223, 0xbfb8aa3b, v82
	v_mul_f32_e32 v224, 0xbfb8aa3b, v83
	v_add_f32_e32 v165, 1.0, v165
	v_add_f32_e32 v166, 1.0, v166
	v_add_f32_e32 v167, 1.0, v167
	v_add_f32_e32 v175, 1.0, v175
	v_exp_f32_e32 v219, v219
	v_exp_f32_e32 v220, v220
	v_exp_f32_e32 v221, v221
	v_exp_f32_e32 v222, v222
	v_exp_f32_e32 v223, v223
	v_exp_f32_e32 v224, v224
	v_mul_f32_e32 v226, v84, v225
	v_mul_f32_e32 v227, v85, v228
	v_mul_f32_e32 v225, v86, v229
	v_add_f32_e32 v228, 1.0, v230
	v_mul_f32_e32 v229, 0xbfb8aa3b, v88
	v_mul_f32_e32 v230, 0xbfb8aa3b, v89
	v_mul_f32_e32 v231, 0xbfb8aa3b, v90
	v_mul_f32_e32 v232, 0xbfb8aa3b, v91
	v_mul_f32_e32 v233, 0xbfb8aa3b, v92
	v_rcp_f32_e32 v165, v165
	v_rcp_f32_e32 v166, v166
	v_rcp_f32_e32 v167, v167
	v_rcp_f32_e32 v175, v175
	v_add_f32_e32 v176, 1.0, v176
	v_add_f32_e32 v177, 1.0, v177
	v_add_f32_e32 v191, 1.0, v191
	v_add_f32_e32 v193, 1.0, v193
	v_exp_f32_e32 v229, v229
	v_exp_f32_e32 v230, v230
	v_exp_f32_e32 v231, v231
	v_exp_f32_e32 v232, v232
	v_exp_f32_e32 v233, v233
	v_mul_f32_e32 v236, v93, v234
	v_mul_f32_e32 v234, v94, v235
	v_mul_f32_e32 v235, v95, v237
	v_add_f32_e32 v237, 1.0, v238
	v_mul_f32_e32 v238, 0xbfb8aa3b, v97
	v_mul_f32_e32 v239, 0xbfb8aa3b, v98
	global_store_dwordx4 v[154:155], v[168:171], off nt
	v_cvt_pk_bf16_f32 v150, v150, v151
	v_mul_f32_e32 v158, v48, v158
	v_mul_f32_e32 v159, v49, v159
	v_mul_f32_e32 v160, v50, v160
	v_mul_f32_e32 v162, v51, v162
	v_mul_f32_e32 v163, v52, v163
	v_mul_f32_e32 v164, v53, v164
	v_rcp_f32_e32 v176, v176
	v_rcp_f32_e32 v177, v177
	v_rcp_f32_e32 v190, v190
	v_rcp_f32_e32 v191, v191
	v_rcp_f32_e32 v193, v193
	v_add_f32_e32 v196, 1.0, v196
	v_add_f32_e32 v198, 1.0, v198
	v_add_f32_e32 v199, 1.0, v199
	v_exp_f32_e32 v238, v238
	v_exp_f32_e32 v239, v239
	v_mul_f32_e32 v194, 0xbfb8aa3b, v104
	v_mul_f32_e32 v192, 0xbfb8aa3b, v108
	v_mul_f32_e32 v168, v120, v152
	v_mul_f32_e32 v169, v121, v153
	v_cvt_pk_bf16_f32 v151, v158, v159
	v_cvt_pk_bf16_f32 v152, v160, v162
	v_cvt_pk_bf16_f32 v153, v163, v164
	global_store_dwordx4 v[154:155], v[150:153], off offset:256 nt
	v_rcp_f32_e32 v196, v196
	v_rcp_f32_e32 v198, v198
	v_or_b32_e32 v150, 48, v140
	v_rcp_f32_e32 v199, v199
	v_add_f32_e32 v212, 1.0, v212
	v_add_f32_e32 v213, 1.0, v213
	v_add_f32_e32 v216, 1.0, v216
	v_add_f32_e32 v217, 1.0, v217
	v_add_f32_e32 v218, 1.0, v218
	v_exp_f32_e32 v194, v194
	v_exp_f32_e32 v192, v192
	v_ashrrev_i32_e32 v151, 31, v150
	v_rcp_f32_e32 v211, v211
	v_rcp_f32_e32 v212, v212
	v_rcp_f32_e32 v213, v213
	v_rcp_f32_e32 v216, v216
	v_rcp_f32_e32 v217, v217
	v_rcp_f32_e32 v218, v218
	v_add_f32_e32 v219, 1.0, v219
	v_add_f32_e32 v220, 1.0, v220
	v_add_f32_e32 v221, 1.0, v221
	v_add_f32_e32 v222, 1.0, v222
	v_add_f32_e32 v223, 1.0, v223
	v_add_f32_e32 v224, 1.0, v224
	v_mul_f32_e32 v172, 0xbfb8aa3b, v131
	v_mul_f32_e32 v149, 0xbfb8aa3b, v124
	v_lshlrev_b64 v[150:151], 13, v[150:151]
	v_mul_f32_e32 v165, v54, v165
	v_mul_f32_e32 v166, v55, v166
	v_mul_f32_e32 v167, v56, v167
	v_mul_f32_e32 v175, v57, v175
	v_rcp_f32_e32 v219, v219
	v_rcp_f32_e32 v220, v220
	v_rcp_f32_e32 v221, v221
	v_rcp_f32_e32 v222, v222
	v_rcp_f32_e32 v223, v223
	v_rcp_f32_e32 v224, v224
	v_add_f32_e32 v229, 1.0, v229
	v_add_f32_e32 v230, 1.0, v230
	v_add_f32_e32 v231, 1.0, v231
	v_add_f32_e32 v232, 1.0, v232
	v_add_f32_e32 v233, 1.0, v233
	v_exp_f32_e32 v172, v172
	v_exp_f32_e32 v149, v149
	v_lshl_add_u64 v[154:155], v[146:147], 0, v[150:151]
	v_cvt_pk_bf16_f32 v150, v165, v166
	v_cvt_pk_bf16_f32 v151, v167, v175
	v_mul_f32_e32 v176, v58, v176
	v_mul_f32_e32 v177, v59, v177
	v_mul_f32_e32 v190, v63, v190
	v_mul_f32_e32 v191, v64, v191
	v_mul_f32_e32 v193, v65, v193
	v_rcp_f32_e32 v228, v228
	v_rcp_f32_e32 v229, v229
	v_rcp_f32_e32 v230, v230
	v_rcp_f32_e32 v231, v231
	v_rcp_f32_e32 v232, v232
	v_rcp_f32_e32 v233, v233
	v_add_f32_e32 v238, 1.0, v238
	v_add_f32_e32 v239, 1.0, v239
	v_cvt_pk_bf16_f32 v152, v176, v177
	v_cvt_pk_bf16_f32 v153, v185, v186
	global_store_dwordx4 v[154:155], v[150:153], off nt
	v_mul_f32_e32 v196, v66, v196
	v_mul_f32_e32 v198, v67, v198
	v_cvt_pk_bf16_f32 v150, v184, v190
	v_cvt_pk_bf16_f32 v151, v191, v193
	v_mul_f32_e32 v199, v68, v199
	v_rcp_f32_e32 v237, v237
	v_rcp_f32_e32 v238, v238
	v_rcp_f32_e32 v239, v239
	v_add_f32_e32 v194, 1.0, v194
	v_add_f32_e32 v192, 1.0, v192
	v_cvt_pk_bf16_f32 v152, v196, v198
	v_cvt_pk_bf16_f32 v153, v199, v210
	global_store_dwordx4 v[154:155], v[150:153], off offset:256 nt
	v_mul_f32_e32 v211, v72, v211
	v_mul_f32_e32 v212, v73, v212
	v_lshlrev_b64 v[150:151], 13, v[142:143]
	v_mul_f32_e32 v213, v74, v213
	v_mul_f32_e32 v216, v75, v216
	v_mul_f32_e32 v217, v76, v217
	v_mul_f32_e32 v218, v77, v218
	v_rcp_f32_e32 v194, v194
	v_rcp_f32_e32 v192, v192
	v_lshl_add_u64 v[146:147], v[146:147], 0, v[150:151]
	v_cvt_pk_bf16_f32 v150, v207, v208
	v_cvt_pk_bf16_f32 v151, v211, v212
	v_cvt_pk_bf16_f32 v152, v213, v216
	v_cvt_pk_bf16_f32 v153, v217, v218
	v_add_co_u32_e32 v154, vcc, s72, v144
	v_mul_f32_e32 v219, v78, v219
	v_mul_f32_e32 v220, v79, v220
	v_mul_f32_e32 v221, v80, v221
	v_mul_f32_e32 v222, v81, v222
	v_mul_f32_e32 v223, v82, v223
	v_mul_f32_e32 v224, v83, v224
	v_add_f32_e32 v172, 1.0, v172
	v_add_f32_e32 v149, 1.0, v149
	global_store_dwordx4 v[146:147], v[150:153], off nt
	s_mov_b64 s[26:27], 0x120000
	v_addc_co_u32_e32 v155, vcc, 0, v145, vcc
	v_cvt_pk_bf16_f32 v150, v219, v220
	v_cvt_pk_bf16_f32 v151, v221, v222
	v_cvt_pk_bf16_f32 v152, v223, v224
	v_cvt_pk_bf16_f32 v153, v226, v227
	global_store_dwordx4 v[146:147], v[150:153], off offset:256 nt
	v_mul_f32_e32 v228, v87, v228
	v_mul_f32_e32 v229, v88, v229
	v_mul_f32_e32 v230, v89, v230
	v_mul_f32_e32 v231, v90, v231
	v_mul_f32_e32 v232, v91, v232
	v_mul_f32_e32 v233, v92, v233
	v_rcp_f32_e32 v172, v172
	v_rcp_f32_e32 v149, v149
	v_rcp_f32_e32 v161, v189
	v_lshl_add_u64 v[146:147], v[144:145], 0, s[26:27]
	v_cvt_pk_bf16_f32 v150, v225, v228
	v_cvt_pk_bf16_f32 v151, v229, v230
	v_cvt_pk_bf16_f32 v152, v231, v232
	v_cvt_pk_bf16_f32 v153, v233, v236
	global_store_dwordx4 v[154:155], v[150:153], off nt
	s_mov_b64 s[26:27], 0x140000
	v_add_co_u32_e32 v154, vcc, s73, v144
	v_mul_f32_e32 v237, v96, v237
	v_mul_f32_e32 v238, v97, v238
	v_mul_f32_e32 v239, v98, v239
	v_mul_f32_e32 v195, v99, v195
	v_cvt_pk_bf16_f32 v150, v234, v235
	v_cvt_pk_bf16_f32 v151, v237, v238
	v_cvt_pk_bf16_f32 v152, v239, v195
	v_cvt_pk_bf16_f32 v153, v206, v209
	global_store_dwordx4 v[146:147], v[150:153], off offset:256 nt
	v_lshl_add_u64 v[146:147], v[144:145], 0, s[26:27]
	v_addc_co_u32_e32 v155, vcc, 0, v145, vcc
	s_mov_b64 s[26:27], 0x160000
	v_mul_f32_e32 v194, v104, v194
	v_mul_f32_e32 v192, v108, v192
	v_cvt_pk_bf16_f32 v150, v241, v242
	v_cvt_pk_bf16_f32 v151, v194, v197
	v_cvt_pk_bf16_f32 v152, v240, v243
	v_cvt_pk_bf16_f32 v153, v192, v204
	global_store_dwordx4 v[154:155], v[150:153], off nt
	v_lshl_add_u64 v[154:155], v[144:145], 0, s[26:27]
	v_add_co_u32_e32 v144, vcc, 0x160000, v144
	v_mul_f32_e32 v173, v117, v173
	v_cvt_pk_bf16_f32 v150, v205, v187
	v_cvt_pk_bf16_f32 v151, v244, v245
	v_cvt_pk_bf16_f32 v152, v182, v200
	v_cvt_pk_bf16_f32 v153, v201, v173
	global_store_dwordx4 v[146:147], v[150:153], off offset:256 nt
	v_addc_co_u32_e32 v145, vcc, 0, v145, vcc
	v_mul_f32_e32 v172, v131, v172
	v_mul_f32_e32 v149, v124, v149
	v_mul_f32_e32 v157, v118, v157
	v_mul_f32_e32 v161, v119, v161
	v_cvt_pk_bf16_f32 v150, v183, v172
	v_cvt_pk_bf16_f32 v151, v174, v202
	v_cvt_pk_bf16_f32 v152, v203, v178
	v_cvt_pk_bf16_f32 v153, v179, v180
	global_store_dwordx4 v[144:145], v[150:153], off nt
	v_cvt_pk_bf16_f32 v144, v181, v188
	v_cvt_pk_bf16_f32 v145, v149, v156
	v_cvt_pk_bf16_f32 v146, v157, v161
	v_cvt_pk_bf16_f32 v147, v168, v169
	global_store_dwordx4 v[154:155], v[144:147], off offset:256 nt
	s_mov_b64 s[26:27], 0

.LBB0_346:
	s_add_u32 s54, s33, 0xffffff80
	s_addc_u32 s55, s52, -1
	s_cmp_eq_u32 s53, 60
	s_cselect_b32 s28, s2, s33
	s_cselect_b32 s29, s1, s52
	s_cselect_b32 s31, s11, s23
	s_cselect_b32 s30, s15, s19
	s_add_u32 s24, s28, 0x80
	s_addc_u32 s25, s29, 0
	s_add_u32 s26, s30, 0x80
	s_addc_u32 s27, s31, 0
	s_add_i32 s56, 0, 0x10000
	s_add_i32 s57, 0, 0x14000
	v_add_u32_e32 v152, s56, v1
	v_add_u32_e32 v168, s57, v1
	ds_read_b128 v[140:143], v152
	ds_read_b128 v[144:147], v152 offset:1024
	ds_read_b128 v[148:151], v152 offset:2048
	ds_read_b128 v[152:155], v152 offset:3072
	ds_read_b128 v[156:159], v168
	ds_read_b128 v[160:163], v168 offset:1024
	ds_read_b128 v[164:167], v168 offset:2048
	ds_read_b128 v[168:171], v168 offset:3072
	s_add_u32 s54, s54, 0x100000
	s_addc_u32 s55, s55, 0
	v_lshl_add_u64 v[204:205], s[54:55], 0, v[2:3]
	s_add_i32 m0, s41, 0xc000
	ds_read_b128 v[172:175], v5
	ds_read_b128 v[176:179], v5 offset:1024
	ds_read_b128 v[180:183], v5 offset:2048
	ds_read_b128 v[184:187], v5 offset:3072
	ds_read_b128 v[188:191], v5 offset:4096
	ds_read_b128 v[192:195], v5 offset:5120
	ds_read_b128 v[196:199], v5 offset:6144
	ds_read_b128 v[200:203], v5 offset:7168
	global_load_lds_dwordx4 v[204:205], off
	v_lshl_add_u64 v[204:205], s[54:55], 0, v[136:137]
	s_add_i32 m0, s41, 0xe000
	s_nop 0
	global_load_lds_dwordx4 v[204:205], off
	s_waitcnt vmcnt(8)
	s_waitcnt lgkmcnt(0)
	s_barrier
	s_setprio 1
	v_mfma_f32_16x16x32_bf16 v[130:133], v[140:143], v[172:175], v[130:133]
	v_mfma_f32_16x16x32_bf16 v[126:129], v[148:151], v[172:175], v[126:129]
	v_mfma_f32_16x16x32_bf16 v[114:117], v[140:143], v[180:183], v[114:117]
	v_mfma_f32_16x16x32_bf16 v[110:113], v[148:151], v[180:183], v[110:113]
	v_mfma_f32_16x16x32_bf16 v[98:101], v[140:143], v[188:191], v[98:101]
	v_mfma_f32_16x16x32_bf16 v[94:97], v[148:151], v[188:191], v[94:97]
	v_mfma_f32_16x16x32_bf16 v[82:85], v[140:143], v[196:199], v[82:85]
	v_mfma_f32_16x16x32_bf16 v[78:81], v[148:151], v[196:199], v[78:81]
	v_mfma_f32_16x16x32_bf16 v[130:133], v[144:147], v[176:179], v[130:133]
	v_mfma_f32_16x16x32_bf16 v[126:129], v[152:155], v[176:179], v[126:129]
	v_mfma_f32_16x16x32_bf16 v[114:117], v[144:147], v[184:187], v[114:117]
	v_mfma_f32_16x16x32_bf16 v[110:113], v[152:155], v[184:187], v[110:113]
	v_mfma_f32_16x16x32_bf16 v[98:101], v[144:147], v[192:195], v[98:101]
	v_mfma_f32_16x16x32_bf16 v[94:97], v[152:155], v[192:195], v[94:97]
	v_mfma_f32_16x16x32_bf16 v[82:85], v[144:147], v[200:203], v[82:85]
	v_mfma_f32_16x16x32_bf16 v[78:81], v[152:155], v[200:203], v[78:81]
	v_mfma_f32_16x16x32_bf16 v[122:125], v[156:159], v[172:175], v[122:125]
	v_mfma_f32_16x16x32_bf16 v[118:121], v[164:167], v[172:175], v[118:121]
	v_mfma_f32_16x16x32_bf16 v[106:109], v[156:159], v[180:183], v[106:109]
	v_mfma_f32_16x16x32_bf16 v[102:105], v[164:167], v[180:183], v[102:105]
	v_mfma_f32_16x16x32_bf16 v[90:93], v[156:159], v[188:191], v[90:93]
	v_mfma_f32_16x16x32_bf16 v[86:89], v[164:167], v[188:191], v[86:89]
	v_mfma_f32_16x16x32_bf16 v[74:77], v[156:159], v[196:199], v[74:77]
	v_mfma_f32_16x16x32_bf16 v[70:73], v[164:167], v[196:199], v[70:73]
	v_mfma_f32_16x16x32_bf16 v[122:125], v[160:163], v[176:179], v[122:125]
	v_mfma_f32_16x16x32_bf16 v[118:121], v[168:171], v[176:179], v[118:121]
	v_mfma_f32_16x16x32_bf16 v[106:109], v[160:163], v[184:187], v[106:109]
	v_mfma_f32_16x16x32_bf16 v[102:105], v[168:171], v[184:187], v[102:105]
	v_mfma_f32_16x16x32_bf16 v[90:93], v[160:163], v[192:195], v[90:93]
	v_mfma_f32_16x16x32_bf16 v[86:89], v[168:171], v[192:195], v[86:89]
	v_mfma_f32_16x16x32_bf16 v[74:77], v[160:163], v[200:203], v[74:77]
	v_mfma_f32_16x16x32_bf16 v[70:73], v[168:171], v[200:203], v[70:73]
	s_setprio 0
	s_barrier
	s_add_i32 s54, s56, s38
	v_lshl_add_u64 v[204:205], s[30:31], 0, v[134:135]
	s_mov_b32 m0, s54
	ds_read_b128 v[172:175], v5 offset:16384
	ds_read_b128 v[176:179], v5 offset:17408
	ds_read_b128 v[180:183], v5 offset:18432
	ds_read_b128 v[184:187], v5 offset:19456
	ds_read_b128 v[188:191], v5 offset:20480
	ds_read_b128 v[192:195], v5 offset:21504
	ds_read_b128 v[196:199], v5 offset:22528
	ds_read_b128 v[200:203], v5 offset:23552
	global_load_lds_dwordx4 v[204:205], off
	s_add_i32 m0, s54, 0x2000
	v_lshl_add_u64 v[204:205], s[30:31], 0, v[138:139]
	s_add_u32 s30, s30, 0x100000
	s_addc_u32 s31, s31, 0
	s_add_i32 s54, s57, s38
	global_load_lds_dwordx4 v[204:205], off
	v_lshl_add_u64 v[204:205], s[30:31], 0, v[134:135]
	s_mov_b32 m0, s54
	s_nop 0
	global_load_lds_dwordx4 v[204:205], off
	v_lshl_add_u64 v[204:205], s[30:31], 0, v[138:139]
	s_add_i32 m0, s54, 0x2000
	s_nop 0
	global_load_lds_dwordx4 v[204:205], off
	v_lshl_add_u64 v[204:205], s[28:29], 0, v[2:3]
	s_mov_b32 m0, s41
	s_nop 0
	global_load_lds_dwordx4 v[204:205], off
	v_lshl_add_u64 v[204:205], s[28:29], 0, v[136:137]
	s_mov_b32 m0, s3
	s_nop 0
	global_load_lds_dwordx4 v[204:205], off
	s_waitcnt vmcnt(8)
	s_waitcnt lgkmcnt(0)
	s_barrier
	s_setprio 1
	v_mfma_f32_16x16x32_bf16 v[66:69], v[140:143], v[172:175], v[66:69]
	v_mfma_f32_16x16x32_bf16 v[62:65], v[148:151], v[172:175], v[62:65]
	v_mfma_f32_16x16x32_bf16 v[50:53], v[140:143], v[180:183], v[50:53]
	v_mfma_f32_16x16x32_bf16 v[46:49], v[148:151], v[180:183], v[46:49]
	v_mfma_f32_16x16x32_bf16 v[34:37], v[140:143], v[188:191], v[34:37]
	v_mfma_f32_16x16x32_bf16 v[30:33], v[148:151], v[188:191], v[30:33]
	v_mfma_f32_16x16x32_bf16 v[18:21], v[140:143], v[196:199], v[18:21]
	v_mfma_f32_16x16x32_bf16 v[14:17], v[148:151], v[196:199], v[14:17]
	v_mfma_f32_16x16x32_bf16 v[66:69], v[144:147], v[176:179], v[66:69]
	v_mfma_f32_16x16x32_bf16 v[62:65], v[152:155], v[176:179], v[62:65]
	v_mfma_f32_16x16x32_bf16 v[50:53], v[144:147], v[184:187], v[50:53]
	v_mfma_f32_16x16x32_bf16 v[46:49], v[152:155], v[184:187], v[46:49]
	v_mfma_f32_16x16x32_bf16 v[34:37], v[144:147], v[192:195], v[34:37]
	v_mfma_f32_16x16x32_bf16 v[30:33], v[152:155], v[192:195], v[30:33]
	v_mfma_f32_16x16x32_bf16 v[18:21], v[144:147], v[200:203], v[18:21]
	v_mfma_f32_16x16x32_bf16 v[14:17], v[152:155], v[200:203], v[14:17]
	v_mfma_f32_16x16x32_bf16 v[58:61], v[156:159], v[172:175], v[58:61]
	v_mfma_f32_16x16x32_bf16 v[54:57], v[164:167], v[172:175], v[54:57]
	v_mfma_f32_16x16x32_bf16 v[42:45], v[156:159], v[180:183], v[42:45]
	v_mfma_f32_16x16x32_bf16 v[38:41], v[164:167], v[180:183], v[38:41]
	v_mfma_f32_16x16x32_bf16 v[26:29], v[156:159], v[188:191], v[26:29]
	v_mfma_f32_16x16x32_bf16 v[22:25], v[164:167], v[188:191], v[22:25]
	v_mfma_f32_16x16x32_bf16 v[10:13], v[156:159], v[196:199], v[10:13]
	v_mfma_f32_16x16x32_bf16 v[6:9], v[164:167], v[196:199], v[6:9]
	v_mfma_f32_16x16x32_bf16 v[58:61], v[160:163], v[176:179], v[58:61]
	v_mfma_f32_16x16x32_bf16 v[54:57], v[168:171], v[176:179], v[54:57]
	v_mfma_f32_16x16x32_bf16 v[42:45], v[160:163], v[184:187], v[42:45]
	v_mfma_f32_16x16x32_bf16 v[38:41], v[168:171], v[184:187], v[38:41]
	v_mfma_f32_16x16x32_bf16 v[26:29], v[160:163], v[192:195], v[26:29]
	v_mfma_f32_16x16x32_bf16 v[22:25], v[168:171], v[192:195], v[22:25]
	v_mfma_f32_16x16x32_bf16 v[10:13], v[160:163], v[200:203], v[10:13]
	v_mfma_f32_16x16x32_bf16 v[6:9], v[168:171], v[200:203], v[6:9]
	s_setprio 0
	s_barrier
	s_add_i32 s30, 0, 0x18000
	s_add_i32 s31, 0, 0x1c000
	v_add_u32_e32 v152, s30, v1
	v_add_u32_e32 v168, s31, v1
	ds_read_b128 v[140:143], v152
	ds_read_b128 v[144:147], v152 offset:1024
	ds_read_b128 v[148:151], v152 offset:2048
	ds_read_b128 v[152:155], v152 offset:3072
	ds_read_b128 v[156:159], v168
	ds_read_b128 v[160:163], v168 offset:1024
	ds_read_b128 v[164:167], v168 offset:2048
	ds_read_b128 v[168:171], v168 offset:3072
	s_add_u32 s28, s28, 0x100000
	s_addc_u32 s29, s29, 0
	s_mov_b32 m0, s43
	v_lshl_add_u64 v[204:205], s[28:29], 0, v[2:3]
	ds_read_b128 v[172:175], v5 offset:32768
	ds_read_b128 v[176:179], v5 offset:33792
	ds_read_b128 v[180:183], v5 offset:34816
	ds_read_b128 v[184:187], v5 offset:35840
	ds_read_b128 v[188:191], v5 offset:36864
	ds_read_b128 v[192:195], v5 offset:37888
	ds_read_b128 v[196:199], v5 offset:38912
	ds_read_b128 v[200:203], v5 offset:39936
	global_load_lds_dwordx4 v[204:205], off
	v_lshl_add_u64 v[204:205], s[28:29], 0, v[136:137]
	s_mov_b32 m0, s46
	s_nop 0
	global_load_lds_dwordx4 v[204:205], off
	s_waitcnt vmcnt(8)
	s_waitcnt lgkmcnt(0)
	s_barrier
	s_setprio 1
	v_mfma_f32_16x16x32_bf16 v[130:133], v[140:143], v[172:175], v[130:133]
	v_mfma_f32_16x16x32_bf16 v[126:129], v[148:151], v[172:175], v[126:129]
	v_mfma_f32_16x16x32_bf16 v[114:117], v[140:143], v[180:183], v[114:117]
	v_mfma_f32_16x16x32_bf16 v[110:113], v[148:151], v[180:183], v[110:113]
	v_mfma_f32_16x16x32_bf16 v[98:101], v[140:143], v[188:191], v[98:101]
	v_mfma_f32_16x16x32_bf16 v[94:97], v[148:151], v[188:191], v[94:97]
	v_mfma_f32_16x16x32_bf16 v[82:85], v[140:143], v[196:199], v[82:85]
	v_mfma_f32_16x16x32_bf16 v[78:81], v[148:151], v[196:199], v[78:81]
	v_mfma_f32_16x16x32_bf16 v[130:133], v[144:147], v[176:179], v[130:133]
	v_mfma_f32_16x16x32_bf16 v[126:129], v[152:155], v[176:179], v[126:129]
	v_mfma_f32_16x16x32_bf16 v[114:117], v[144:147], v[184:187], v[114:117]
	v_mfma_f32_16x16x32_bf16 v[110:113], v[152:155], v[184:187], v[110:113]
	v_mfma_f32_16x16x32_bf16 v[98:101], v[144:147], v[192:195], v[98:101]
	v_mfma_f32_16x16x32_bf16 v[94:97], v[152:155], v[192:195], v[94:97]
	v_mfma_f32_16x16x32_bf16 v[82:85], v[144:147], v[200:203], v[82:85]
	v_mfma_f32_16x16x32_bf16 v[78:81], v[152:155], v[200:203], v[78:81]
	v_mfma_f32_16x16x32_bf16 v[122:125], v[156:159], v[172:175], v[122:125]
	v_mfma_f32_16x16x32_bf16 v[118:121], v[164:167], v[172:175], v[118:121]
	v_mfma_f32_16x16x32_bf16 v[106:109], v[156:159], v[180:183], v[106:109]
	v_mfma_f32_16x16x32_bf16 v[102:105], v[164:167], v[180:183], v[102:105]
	v_mfma_f32_16x16x32_bf16 v[90:93], v[156:159], v[188:191], v[90:93]
	v_mfma_f32_16x16x32_bf16 v[86:89], v[164:167], v[188:191], v[86:89]
	v_mfma_f32_16x16x32_bf16 v[74:77], v[156:159], v[196:199], v[74:77]
	v_mfma_f32_16x16x32_bf16 v[70:73], v[164:167], v[196:199], v[70:73]
	v_mfma_f32_16x16x32_bf16 v[122:125], v[160:163], v[176:179], v[122:125]
	v_mfma_f32_16x16x32_bf16 v[118:121], v[168:171], v[176:179], v[118:121]
	v_mfma_f32_16x16x32_bf16 v[106:109], v[160:163], v[184:187], v[106:109]
	v_mfma_f32_16x16x32_bf16 v[102:105], v[168:171], v[184:187], v[102:105]
	v_mfma_f32_16x16x32_bf16 v[90:93], v[160:163], v[192:195], v[90:93]
	v_mfma_f32_16x16x32_bf16 v[86:89], v[168:171], v[192:195], v[86:89]
	v_mfma_f32_16x16x32_bf16 v[74:77], v[160:163], v[200:203], v[74:77]
	v_mfma_f32_16x16x32_bf16 v[70:73], v[168:171], v[200:203], v[70:73]
	s_setprio 0
	s_barrier
	s_add_i32 s28, s30, s38
	v_lshl_add_u64 v[204:205], s[26:27], 0, v[134:135]
	s_mov_b32 m0, s28
	ds_read_b128 v[172:175], v5 offset:49152
	ds_read_b128 v[176:179], v5 offset:50176
	ds_read_b128 v[180:183], v5 offset:51200
	ds_read_b128 v[184:187], v5 offset:52224
	ds_read_b128 v[188:191], v5 offset:53248
	ds_read_b128 v[192:195], v5 offset:54272
	ds_read_b128 v[196:199], v5 offset:55296
	ds_read_b128 v[200:203], v5 offset:56320
	global_load_lds_dwordx4 v[204:205], off
	s_add_i32 m0, s28, 0x2000
	v_lshl_add_u64 v[204:205], s[26:27], 0, v[138:139]
	s_add_u32 s26, s26, 0x100000
	s_addc_u32 s27, s27, 0
	s_add_i32 s28, s31, s38
	global_load_lds_dwordx4 v[204:205], off
	v_lshl_add_u64 v[204:205], s[26:27], 0, v[134:135]
	s_mov_b32 m0, s28
	s_nop 0
	global_load_lds_dwordx4 v[204:205], off
	v_lshl_add_u64 v[204:205], s[26:27], 0, v[138:139]
	s_add_i32 m0, s28, 0x2000
	s_nop 0
	global_load_lds_dwordx4 v[204:205], off
	v_lshl_add_u64 v[204:205], s[24:25], 0, v[2:3]
	s_mov_b32 m0, s49
	s_nop 0
	global_load_lds_dwordx4 v[204:205], off
	v_lshl_add_u64 v[204:205], s[24:25], 0, v[136:137]
	s_mov_b32 m0, s50
	s_nop 0
	global_load_lds_dwordx4 v[204:205], off
	s_waitcnt vmcnt(8)
	s_waitcnt lgkmcnt(0)
	s_barrier
	s_setprio 1
	v_mfma_f32_16x16x32_bf16 v[66:69], v[140:143], v[172:175], v[66:69]
	v_mfma_f32_16x16x32_bf16 v[62:65], v[148:151], v[172:175], v[62:65]
	v_mfma_f32_16x16x32_bf16 v[50:53], v[140:143], v[180:183], v[50:53]
	v_mfma_f32_16x16x32_bf16 v[46:49], v[148:151], v[180:183], v[46:49]
	v_mfma_f32_16x16x32_bf16 v[34:37], v[140:143], v[188:191], v[34:37]
	v_mfma_f32_16x16x32_bf16 v[30:33], v[148:151], v[188:191], v[30:33]
	v_mfma_f32_16x16x32_bf16 v[18:21], v[140:143], v[196:199], v[18:21]
	v_mfma_f32_16x16x32_bf16 v[14:17], v[148:151], v[196:199], v[14:17]
	v_mfma_f32_16x16x32_bf16 v[66:69], v[144:147], v[176:179], v[66:69]
	v_mfma_f32_16x16x32_bf16 v[62:65], v[152:155], v[176:179], v[62:65]
	v_mfma_f32_16x16x32_bf16 v[50:53], v[144:147], v[184:187], v[50:53]
	v_mfma_f32_16x16x32_bf16 v[46:49], v[152:155], v[184:187], v[46:49]
	v_mfma_f32_16x16x32_bf16 v[34:37], v[144:147], v[192:195], v[34:37]
	v_mfma_f32_16x16x32_bf16 v[30:33], v[152:155], v[192:195], v[30:33]
	v_mfma_f32_16x16x32_bf16 v[18:21], v[144:147], v[200:203], v[18:21]
	v_mfma_f32_16x16x32_bf16 v[14:17], v[152:155], v[200:203], v[14:17]
	v_mfma_f32_16x16x32_bf16 v[58:61], v[156:159], v[172:175], v[58:61]
	v_mfma_f32_16x16x32_bf16 v[54:57], v[164:167], v[172:175], v[54:57]
	v_mfma_f32_16x16x32_bf16 v[42:45], v[156:159], v[180:183], v[42:45]
	v_mfma_f32_16x16x32_bf16 v[38:41], v[164:167], v[180:183], v[38:41]
	v_mfma_f32_16x16x32_bf16 v[26:29], v[156:159], v[188:191], v[26:29]
	v_mfma_f32_16x16x32_bf16 v[22:25], v[164:167], v[188:191], v[22:25]
	v_mfma_f32_16x16x32_bf16 v[10:13], v[156:159], v[196:199], v[10:13]
	v_mfma_f32_16x16x32_bf16 v[6:9], v[164:167], v[196:199], v[6:9]
	v_mfma_f32_16x16x32_bf16 v[58:61], v[160:163], v[176:179], v[58:61]
	v_mfma_f32_16x16x32_bf16 v[54:57], v[168:171], v[176:179], v[54:57]
	v_mfma_f32_16x16x32_bf16 v[42:45], v[160:163], v[184:187], v[42:45]
	v_mfma_f32_16x16x32_bf16 v[38:41], v[168:171], v[184:187], v[38:41]
	v_mfma_f32_16x16x32_bf16 v[26:29], v[160:163], v[192:195], v[26:29]
	v_mfma_f32_16x16x32_bf16 v[22:25], v[168:171], v[192:195], v[22:25]
	v_mfma_f32_16x16x32_bf16 v[10:13], v[160:163], v[200:203], v[10:13]
	v_mfma_f32_16x16x32_bf16 v[6:9], v[168:171], v[200:203], v[6:9]
	s_setprio 0
	s_barrier
	s_add_i32 s53, s53, 2
	s_add_u32 s19, s19, 0x100
	s_addc_u32 s23, s23, 0
	s_add_u32 s33, s33, 0x100
	s_addc_u32 s52, s52, 0
	s_cmp_gt_u32 s53, 61
	s_cbranch_scc0 .LBB0_346
	v_mov_b32_e32 v140, v0
	s_lshl_b32 s1, s0, 8
	s_mov_b64 s[24:25], s[84:85]
	s_add_i32 s1, s1, s47
	v_bfe_u32 v210, v140, 4, 2
	v_and_or_b32 v140, v140, 15, s1
	s_add_u32 s26, s24, s6
	s_addc_u32 s27, s25, s7
	v_ashrrev_i32_e32 v141, 31, v140
	v_lshl_add_u64 v[142:143], v[140:141], 2, s[26:27]
	s_mov_b64 s[26:27], 0x10000
	v_lshl_add_u64 v[154:155], v[142:143], 0, s[26:27]
	v_add_co_u32_e32 v142, vcc, s91, v142
	s_cmp_gt_i32 s22, 3
	s_nop 0
	v_addc_co_u32_e32 v143, vcc, 0, v143, vcc
	global_load_dword v142, v[142:143], off
	s_cselect_b64 s[28:29], -1, 0
	s_cmp_lt_i32 s22, 4
	s_cselect_b64 s[26:27], -1, 0
	global_load_dword v205, v[154:155], off offset:64
	global_load_dword v204, v[154:155], off offset:128
	global_load_dword v203, v[154:155], off offset:192
	global_load_dword v202, v[154:155], off offset:512
	global_load_dword v201, v[154:155], off offset:576
	global_load_dword v200, v[154:155], off offset:640
	global_load_dword v199, v[154:155], off offset:704
	s_waitcnt vmcnt(0)
	v_fmamk_f32 v142, v142, 0x39800000, v246
	v_cmp_gt_f32_e32 vcc, s95, v142
	v_mul_f32_e32 v143, 0x4b800000, v142
	s_nop 0
	v_cndmask_b32_e32 v142, v142, v143, vcc
	v_rsq_f32_e32 v142, v142
	s_nop 0
	v_mul_f32_e32 v143, 0x45800000, v142
	v_cndmask_b32_e32 v142, v142, v143, vcc
	v_pk_mul_f32 v[132:133], v[132:133], v[142:143] op_sel_hi:[1,0]
	v_pk_mul_f32 v[130:131], v[130:131], v[142:143] op_sel_hi:[1,0]
	v_pk_mul_f32 v[128:129], v[128:129], v[142:143] op_sel_hi:[1,0]
	v_pk_mul_f32 v[126:127], v[126:127], v[142:143] op_sel_hi:[1,0]
	v_pk_mul_f32 v[124:125], v[124:125], v[142:143] op_sel_hi:[1,0]
	v_pk_mul_f32 v[122:123], v[122:123], v[142:143] op_sel_hi:[1,0]
	v_pk_mul_f32 v[120:121], v[120:121], v[142:143] op_sel_hi:[1,0]
	v_pk_mul_f32 v[118:119], v[118:119], v[142:143] op_sel_hi:[1,0]
	s_waitcnt vmcnt(0)
	v_fmamk_f32 v142, v205, 0x39800000, v246
	v_cmp_gt_f32_e32 vcc, s95, v142
	v_mul_f32_e32 v143, 0x4b800000, v142
	s_nop 0
	v_cndmask_b32_e32 v142, v142, v143, vcc
	v_rsq_f32_e32 v142, v142
	s_nop 0
	v_mul_f32_e32 v143, 0x45800000, v142
	v_cndmask_b32_e32 v142, v142, v143, vcc
	v_pk_mul_f32 v[116:117], v[116:117], v[142:143] op_sel_hi:[1,0]
	v_pk_mul_f32 v[114:115], v[114:115], v[142:143] op_sel_hi:[1,0]
	v_pk_mul_f32 v[112:113], v[112:113], v[142:143] op_sel_hi:[1,0]
	v_pk_mul_f32 v[110:111], v[110:111], v[142:143] op_sel_hi:[1,0]
	v_pk_mul_f32 v[108:109], v[108:109], v[142:143] op_sel_hi:[1,0]
	v_pk_mul_f32 v[106:107], v[106:107], v[142:143] op_sel_hi:[1,0]
	v_pk_mul_f32 v[104:105], v[104:105], v[142:143] op_sel_hi:[1,0]
	v_pk_mul_f32 v[102:103], v[102:103], v[142:143] op_sel_hi:[1,0]
	s_waitcnt vmcnt(0)
	v_fmamk_f32 v142, v204, 0x39800000, v246
	v_cmp_gt_f32_e32 vcc, s95, v142
	v_mul_f32_e32 v143, 0x4b800000, v142
	s_nop 0
	v_cndmask_b32_e32 v142, v142, v143, vcc
	v_rsq_f32_e32 v142, v142
	s_nop 0
	v_mul_f32_e32 v143, 0x45800000, v142
	v_cndmask_b32_e32 v142, v142, v143, vcc
	v_pk_mul_f32 v[150:151], v[94:95], v[142:143] op_sel_hi:[1,0]
	v_pk_mul_f32 v[152:153], v[98:99], v[142:143] op_sel_hi:[1,0]
	v_pk_mul_f32 v[100:101], v[100:101], v[142:143] op_sel_hi:[1,0]
	v_pk_mul_f32 v[92:93], v[92:93], v[142:143] op_sel_hi:[1,0]
	v_pk_mul_f32 v[90:91], v[90:91], v[142:143] op_sel_hi:[1,0]
	v_pk_mul_f32 v[86:87], v[86:87], v[142:143] op_sel_hi:[1,0]
	v_pk_mul_f32 v[96:97], v[96:97], v[142:143] op_sel_hi:[1,0]
	v_pk_mul_f32 v[88:89], v[88:89], v[142:143] op_sel_hi:[1,0]
	s_waitcnt vmcnt(0)
	v_fmamk_f32 v94, v203, 0x39800000, v246
	v_cmp_gt_f32_e32 vcc, s95, v94
	v_mul_f32_e32 v95, 0x4b800000, v94
	s_nop 0
	v_cndmask_b32_e32 v94, v94, v95, vcc
	v_rsq_f32_e32 v94, v94
	s_nop 0
	v_mul_f32_e32 v95, 0x45800000, v94
	v_cndmask_b32_e32 v94, v94, v95, vcc
	v_pk_mul_f32 v[164:165], v[80:81], v[94:95] op_sel_hi:[1,0]
	v_pk_mul_f32 v[80:81], v[74:75], v[94:95] op_sel_hi:[1,0]
	v_pk_mul_f32 v[166:167], v[84:85], v[94:95] op_sel_hi:[1,0]
	v_pk_mul_f32 v[170:171], v[82:83], v[94:95] op_sel_hi:[1,0]
	v_pk_mul_f32 v[168:169], v[78:79], v[94:95] op_sel_hi:[1,0]
	v_pk_mul_f32 v[78:79], v[76:77], v[94:95] op_sel_hi:[1,0]
	v_pk_mul_f32 v[72:73], v[72:73], v[94:95] op_sel_hi:[1,0]
	v_pk_mul_f32 v[70:71], v[70:71], v[94:95] op_sel_hi:[1,0]
	s_waitcnt vmcnt(0)
	v_fmamk_f32 v74, v202, 0x39800000, v246
	v_cmp_gt_f32_e32 vcc, s95, v74
	v_mul_f32_e32 v75, 0x4b800000, v74
	s_nop 0
	v_cndmask_b32_e32 v74, v74, v75, vcc
	v_rsq_f32_e32 v74, v74
	s_nop 0
	v_mul_f32_e32 v75, 0x45800000, v74
	v_cndmask_b32_e32 v98, v74, v75, vcc
	v_pk_mul_f32 v[76:77], v[68:69], v[98:99] op_sel_hi:[1,0]
	v_pk_mul_f32 v[176:177], v[66:67], v[98:99] op_sel_hi:[1,0]
	v_pk_mul_f32 v[74:75], v[64:65], v[98:99] op_sel_hi:[1,0]
	v_pk_mul_f32 v[174:175], v[62:63], v[98:99] op_sel_hi:[1,0]
	v_pk_mul_f32 v[84:85], v[60:61], v[98:99] op_sel_hi:[1,0]
	v_pk_mul_f32 v[94:95], v[58:59], v[98:99] op_sel_hi:[1,0]
	v_pk_mul_f32 v[82:83], v[56:57], v[98:99] op_sel_hi:[1,0]
	v_pk_mul_f32 v[98:99], v[54:55], v[98:99] op_sel_hi:[1,0]
	s_waitcnt vmcnt(0)
	v_fmamk_f32 v54, v201, 0x39800000, v246
	v_cmp_gt_f32_e32 vcc, s95, v54
	v_mul_f32_e32 v55, 0x4b800000, v54
	s_nop 0
	v_cndmask_b32_e32 v54, v54, v55, vcc
	v_rsq_f32_e32 v54, v54
	s_nop 0
	v_mul_f32_e32 v55, 0x45800000, v54
	v_cndmask_b32_e32 v54, v54, v55, vcc
	v_pk_mul_f32 v[146:147], v[38:39], v[54:55] op_sel_hi:[1,0]
	v_pk_mul_f32 v[180:181], v[52:53], v[54:55] op_sel_hi:[1,0]
	v_pk_mul_f32 v[184:185], v[50:51], v[54:55] op_sel_hi:[1,0]
	v_pk_mul_f32 v[144:145], v[44:45], v[54:55] op_sel_hi:[1,0]
	v_pk_mul_f32 v[148:149], v[42:43], v[54:55] op_sel_hi:[1,0]
	v_pk_mul_f32 v[182:183], v[46:47], v[54:55] op_sel_hi:[1,0]
	v_pk_mul_f32 v[178:179], v[48:49], v[54:55] op_sel_hi:[1,0]
	v_pk_mul_f32 v[142:143], v[40:41], v[54:55] op_sel_hi:[1,0]
	s_waitcnt vmcnt(0)
	v_fmamk_f32 v38, v200, 0x39800000, v246
	v_cmp_gt_f32_e32 vcc, s95, v38
	v_mul_f32_e32 v39, 0x4b800000, v38
	s_nop 0
	v_cndmask_b32_e32 v38, v38, v39, vcc
	v_rsq_f32_e32 v38, v38
	s_nop 0
	v_mul_f32_e32 v39, 0x45800000, v38
	v_cndmask_b32_e32 v38, v38, v39, vcc
	v_pk_mul_f32 v[160:161], v[22:23], v[38:39] op_sel_hi:[1,0]
	v_pk_mul_f32 v[188:189], v[36:37], v[38:39] op_sel_hi:[1,0]
	v_pk_mul_f32 v[192:193], v[34:35], v[38:39] op_sel_hi:[1,0]
	v_pk_mul_f32 v[158:159], v[28:29], v[38:39] op_sel_hi:[1,0]
	v_pk_mul_f32 v[162:163], v[26:27], v[38:39] op_sel_hi:[1,0]
	v_pk_mul_f32 v[186:187], v[32:33], v[38:39] op_sel_hi:[1,0]
	v_pk_mul_f32 v[190:191], v[30:31], v[38:39] op_sel_hi:[1,0]
	v_pk_mul_f32 v[156:157], v[24:25], v[38:39] op_sel_hi:[1,0]
	v_mul_f32_e32 v24, v95, v95
	v_mul_f32_e32 v25, v85, v85
	v_mul_f32_e32 v26, v185, v185
	v_mul_f32_e32 v27, v181, v181
	v_mul_f32_e32 v28, v149, v149
	v_mul_f32_e32 v29, v145, v145
	v_mul_f32_e32 v30, v193, v193
	v_mul_f32_e32 v31, v189, v189
	v_mul_f32_e32 v32, v163, v163
	v_mul_f32_e32 v33, v159, v159
	v_fmac_f32_e32 v24, v94, v94
	v_fmac_f32_e32 v25, v84, v84
	v_fmac_f32_e32 v26, v184, v184
	v_fmac_f32_e32 v27, v180, v180
	v_fmac_f32_e32 v28, v148, v148
	v_fmac_f32_e32 v29, v144, v144
	v_fmac_f32_e32 v30, v192, v192
	v_fmac_f32_e32 v31, v188, v188
	v_fmac_f32_e32 v32, v162, v162
	v_fmac_f32_e32 v33, v158, v158
	v_add_f32_e32 v24, v24, v25
	v_mul_f32_e32 v25, v99, v99
	v_add_f32_e32 v26, v26, v27
	v_mul_f32_e32 v27, v183, v183
	v_add_f32_e32 v28, v28, v29
	v_mul_f32_e32 v29, v147, v147
	v_add_f32_e32 v30, v30, v31
	v_mul_f32_e32 v31, v191, v191
	v_add_f32_e32 v32, v32, v33
	v_mul_f32_e32 v33, v161, v161
	v_fmac_f32_e32 v25, v98, v98
	v_fmac_f32_e32 v27, v182, v182
	v_fmac_f32_e32 v29, v146, v146
	v_fmac_f32_e32 v31, v190, v190
	v_fmac_f32_e32 v33, v160, v160
	v_add_f32_e32 v24, v25, v24
	v_mul_f32_e32 v25, v83, v83
	v_add_f32_e32 v26, v27, v26
	v_mul_f32_e32 v27, v179, v179
	v_add_f32_e32 v28, v29, v28
	v_mul_f32_e32 v29, v143, v143
	v_add_f32_e32 v30, v31, v30
	v_mul_f32_e32 v31, v187, v187
	v_add_f32_e32 v32, v33, v32
	v_mul_f32_e32 v33, v157, v157
	v_fmac_f32_e32 v25, v82, v82
	v_fmac_f32_e32 v27, v178, v178
	v_fmac_f32_e32 v29, v142, v142
	v_fmac_f32_e32 v31, v186, v186
	v_fmac_f32_e32 v33, v156, v156
	v_add_f32_e32 v24, v25, v24
	v_add_f32_e32 v26, v27, v26
	v_add_f32_e32 v28, v29, v28
	v_add_f32_e32 v30, v31, v30
	v_add_f32_e32 v32, v33, v32
	ds_swizzle_b32 v25, v24 offset:swizzle(SWAP,16)
	ds_swizzle_b32 v27, v26 offset:swizzle(SWAP,16)
	ds_swizzle_b32 v29, v28 offset:swizzle(SWAP,16)
	ds_swizzle_b32 v31, v30 offset:swizzle(SWAP,16)
	ds_swizzle_b32 v33, v32 offset:swizzle(SWAP,16)
	s_waitcnt lgkmcnt(4)
	v_add_f32_e32 v24, v24, v25
	s_waitcnt lgkmcnt(3)
	v_add_f32_e32 v26, v26, v27
	s_waitcnt lgkmcnt(2)
	v_add_f32_e32 v28, v28, v29
	s_waitcnt lgkmcnt(1)
	v_add_f32_e32 v30, v30, v31
	s_waitcnt lgkmcnt(0)
	v_add_f32_e32 v32, v32, v33
	v_mov_b32_e32 v25, v24
	v_mov_b32_e32 v27, v26
	v_mov_b32_e32 v29, v28
	v_mov_b32_e32 v31, v30
	v_mov_b32_e32 v33, v32
	v_permlane32_swap_b32_e32 v24, v25
	s_waitcnt vmcnt(0)
	v_fmamk_f32 v22, v199, 0x39800000, v246
	v_cmp_gt_f32_e32 vcc, s95, v22
	v_mul_f32_e32 v23, 0x4b800000, v22
	v_permlane32_swap_b32_e32 v26, v27
	v_cndmask_b32_e32 v22, v22, v23, vcc
	v_rsq_f32_e32 v22, v22
	v_permlane32_swap_b32_e32 v28, v29
	v_permlane32_swap_b32_e32 v30, v31
	v_mul_f32_e32 v23, 0x45800000, v22
	v_cndmask_b32_e32 v22, v22, v23, vcc
	v_pk_mul_f32 v[202:203], v[20:21], v[22:23] op_sel_hi:[1,0]
	v_pk_mul_f32 v[204:205], v[18:19], v[22:23] op_sel_hi:[1,0]
	v_pk_mul_f32 v[194:195], v[12:13], v[22:23] op_sel_hi:[1,0]
	v_pk_mul_f32 v[196:197], v[10:11], v[22:23] op_sel_hi:[1,0]
	v_pk_mul_f32 v[206:207], v[16:17], v[22:23] op_sel_hi:[1,0]
	v_pk_mul_f32 v[208:209], v[14:15], v[22:23] op_sel_hi:[1,0]
	v_pk_mul_f32 v[198:199], v[8:9], v[22:23] op_sel_hi:[1,0]
	v_pk_mul_f32 v[200:201], v[6:7], v[22:23] op_sel_hi:[1,0]
	v_mul_f32_e32 v6, v131, v131
	v_mul_f32_e32 v7, v133, v133
	v_mul_f32_e32 v8, v123, v123
	v_mul_f32_e32 v9, v125, v125
	v_mul_f32_e32 v10, v115, v115
	v_mul_f32_e32 v11, v117, v117
	v_mul_f32_e32 v12, v107, v107
	v_mul_f32_e32 v13, v109, v109
	v_mul_f32_e32 v14, v153, v153
	v_mul_f32_e32 v15, v101, v101
	v_mul_f32_e32 v16, v91, v91
	v_mul_f32_e32 v17, v93, v93
	v_mul_f32_e32 v18, v171, v171
	v_mul_f32_e32 v19, v167, v167
	v_mul_f32_e32 v20, v81, v81
	v_mul_f32_e32 v21, v79, v79
	v_mul_f32_e32 v22, v177, v177
	v_mul_f32_e32 v23, v77, v77
	v_mul_f32_e32 v34, v205, v205
	v_mul_f32_e32 v35, v203, v203
	v_mul_f32_e32 v36, v197, v197
	v_mul_f32_e32 v37, v195, v195
	v_fmac_f32_e32 v6, v130, v130
	v_fmac_f32_e32 v7, v132, v132
	v_fmac_f32_e32 v8, v122, v122
	v_fmac_f32_e32 v9, v124, v124
	v_fmac_f32_e32 v10, v114, v114
	v_fmac_f32_e32 v11, v116, v116
	v_fmac_f32_e32 v12, v106, v106
	v_fmac_f32_e32 v13, v108, v108
	v_fmac_f32_e32 v14, v152, v152
	v_fmac_f32_e32 v15, v100, v100
	v_fmac_f32_e32 v16, v90, v90
	v_fmac_f32_e32 v17, v92, v92
	v_fmac_f32_e32 v18, v170, v170
	v_fmac_f32_e32 v19, v166, v166
	v_fmac_f32_e32 v20, v80, v80
	v_fmac_f32_e32 v21, v78, v78
	v_fmac_f32_e32 v22, v176, v176
	v_fmac_f32_e32 v23, v76, v76
	v_fmac_f32_e32 v34, v204, v204
	v_fmac_f32_e32 v35, v202, v202
	v_fmac_f32_e32 v36, v196, v196
	v_fmac_f32_e32 v37, v194, v194
	v_add_f32_e32 v6, v6, v7
	v_mul_f32_e32 v7, v127, v127
	v_add_f32_e32 v8, v8, v9
	v_mul_f32_e32 v9, v119, v119
	v_add_f32_e32 v10, v10, v11
	v_mul_f32_e32 v11, v111, v111
	v_add_f32_e32 v12, v12, v13
	v_mul_f32_e32 v13, v103, v103
	v_add_f32_e32 v14, v14, v15
	v_mul_f32_e32 v15, v151, v151
	v_add_f32_e32 v16, v16, v17
	v_mul_f32_e32 v17, v87, v87
	v_add_f32_e32 v18, v18, v19
	v_mul_f32_e32 v19, v169, v169
	v_add_f32_e32 v20, v20, v21
	v_mul_f32_e32 v21, v71, v71
	v_add_f32_e32 v22, v22, v23
	v_mul_f32_e32 v23, v175, v175
	v_add_f32_e32 v34, v34, v35
	v_mul_f32_e32 v35, v209, v209
	v_add_f32_e32 v36, v36, v37
	v_mul_f32_e32 v37, v201, v201
	v_fmac_f32_e32 v7, v126, v126
	v_fmac_f32_e32 v9, v118, v118
	v_fmac_f32_e32 v11, v110, v110
	v_fmac_f32_e32 v13, v102, v102
	v_fmac_f32_e32 v15, v150, v150
	v_fmac_f32_e32 v17, v86, v86
	v_fmac_f32_e32 v19, v168, v168
	v_fmac_f32_e32 v21, v70, v70
	v_fmac_f32_e32 v23, v174, v174
	v_fmac_f32_e32 v35, v208, v208
	v_fmac_f32_e32 v37, v200, v200
	v_add_f32_e32 v6, v7, v6
	v_mul_f32_e32 v7, v129, v129
	v_add_f32_e32 v8, v9, v8
	v_mul_f32_e32 v9, v121, v121
	v_add_f32_e32 v10, v11, v10
	v_mul_f32_e32 v11, v113, v113
	v_add_f32_e32 v12, v13, v12
	v_mul_f32_e32 v13, v105, v105
	v_add_f32_e32 v14, v15, v14
	v_mul_f32_e32 v15, v97, v97
	v_add_f32_e32 v16, v17, v16
	v_mul_f32_e32 v17, v89, v89
	v_add_f32_e32 v18, v19, v18
	v_mul_f32_e32 v19, v165, v165
	v_add_f32_e32 v20, v21, v20
	v_mul_f32_e32 v21, v73, v73
	v_add_f32_e32 v22, v23, v22
	v_mul_f32_e32 v23, v75, v75
	v_add_f32_e32 v34, v35, v34
	v_mul_f32_e32 v35, v207, v207
	v_add_f32_e32 v36, v37, v36
	v_mul_f32_e32 v37, v199, v199
	v_fmac_f32_e32 v7, v128, v128
	v_fmac_f32_e32 v9, v120, v120
	v_fmac_f32_e32 v11, v112, v112
	v_fmac_f32_e32 v13, v104, v104
	v_fmac_f32_e32 v15, v96, v96
	v_fmac_f32_e32 v17, v88, v88
	v_fmac_f32_e32 v19, v164, v164
	v_fmac_f32_e32 v21, v72, v72
	v_fmac_f32_e32 v23, v74, v74
	v_fmac_f32_e32 v35, v206, v206
	v_fmac_f32_e32 v37, v198, v198
	v_add_f32_e32 v6, v7, v6
	v_add_f32_e32 v8, v9, v8
	v_add_f32_e32 v10, v11, v10
	v_add_f32_e32 v12, v13, v12
	v_add_f32_e32 v14, v15, v14
	v_add_f32_e32 v16, v17, v16
	v_add_f32_e32 v18, v19, v18
	v_add_f32_e32 v20, v21, v20
	v_add_f32_e32 v22, v23, v22
	v_add_f32_e32 v34, v35, v34
	v_add_f32_e32 v36, v37, v36
	ds_swizzle_b32 v7, v6 offset:swizzle(SWAP,16)
	ds_swizzle_b32 v9, v8 offset:swizzle(SWAP,16)
	ds_swizzle_b32 v11, v10 offset:swizzle(SWAP,16)
	ds_swizzle_b32 v13, v12 offset:swizzle(SWAP,16)
	ds_swizzle_b32 v15, v14 offset:swizzle(SWAP,16)
	ds_swizzle_b32 v17, v16 offset:swizzle(SWAP,16)
	ds_swizzle_b32 v19, v18 offset:swizzle(SWAP,16)
	ds_swizzle_b32 v21, v20 offset:swizzle(SWAP,16)
	ds_swizzle_b32 v23, v22 offset:swizzle(SWAP,16)
	ds_swizzle_b32 v35, v34 offset:swizzle(SWAP,16)
	ds_swizzle_b32 v37, v36 offset:swizzle(SWAP,16)
	s_waitcnt lgkmcnt(10)
	v_add_f32_e32 v6, v6, v7
	s_waitcnt lgkmcnt(9)
	v_add_f32_e32 v8, v8, v9
	s_waitcnt lgkmcnt(8)
	v_add_f32_e32 v10, v10, v11
	s_waitcnt lgkmcnt(7)
	v_add_f32_e32 v12, v12, v13
	s_waitcnt lgkmcnt(6)
	v_add_f32_e32 v14, v14, v15
	s_waitcnt lgkmcnt(5)
	v_add_f32_e32 v16, v16, v17
	s_waitcnt lgkmcnt(4)
	v_add_f32_e32 v18, v18, v19
	s_waitcnt lgkmcnt(3)
	v_add_f32_e32 v20, v20, v21
	s_waitcnt lgkmcnt(2)
	v_add_f32_e32 v22, v22, v23
	s_waitcnt lgkmcnt(1)
	v_add_f32_e32 v34, v34, v35
	s_waitcnt lgkmcnt(0)
	v_add_f32_e32 v36, v36, v37
	v_mov_b32_e32 v7, v6
	v_mov_b32_e32 v9, v8
	v_mov_b32_e32 v11, v10
	v_mov_b32_e32 v13, v12
	v_mov_b32_e32 v15, v14
	v_mov_b32_e32 v17, v16
	v_mov_b32_e32 v19, v18
	v_mov_b32_e32 v21, v20
	v_mov_b32_e32 v23, v22
	v_mov_b32_e32 v35, v34
	v_mov_b32_e32 v37, v36
	v_permlane32_swap_b32_e32 v6, v7
	v_permlane32_swap_b32_e32 v8, v9
	v_permlane32_swap_b32_e32 v10, v11
	v_permlane32_swap_b32_e32 v12, v13
	v_permlane32_swap_b32_e32 v14, v15
	v_permlane32_swap_b32_e32 v16, v17
	v_permlane32_swap_b32_e32 v18, v19
	v_permlane32_swap_b32_e32 v20, v21
	v_permlane32_swap_b32_e32 v22, v23
	v_permlane32_swap_b32_e32 v32, v33
	v_permlane32_swap_b32_e32 v34, v35
	v_permlane32_swap_b32_e32 v36, v37
	v_cmp_eq_u32_e32 vcc, 0, v210
	s_and_saveexec_b64 s[30:31], vcc
	s_cbranch_execz .LBB0_349
	s_and_b64 s[52:53], s[28:29], exec
	s_mov_b32 s1, 0x31000
	s_cselect_b32 s1, s1, 0x20800
	s_add_u32 s1, s24, s1
	s_addc_u32 s2, s25, 0
	s_add_u32 s52, s1, s6
	v_add_f32_e32 v8, v8, v9
	v_add_f32_e32 v9, v6, v7
	s_addc_u32 s53, s2, s7
	v_add_f32_e32 v12, v12, v13
	v_add_f32_e32 v10, v10, v11
	v_lshl_add_u64 v[6:7], v[140:141], 2, s[52:53]
	v_add_f32_e32 v8, v9, v8
	v_add_f32_e32 v16, v16, v17
	v_add_f32_e32 v14, v14, v15
	global_atomic_add_f32 v[6:7], v8, off
	v_add_f32_e32 v8, v10, v12
	v_add_f32_e32 v20, v20, v21
	v_add_f32_e32 v18, v18, v19
	global_atomic_add_f32 v[6:7], v8, off offset:64
	v_add_f32_e32 v8, v14, v16
	v_add_f32_e32 v24, v24, v25
	v_add_f32_e32 v22, v22, v23
	global_atomic_add_f32 v[6:7], v8, off offset:128
	v_add_f32_e32 v8, v18, v20
	v_add_f32_e32 v28, v28, v29
	v_add_f32_e32 v26, v26, v27
	global_atomic_add_f32 v[6:7], v8, off offset:192
	v_add_f32_e32 v8, v22, v24
	v_add_f32_e32 v32, v32, v33
	v_add_f32_e32 v30, v30, v31
	global_atomic_add_f32 v[6:7], v8, off offset:512
	v_add_f32_e32 v8, v26, v28
	v_add_f32_e32 v36, v36, v37
	v_add_f32_e32 v34, v34, v35
	global_atomic_add_f32 v[6:7], v8, off offset:576
	v_add_f32_e32 v8, v30, v32
	global_atomic_add_f32 v[6:7], v8, off offset:640
	v_add_f32_e32 v8, v34, v36
	global_atomic_add_f32 v[6:7], v8, off offset:704

.LBB0_454:
	s_add_u32 s66, s62, 0xffffff80
	s_addc_u32 s67, s63, -1
	s_cmp_eq_u32 s64, 12
	s_cselect_b32 s38, s21, s62
	s_cselect_b32 s39, s3, s63
	s_cselect_b32 s41, s23, s61
	s_cselect_b32 s40, s31, s33
	s_add_u32 s34, s38, 0x80
	s_addc_u32 s35, s39, 0
	s_add_u32 s36, s40, 0x80
	s_addc_u32 s37, s41, 0
	s_add_i32 s65, 0, 0x10000
	s_add_i32 s68, 0, 0x14000
	v_add_u32_e32 v152, s65, v1
	v_add_u32_e32 v168, s68, v1
	ds_read_b128 v[140:143], v152
	ds_read_b128 v[144:147], v152 offset:1024
	ds_read_b128 v[148:151], v152 offset:2048
	ds_read_b128 v[152:155], v152 offset:3072
	ds_read_b128 v[156:159], v168
	ds_read_b128 v[160:163], v168 offset:1024
	ds_read_b128 v[164:167], v168 offset:2048
	ds_read_b128 v[168:171], v168 offset:3072
	s_add_u32 s66, s66, 0x40000
	s_addc_u32 s67, s67, 0
	v_lshl_add_u64 v[204:205], s[66:67], 0, v[2:3]
	s_add_i32 m0, s29, 0xc000
	ds_read_b128 v[172:175], v5
	ds_read_b128 v[176:179], v5 offset:1024
	ds_read_b128 v[180:183], v5 offset:2048
	ds_read_b128 v[184:187], v5 offset:3072
	ds_read_b128 v[188:191], v5 offset:4096
	ds_read_b128 v[192:195], v5 offset:5120
	ds_read_b128 v[196:199], v5 offset:6144
	ds_read_b128 v[200:203], v5 offset:7168
	global_load_lds_dwordx4 v[204:205], off
	v_lshl_add_u64 v[204:205], s[66:67], 0, v[136:137]
	s_add_i32 m0, s29, 0xe000
	s_nop 0
	global_load_lds_dwordx4 v[204:205], off
	s_waitcnt vmcnt(8)
	s_waitcnt lgkmcnt(0)
	s_barrier
	s_setprio 1
	v_mfma_f32_16x16x32_bf16 v[130:133], v[140:143], v[172:175], v[130:133]
	v_mfma_f32_16x16x32_bf16 v[126:129], v[148:151], v[172:175], v[126:129]
	v_mfma_f32_16x16x32_bf16 v[114:117], v[140:143], v[180:183], v[114:117]
	v_mfma_f32_16x16x32_bf16 v[110:113], v[148:151], v[180:183], v[110:113]
	v_mfma_f32_16x16x32_bf16 v[98:101], v[140:143], v[188:191], v[98:101]
	v_mfma_f32_16x16x32_bf16 v[94:97], v[148:151], v[188:191], v[94:97]
	v_mfma_f32_16x16x32_bf16 v[82:85], v[140:143], v[196:199], v[82:85]
	v_mfma_f32_16x16x32_bf16 v[78:81], v[148:151], v[196:199], v[78:81]
	v_mfma_f32_16x16x32_bf16 v[130:133], v[144:147], v[176:179], v[130:133]
	v_mfma_f32_16x16x32_bf16 v[126:129], v[152:155], v[176:179], v[126:129]
	v_mfma_f32_16x16x32_bf16 v[114:117], v[144:147], v[184:187], v[114:117]
	v_mfma_f32_16x16x32_bf16 v[110:113], v[152:155], v[184:187], v[110:113]
	v_mfma_f32_16x16x32_bf16 v[98:101], v[144:147], v[192:195], v[98:101]
	v_mfma_f32_16x16x32_bf16 v[94:97], v[152:155], v[192:195], v[94:97]
	v_mfma_f32_16x16x32_bf16 v[82:85], v[144:147], v[200:203], v[82:85]
	v_mfma_f32_16x16x32_bf16 v[78:81], v[152:155], v[200:203], v[78:81]
	v_mfma_f32_16x16x32_bf16 v[122:125], v[156:159], v[172:175], v[122:125]
	v_mfma_f32_16x16x32_bf16 v[118:121], v[164:167], v[172:175], v[118:121]
	v_mfma_f32_16x16x32_bf16 v[106:109], v[156:159], v[180:183], v[106:109]
	v_mfma_f32_16x16x32_bf16 v[102:105], v[164:167], v[180:183], v[102:105]
	v_mfma_f32_16x16x32_bf16 v[90:93], v[156:159], v[188:191], v[90:93]
	v_mfma_f32_16x16x32_bf16 v[86:89], v[164:167], v[188:191], v[86:89]
	v_mfma_f32_16x16x32_bf16 v[74:77], v[156:159], v[196:199], v[74:77]
	v_mfma_f32_16x16x32_bf16 v[70:73], v[164:167], v[196:199], v[70:73]
	v_mfma_f32_16x16x32_bf16 v[122:125], v[160:163], v[176:179], v[122:125]
	v_mfma_f32_16x16x32_bf16 v[118:121], v[168:171], v[176:179], v[118:121]
	v_mfma_f32_16x16x32_bf16 v[106:109], v[160:163], v[184:187], v[106:109]
	v_mfma_f32_16x16x32_bf16 v[102:105], v[168:171], v[184:187], v[102:105]
	v_mfma_f32_16x16x32_bf16 v[90:93], v[160:163], v[192:195], v[90:93]
	v_mfma_f32_16x16x32_bf16 v[86:89], v[168:171], v[192:195], v[86:89]
	v_mfma_f32_16x16x32_bf16 v[74:77], v[160:163], v[200:203], v[74:77]
	v_mfma_f32_16x16x32_bf16 v[70:73], v[168:171], v[200:203], v[70:73]
	s_setprio 0
	s_barrier
	s_add_i32 s65, s65, s46
	v_lshl_add_u64 v[204:205], s[40:41], 0, v[134:135]
	s_mov_b32 m0, s65
	ds_read_b128 v[172:175], v5 offset:16384
	ds_read_b128 v[176:179], v5 offset:17408
	ds_read_b128 v[180:183], v5 offset:18432
	ds_read_b128 v[184:187], v5 offset:19456
	ds_read_b128 v[188:191], v5 offset:20480
	ds_read_b128 v[192:195], v5 offset:21504
	ds_read_b128 v[196:199], v5 offset:22528
	ds_read_b128 v[200:203], v5 offset:23552
	global_load_lds_dwordx4 v[204:205], off
	s_add_i32 m0, s65, 0x2000
	v_lshl_add_u64 v[204:205], s[40:41], 0, v[138:139]
	s_add_u32 s40, s40, 0x40000
	s_addc_u32 s41, s41, 0
	s_add_i32 s65, s68, s46
	global_load_lds_dwordx4 v[204:205], off
	v_lshl_add_u64 v[204:205], s[40:41], 0, v[134:135]
	s_mov_b32 m0, s65
	s_nop 0
	global_load_lds_dwordx4 v[204:205], off
	v_lshl_add_u64 v[204:205], s[40:41], 0, v[138:139]
	s_add_i32 m0, s65, 0x2000
	s_nop 0
	global_load_lds_dwordx4 v[204:205], off
	v_lshl_add_u64 v[204:205], s[38:39], 0, v[2:3]
	s_mov_b32 m0, s29
	s_nop 0
	global_load_lds_dwordx4 v[204:205], off
	v_lshl_add_u64 v[204:205], s[38:39], 0, v[136:137]
	s_mov_b32 m0, s51
	s_nop 0
	global_load_lds_dwordx4 v[204:205], off
	s_waitcnt vmcnt(8)
	s_waitcnt lgkmcnt(0)
	s_barrier
	s_setprio 1
	v_mfma_f32_16x16x32_bf16 v[66:69], v[140:143], v[172:175], v[66:69]
	v_mfma_f32_16x16x32_bf16 v[62:65], v[148:151], v[172:175], v[62:65]
	v_mfma_f32_16x16x32_bf16 v[50:53], v[140:143], v[180:183], v[50:53]
	v_mfma_f32_16x16x32_bf16 v[46:49], v[148:151], v[180:183], v[46:49]
	v_mfma_f32_16x16x32_bf16 v[34:37], v[140:143], v[188:191], v[34:37]
	v_mfma_f32_16x16x32_bf16 v[30:33], v[148:151], v[188:191], v[30:33]
	v_mfma_f32_16x16x32_bf16 v[18:21], v[140:143], v[196:199], v[18:21]
	v_mfma_f32_16x16x32_bf16 v[14:17], v[148:151], v[196:199], v[14:17]
	v_mfma_f32_16x16x32_bf16 v[66:69], v[144:147], v[176:179], v[66:69]
	v_mfma_f32_16x16x32_bf16 v[62:65], v[152:155], v[176:179], v[62:65]
	v_mfma_f32_16x16x32_bf16 v[50:53], v[144:147], v[184:187], v[50:53]
	v_mfma_f32_16x16x32_bf16 v[46:49], v[152:155], v[184:187], v[46:49]
	v_mfma_f32_16x16x32_bf16 v[34:37], v[144:147], v[192:195], v[34:37]
	v_mfma_f32_16x16x32_bf16 v[30:33], v[152:155], v[192:195], v[30:33]
	v_mfma_f32_16x16x32_bf16 v[18:21], v[144:147], v[200:203], v[18:21]
	v_mfma_f32_16x16x32_bf16 v[14:17], v[152:155], v[200:203], v[14:17]
	v_mfma_f32_16x16x32_bf16 v[58:61], v[156:159], v[172:175], v[58:61]
	v_mfma_f32_16x16x32_bf16 v[54:57], v[164:167], v[172:175], v[54:57]
	v_mfma_f32_16x16x32_bf16 v[42:45], v[156:159], v[180:183], v[42:45]
	v_mfma_f32_16x16x32_bf16 v[38:41], v[164:167], v[180:183], v[38:41]
	v_mfma_f32_16x16x32_bf16 v[26:29], v[156:159], v[188:191], v[26:29]
	v_mfma_f32_16x16x32_bf16 v[22:25], v[164:167], v[188:191], v[22:25]
	v_mfma_f32_16x16x32_bf16 v[10:13], v[156:159], v[196:199], v[10:13]
	v_mfma_f32_16x16x32_bf16 v[6:9], v[164:167], v[196:199], v[6:9]
	v_mfma_f32_16x16x32_bf16 v[58:61], v[160:163], v[176:179], v[58:61]
	v_mfma_f32_16x16x32_bf16 v[54:57], v[168:171], v[176:179], v[54:57]
	v_mfma_f32_16x16x32_bf16 v[42:45], v[160:163], v[184:187], v[42:45]
	v_mfma_f32_16x16x32_bf16 v[38:41], v[168:171], v[184:187], v[38:41]
	v_mfma_f32_16x16x32_bf16 v[26:29], v[160:163], v[192:195], v[26:29]
	v_mfma_f32_16x16x32_bf16 v[22:25], v[168:171], v[192:195], v[22:25]
	v_mfma_f32_16x16x32_bf16 v[10:13], v[160:163], v[200:203], v[10:13]
	v_mfma_f32_16x16x32_bf16 v[6:9], v[168:171], v[200:203], v[6:9]
	s_setprio 0
	s_barrier
	s_add_i32 s40, 0, 0x18000
	s_add_i32 s41, 0, 0x1c000
	v_add_u32_e32 v152, s40, v1
	v_add_u32_e32 v168, s41, v1
	ds_read_b128 v[140:143], v152
	ds_read_b128 v[144:147], v152 offset:1024
	ds_read_b128 v[148:151], v152 offset:2048
	ds_read_b128 v[152:155], v152 offset:3072
	ds_read_b128 v[156:159], v168
	ds_read_b128 v[160:163], v168 offset:1024
	ds_read_b128 v[164:167], v168 offset:2048
	ds_read_b128 v[168:171], v168 offset:3072
	s_add_u32 s38, s38, 0x40000
	s_addc_u32 s39, s39, 0
	s_mov_b32 m0, s52
	v_lshl_add_u64 v[204:205], s[38:39], 0, v[2:3]
	ds_read_b128 v[172:175], v5 offset:32768
	ds_read_b128 v[176:179], v5 offset:33792
	ds_read_b128 v[180:183], v5 offset:34816
	ds_read_b128 v[184:187], v5 offset:35840
	ds_read_b128 v[188:191], v5 offset:36864
	ds_read_b128 v[192:195], v5 offset:37888
	ds_read_b128 v[196:199], v5 offset:38912
	ds_read_b128 v[200:203], v5 offset:39936
	global_load_lds_dwordx4 v[204:205], off
	v_lshl_add_u64 v[204:205], s[38:39], 0, v[136:137]
	s_mov_b32 m0, s53
	s_nop 0
	global_load_lds_dwordx4 v[204:205], off
	s_waitcnt vmcnt(8)
	s_waitcnt lgkmcnt(0)
	s_barrier
	s_setprio 1
	v_mfma_f32_16x16x32_bf16 v[130:133], v[140:143], v[172:175], v[130:133]
	v_mfma_f32_16x16x32_bf16 v[126:129], v[148:151], v[172:175], v[126:129]
	v_mfma_f32_16x16x32_bf16 v[114:117], v[140:143], v[180:183], v[114:117]
	v_mfma_f32_16x16x32_bf16 v[110:113], v[148:151], v[180:183], v[110:113]
	v_mfma_f32_16x16x32_bf16 v[98:101], v[140:143], v[188:191], v[98:101]
	v_mfma_f32_16x16x32_bf16 v[94:97], v[148:151], v[188:191], v[94:97]
	v_mfma_f32_16x16x32_bf16 v[82:85], v[140:143], v[196:199], v[82:85]
	v_mfma_f32_16x16x32_bf16 v[78:81], v[148:151], v[196:199], v[78:81]
	v_mfma_f32_16x16x32_bf16 v[130:133], v[144:147], v[176:179], v[130:133]
	v_mfma_f32_16x16x32_bf16 v[126:129], v[152:155], v[176:179], v[126:129]
	v_mfma_f32_16x16x32_bf16 v[114:117], v[144:147], v[184:187], v[114:117]
	v_mfma_f32_16x16x32_bf16 v[110:113], v[152:155], v[184:187], v[110:113]
	v_mfma_f32_16x16x32_bf16 v[98:101], v[144:147], v[192:195], v[98:101]
	v_mfma_f32_16x16x32_bf16 v[94:97], v[152:155], v[192:195], v[94:97]
	v_mfma_f32_16x16x32_bf16 v[82:85], v[144:147], v[200:203], v[82:85]
	v_mfma_f32_16x16x32_bf16 v[78:81], v[152:155], v[200:203], v[78:81]
	v_mfma_f32_16x16x32_bf16 v[122:125], v[156:159], v[172:175], v[122:125]
	v_mfma_f32_16x16x32_bf16 v[118:121], v[164:167], v[172:175], v[118:121]
	v_mfma_f32_16x16x32_bf16 v[106:109], v[156:159], v[180:183], v[106:109]
	v_mfma_f32_16x16x32_bf16 v[102:105], v[164:167], v[180:183], v[102:105]
	v_mfma_f32_16x16x32_bf16 v[90:93], v[156:159], v[188:191], v[90:93]
	v_mfma_f32_16x16x32_bf16 v[86:89], v[164:167], v[188:191], v[86:89]
	v_mfma_f32_16x16x32_bf16 v[74:77], v[156:159], v[196:199], v[74:77]
	v_mfma_f32_16x16x32_bf16 v[70:73], v[164:167], v[196:199], v[70:73]
	v_mfma_f32_16x16x32_bf16 v[122:125], v[160:163], v[176:179], v[122:125]
	v_mfma_f32_16x16x32_bf16 v[118:121], v[168:171], v[176:179], v[118:121]
	v_mfma_f32_16x16x32_bf16 v[106:109], v[160:163], v[184:187], v[106:109]
	v_mfma_f32_16x16x32_bf16 v[102:105], v[168:171], v[184:187], v[102:105]
	v_mfma_f32_16x16x32_bf16 v[90:93], v[160:163], v[192:195], v[90:93]
	v_mfma_f32_16x16x32_bf16 v[86:89], v[168:171], v[192:195], v[86:89]
	v_mfma_f32_16x16x32_bf16 v[74:77], v[160:163], v[200:203], v[74:77]
	v_mfma_f32_16x16x32_bf16 v[70:73], v[168:171], v[200:203], v[70:73]
	s_setprio 0
	s_barrier
	s_add_i32 s38, s40, s46
	v_lshl_add_u64 v[204:205], s[36:37], 0, v[134:135]
	s_mov_b32 m0, s38
	ds_read_b128 v[172:175], v5 offset:49152
	ds_read_b128 v[176:179], v5 offset:50176
	ds_read_b128 v[180:183], v5 offset:51200
	ds_read_b128 v[184:187], v5 offset:52224
	ds_read_b128 v[188:191], v5 offset:53248
	ds_read_b128 v[192:195], v5 offset:54272
	ds_read_b128 v[196:199], v5 offset:55296
	ds_read_b128 v[200:203], v5 offset:56320
	global_load_lds_dwordx4 v[204:205], off
	s_add_i32 m0, s38, 0x2000
	v_lshl_add_u64 v[204:205], s[36:37], 0, v[138:139]
	s_add_u32 s36, s36, 0x40000
	s_addc_u32 s37, s37, 0
	s_add_i32 s38, s41, s46
	global_load_lds_dwordx4 v[204:205], off
	v_lshl_add_u64 v[204:205], s[36:37], 0, v[134:135]
	s_mov_b32 m0, s38
	s_nop 0
	global_load_lds_dwordx4 v[204:205], off
	v_lshl_add_u64 v[204:205], s[36:37], 0, v[138:139]
	s_add_i32 m0, s38, 0x2000
	s_nop 0
	global_load_lds_dwordx4 v[204:205], off
	v_lshl_add_u64 v[204:205], s[34:35], 0, v[2:3]
	s_mov_b32 m0, s56
	s_nop 0
	global_load_lds_dwordx4 v[204:205], off
	v_lshl_add_u64 v[204:205], s[34:35], 0, v[136:137]
	s_mov_b32 m0, s57
	s_nop 0
	global_load_lds_dwordx4 v[204:205], off
	s_waitcnt vmcnt(8)
	s_waitcnt lgkmcnt(0)
	s_barrier
	s_setprio 1
	v_mfma_f32_16x16x32_bf16 v[66:69], v[140:143], v[172:175], v[66:69]
	v_mfma_f32_16x16x32_bf16 v[62:65], v[148:151], v[172:175], v[62:65]
	v_mfma_f32_16x16x32_bf16 v[50:53], v[140:143], v[180:183], v[50:53]
	v_mfma_f32_16x16x32_bf16 v[46:49], v[148:151], v[180:183], v[46:49]
	v_mfma_f32_16x16x32_bf16 v[34:37], v[140:143], v[188:191], v[34:37]
	v_mfma_f32_16x16x32_bf16 v[30:33], v[148:151], v[188:191], v[30:33]
	v_mfma_f32_16x16x32_bf16 v[18:21], v[140:143], v[196:199], v[18:21]
	v_mfma_f32_16x16x32_bf16 v[14:17], v[148:151], v[196:199], v[14:17]
	v_mfma_f32_16x16x32_bf16 v[66:69], v[144:147], v[176:179], v[66:69]
	v_mfma_f32_16x16x32_bf16 v[62:65], v[152:155], v[176:179], v[62:65]
	v_mfma_f32_16x16x32_bf16 v[50:53], v[144:147], v[184:187], v[50:53]
	v_mfma_f32_16x16x32_bf16 v[46:49], v[152:155], v[184:187], v[46:49]
	v_mfma_f32_16x16x32_bf16 v[34:37], v[144:147], v[192:195], v[34:37]
	v_mfma_f32_16x16x32_bf16 v[30:33], v[152:155], v[192:195], v[30:33]
	v_mfma_f32_16x16x32_bf16 v[18:21], v[144:147], v[200:203], v[18:21]
	v_mfma_f32_16x16x32_bf16 v[14:17], v[152:155], v[200:203], v[14:17]
	v_mfma_f32_16x16x32_bf16 v[58:61], v[156:159], v[172:175], v[58:61]
	v_mfma_f32_16x16x32_bf16 v[54:57], v[164:167], v[172:175], v[54:57]
	v_mfma_f32_16x16x32_bf16 v[42:45], v[156:159], v[180:183], v[42:45]
	v_mfma_f32_16x16x32_bf16 v[38:41], v[164:167], v[180:183], v[38:41]
	v_mfma_f32_16x16x32_bf16 v[26:29], v[156:159], v[188:191], v[26:29]
	v_mfma_f32_16x16x32_bf16 v[22:25], v[164:167], v[188:191], v[22:25]
	v_mfma_f32_16x16x32_bf16 v[10:13], v[156:159], v[196:199], v[10:13]
	v_mfma_f32_16x16x32_bf16 v[6:9], v[164:167], v[196:199], v[6:9]
	v_mfma_f32_16x16x32_bf16 v[58:61], v[160:163], v[176:179], v[58:61]
	v_mfma_f32_16x16x32_bf16 v[54:57], v[168:171], v[176:179], v[54:57]
	v_mfma_f32_16x16x32_bf16 v[42:45], v[160:163], v[184:187], v[42:45]
	v_mfma_f32_16x16x32_bf16 v[38:41], v[168:171], v[184:187], v[38:41]
	v_mfma_f32_16x16x32_bf16 v[26:29], v[160:163], v[192:195], v[26:29]
	v_mfma_f32_16x16x32_bf16 v[22:25], v[168:171], v[192:195], v[22:25]
	v_mfma_f32_16x16x32_bf16 v[10:13], v[160:163], v[200:203], v[10:13]
	v_mfma_f32_16x16x32_bf16 v[6:9], v[168:171], v[200:203], v[6:9]
	s_setprio 0
	s_barrier
	s_add_i32 s64, s64, 2
	s_add_u32 s33, s33, 0x100
	s_addc_u32 s61, s61, 0
	s_add_u32 s62, s62, 0x100
	s_addc_u32 s63, s63, 0
	s_cmp_gt_u32 s64, 13
	s_cbranch_scc0 .LBB0_454
	s_and_b64 vcc, exec, s[8:9]
	s_cbranch_vccz .LBB0_457
	s_barrier

.LBB0_480:
	s_add_u32 s58, s54, 0xffffff80
	s_addc_u32 s59, s55, -1
	s_cmp_eq_u32 s56, 4
	s_cselect_b32 s30, s25, s54
	s_cselect_b32 s31, s15, s55
	s_cselect_b32 s35, s17, s53
	s_cselect_b32 s34, s33, s52
	s_add_u32 s26, s30, 0x80
	s_addc_u32 s27, s31, 0
	s_add_u32 s28, s34, 0x80
	s_addc_u32 s29, s35, 0
	s_add_i32 s57, 0, 0x10000
	s_add_i32 s60, 0, 0x14000
	v_add_u32_e32 v152, s57, v1
	v_add_u32_e32 v168, s60, v1
	ds_read_b128 v[140:143], v152
	ds_read_b128 v[144:147], v152 offset:1024
	ds_read_b128 v[148:151], v152 offset:2048
	ds_read_b128 v[152:155], v152 offset:3072
	ds_read_b128 v[156:159], v168
	ds_read_b128 v[160:163], v168 offset:1024
	ds_read_b128 v[164:167], v168 offset:2048
	ds_read_b128 v[168:171], v168 offset:3072
	s_add_u32 s58, s58, 0x20000
	s_addc_u32 s59, s59, 0
	v_lshl_add_u64 v[204:205], s[58:59], 0, v[2:3]
	s_add_i32 m0, s43, 0xc000
	ds_read_b128 v[172:175], v5
	ds_read_b128 v[176:179], v5 offset:1024
	ds_read_b128 v[180:183], v5 offset:2048
	ds_read_b128 v[184:187], v5 offset:3072
	ds_read_b128 v[188:191], v5 offset:4096
	ds_read_b128 v[192:195], v5 offset:5120
	ds_read_b128 v[196:199], v5 offset:6144
	ds_read_b128 v[200:203], v5 offset:7168
	global_load_lds_dwordx4 v[204:205], off
	v_lshl_add_u64 v[204:205], s[58:59], 0, v[136:137]
	s_add_i32 m0, s43, 0xe000
	s_nop 0
	global_load_lds_dwordx4 v[204:205], off
	s_waitcnt vmcnt(8)
	s_waitcnt lgkmcnt(0)
	s_barrier
	s_setprio 1
	v_mfma_f32_16x16x32_bf16 v[130:133], v[140:143], v[172:175], v[130:133]
	v_mfma_f32_16x16x32_bf16 v[126:129], v[148:151], v[172:175], v[126:129]
	v_mfma_f32_16x16x32_bf16 v[114:117], v[140:143], v[180:183], v[114:117]
	v_mfma_f32_16x16x32_bf16 v[110:113], v[148:151], v[180:183], v[110:113]
	v_mfma_f32_16x16x32_bf16 v[98:101], v[140:143], v[188:191], v[98:101]
	v_mfma_f32_16x16x32_bf16 v[94:97], v[148:151], v[188:191], v[94:97]
	v_mfma_f32_16x16x32_bf16 v[82:85], v[140:143], v[196:199], v[82:85]
	v_mfma_f32_16x16x32_bf16 v[78:81], v[148:151], v[196:199], v[78:81]
	v_mfma_f32_16x16x32_bf16 v[130:133], v[144:147], v[176:179], v[130:133]
	v_mfma_f32_16x16x32_bf16 v[126:129], v[152:155], v[176:179], v[126:129]
	v_mfma_f32_16x16x32_bf16 v[114:117], v[144:147], v[184:187], v[114:117]
	v_mfma_f32_16x16x32_bf16 v[110:113], v[152:155], v[184:187], v[110:113]
	v_mfma_f32_16x16x32_bf16 v[98:101], v[144:147], v[192:195], v[98:101]
	v_mfma_f32_16x16x32_bf16 v[94:97], v[152:155], v[192:195], v[94:97]
	v_mfma_f32_16x16x32_bf16 v[82:85], v[144:147], v[200:203], v[82:85]
	v_mfma_f32_16x16x32_bf16 v[78:81], v[152:155], v[200:203], v[78:81]
	v_mfma_f32_16x16x32_bf16 v[122:125], v[156:159], v[172:175], v[122:125]
	v_mfma_f32_16x16x32_bf16 v[118:121], v[164:167], v[172:175], v[118:121]
	v_mfma_f32_16x16x32_bf16 v[106:109], v[156:159], v[180:183], v[106:109]
	v_mfma_f32_16x16x32_bf16 v[102:105], v[164:167], v[180:183], v[102:105]
	v_mfma_f32_16x16x32_bf16 v[90:93], v[156:159], v[188:191], v[90:93]
	v_mfma_f32_16x16x32_bf16 v[86:89], v[164:167], v[188:191], v[86:89]
	v_mfma_f32_16x16x32_bf16 v[74:77], v[156:159], v[196:199], v[74:77]
	v_mfma_f32_16x16x32_bf16 v[70:73], v[164:167], v[196:199], v[70:73]
	v_mfma_f32_16x16x32_bf16 v[122:125], v[160:163], v[176:179], v[122:125]
	v_mfma_f32_16x16x32_bf16 v[118:121], v[168:171], v[176:179], v[118:121]
	v_mfma_f32_16x16x32_bf16 v[106:109], v[160:163], v[184:187], v[106:109]
	v_mfma_f32_16x16x32_bf16 v[102:105], v[168:171], v[184:187], v[102:105]
	v_mfma_f32_16x16x32_bf16 v[90:93], v[160:163], v[192:195], v[90:93]
	v_mfma_f32_16x16x32_bf16 v[86:89], v[168:171], v[192:195], v[86:89]
	v_mfma_f32_16x16x32_bf16 v[74:77], v[160:163], v[200:203], v[74:77]
	v_mfma_f32_16x16x32_bf16 v[70:73], v[168:171], v[200:203], v[70:73]
	s_setprio 0
	s_barrier
	s_add_i32 s57, s57, s42
	v_lshl_add_u64 v[204:205], s[34:35], 0, v[134:135]
	s_mov_b32 m0, s57
	ds_read_b128 v[172:175], v5 offset:16384
	ds_read_b128 v[176:179], v5 offset:17408
	ds_read_b128 v[180:183], v5 offset:18432
	ds_read_b128 v[184:187], v5 offset:19456
	ds_read_b128 v[188:191], v5 offset:20480
	ds_read_b128 v[192:195], v5 offset:21504
	ds_read_b128 v[196:199], v5 offset:22528
	ds_read_b128 v[200:203], v5 offset:23552
	global_load_lds_dwordx4 v[204:205], off
	s_add_i32 m0, s57, 0x2000
	v_lshl_add_u64 v[204:205], s[34:35], 0, v[138:139]
	s_add_u32 s34, s34, 0x20000
	s_addc_u32 s35, s35, 0
	s_add_i32 s57, s60, s42
	global_load_lds_dwordx4 v[204:205], off
	v_lshl_add_u64 v[204:205], s[34:35], 0, v[134:135]
	s_mov_b32 m0, s57
	s_nop 0
	global_load_lds_dwordx4 v[204:205], off
	v_lshl_add_u64 v[204:205], s[34:35], 0, v[138:139]
	s_add_i32 m0, s57, 0x2000
	s_nop 0
	global_load_lds_dwordx4 v[204:205], off
	v_lshl_add_u64 v[204:205], s[30:31], 0, v[2:3]
	s_mov_b32 m0, s43
	s_nop 0
	global_load_lds_dwordx4 v[204:205], off
	v_lshl_add_u64 v[204:205], s[30:31], 0, v[136:137]
	s_mov_b32 m0, s44
	s_nop 0
	global_load_lds_dwordx4 v[204:205], off
	s_waitcnt vmcnt(8)
	s_waitcnt lgkmcnt(0)
	s_barrier
	s_setprio 1
	v_mfma_f32_16x16x32_bf16 v[66:69], v[140:143], v[172:175], v[66:69]
	v_mfma_f32_16x16x32_bf16 v[62:65], v[148:151], v[172:175], v[62:65]
	v_mfma_f32_16x16x32_bf16 v[50:53], v[140:143], v[180:183], v[50:53]
	v_mfma_f32_16x16x32_bf16 v[46:49], v[148:151], v[180:183], v[46:49]
	v_mfma_f32_16x16x32_bf16 v[34:37], v[140:143], v[188:191], v[34:37]
	v_mfma_f32_16x16x32_bf16 v[30:33], v[148:151], v[188:191], v[30:33]
	v_mfma_f32_16x16x32_bf16 v[18:21], v[140:143], v[196:199], v[18:21]
	v_mfma_f32_16x16x32_bf16 v[14:17], v[148:151], v[196:199], v[14:17]
	v_mfma_f32_16x16x32_bf16 v[66:69], v[144:147], v[176:179], v[66:69]
	v_mfma_f32_16x16x32_bf16 v[62:65], v[152:155], v[176:179], v[62:65]
	v_mfma_f32_16x16x32_bf16 v[50:53], v[144:147], v[184:187], v[50:53]
	v_mfma_f32_16x16x32_bf16 v[46:49], v[152:155], v[184:187], v[46:49]
	v_mfma_f32_16x16x32_bf16 v[34:37], v[144:147], v[192:195], v[34:37]
	v_mfma_f32_16x16x32_bf16 v[30:33], v[152:155], v[192:195], v[30:33]
	v_mfma_f32_16x16x32_bf16 v[18:21], v[144:147], v[200:203], v[18:21]
	v_mfma_f32_16x16x32_bf16 v[14:17], v[152:155], v[200:203], v[14:17]
	v_mfma_f32_16x16x32_bf16 v[58:61], v[156:159], v[172:175], v[58:61]
	v_mfma_f32_16x16x32_bf16 v[54:57], v[164:167], v[172:175], v[54:57]
	v_mfma_f32_16x16x32_bf16 v[42:45], v[156:159], v[180:183], v[42:45]
	v_mfma_f32_16x16x32_bf16 v[38:41], v[164:167], v[180:183], v[38:41]
	v_mfma_f32_16x16x32_bf16 v[26:29], v[156:159], v[188:191], v[26:29]
	v_mfma_f32_16x16x32_bf16 v[22:25], v[164:167], v[188:191], v[22:25]
	v_mfma_f32_16x16x32_bf16 v[10:13], v[156:159], v[196:199], v[10:13]
	v_mfma_f32_16x16x32_bf16 v[6:9], v[164:167], v[196:199], v[6:9]
	v_mfma_f32_16x16x32_bf16 v[58:61], v[160:163], v[176:179], v[58:61]
	v_mfma_f32_16x16x32_bf16 v[54:57], v[168:171], v[176:179], v[54:57]
	v_mfma_f32_16x16x32_bf16 v[42:45], v[160:163], v[184:187], v[42:45]
	v_mfma_f32_16x16x32_bf16 v[38:41], v[168:171], v[184:187], v[38:41]
	v_mfma_f32_16x16x32_bf16 v[26:29], v[160:163], v[192:195], v[26:29]
	v_mfma_f32_16x16x32_bf16 v[22:25], v[168:171], v[192:195], v[22:25]
	v_mfma_f32_16x16x32_bf16 v[10:13], v[160:163], v[200:203], v[10:13]
	v_mfma_f32_16x16x32_bf16 v[6:9], v[168:171], v[200:203], v[6:9]
	s_setprio 0
	s_barrier
	s_add_i32 s34, 0, 0x18000
	s_add_i32 s35, 0, 0x1c000
	v_add_u32_e32 v152, s34, v1
	v_add_u32_e32 v168, s35, v1
	ds_read_b128 v[140:143], v152
	ds_read_b128 v[144:147], v152 offset:1024
	ds_read_b128 v[148:151], v152 offset:2048
	ds_read_b128 v[152:155], v152 offset:3072
	ds_read_b128 v[156:159], v168
	ds_read_b128 v[160:163], v168 offset:1024
	ds_read_b128 v[164:167], v168 offset:2048
	ds_read_b128 v[168:171], v168 offset:3072
	s_add_u32 s30, s30, 0x20000
	s_addc_u32 s31, s31, 0
	s_mov_b32 m0, s45
	v_lshl_add_u64 v[204:205], s[30:31], 0, v[2:3]
	ds_read_b128 v[172:175], v5 offset:32768
	ds_read_b128 v[176:179], v5 offset:33792
	ds_read_b128 v[180:183], v5 offset:34816
	ds_read_b128 v[184:187], v5 offset:35840
	ds_read_b128 v[188:191], v5 offset:36864
	ds_read_b128 v[192:195], v5 offset:37888
	ds_read_b128 v[196:199], v5 offset:38912
	ds_read_b128 v[200:203], v5 offset:39936
	global_load_lds_dwordx4 v[204:205], off
	v_lshl_add_u64 v[204:205], s[30:31], 0, v[136:137]
	s_mov_b32 m0, s46
	s_nop 0
	global_load_lds_dwordx4 v[204:205], off
	s_waitcnt vmcnt(8)
	s_waitcnt lgkmcnt(0)
	s_barrier
	s_setprio 1
	v_mfma_f32_16x16x32_bf16 v[130:133], v[140:143], v[172:175], v[130:133]
	v_mfma_f32_16x16x32_bf16 v[126:129], v[148:151], v[172:175], v[126:129]
	v_mfma_f32_16x16x32_bf16 v[114:117], v[140:143], v[180:183], v[114:117]
	v_mfma_f32_16x16x32_bf16 v[110:113], v[148:151], v[180:183], v[110:113]
	v_mfma_f32_16x16x32_bf16 v[98:101], v[140:143], v[188:191], v[98:101]
	v_mfma_f32_16x16x32_bf16 v[94:97], v[148:151], v[188:191], v[94:97]
	v_mfma_f32_16x16x32_bf16 v[82:85], v[140:143], v[196:199], v[82:85]
	v_mfma_f32_16x16x32_bf16 v[78:81], v[148:151], v[196:199], v[78:81]
	v_mfma_f32_16x16x32_bf16 v[130:133], v[144:147], v[176:179], v[130:133]
	v_mfma_f32_16x16x32_bf16 v[126:129], v[152:155], v[176:179], v[126:129]
	v_mfma_f32_16x16x32_bf16 v[114:117], v[144:147], v[184:187], v[114:117]
	v_mfma_f32_16x16x32_bf16 v[110:113], v[152:155], v[184:187], v[110:113]
	v_mfma_f32_16x16x32_bf16 v[98:101], v[144:147], v[192:195], v[98:101]
	v_mfma_f32_16x16x32_bf16 v[94:97], v[152:155], v[192:195], v[94:97]
	v_mfma_f32_16x16x32_bf16 v[82:85], v[144:147], v[200:203], v[82:85]
	v_mfma_f32_16x16x32_bf16 v[78:81], v[152:155], v[200:203], v[78:81]
	v_mfma_f32_16x16x32_bf16 v[122:125], v[156:159], v[172:175], v[122:125]
	v_mfma_f32_16x16x32_bf16 v[118:121], v[164:167], v[172:175], v[118:121]
	v_mfma_f32_16x16x32_bf16 v[106:109], v[156:159], v[180:183], v[106:109]
	v_mfma_f32_16x16x32_bf16 v[102:105], v[164:167], v[180:183], v[102:105]
	v_mfma_f32_16x16x32_bf16 v[90:93], v[156:159], v[188:191], v[90:93]
	v_mfma_f32_16x16x32_bf16 v[86:89], v[164:167], v[188:191], v[86:89]
	v_mfma_f32_16x16x32_bf16 v[74:77], v[156:159], v[196:199], v[74:77]
	v_mfma_f32_16x16x32_bf16 v[70:73], v[164:167], v[196:199], v[70:73]
	v_mfma_f32_16x16x32_bf16 v[122:125], v[160:163], v[176:179], v[122:125]
	v_mfma_f32_16x16x32_bf16 v[118:121], v[168:171], v[176:179], v[118:121]
	v_mfma_f32_16x16x32_bf16 v[106:109], v[160:163], v[184:187], v[106:109]
	v_mfma_f32_16x16x32_bf16 v[102:105], v[168:171], v[184:187], v[102:105]
	v_mfma_f32_16x16x32_bf16 v[90:93], v[160:163], v[192:195], v[90:93]
	v_mfma_f32_16x16x32_bf16 v[86:89], v[168:171], v[192:195], v[86:89]
	v_mfma_f32_16x16x32_bf16 v[74:77], v[160:163], v[200:203], v[74:77]
	v_mfma_f32_16x16x32_bf16 v[70:73], v[168:171], v[200:203], v[70:73]
	s_setprio 0
	s_barrier
	s_add_i32 s30, s34, s42
	v_lshl_add_u64 v[204:205], s[28:29], 0, v[134:135]
	s_mov_b32 m0, s30
	ds_read_b128 v[172:175], v5 offset:49152
	ds_read_b128 v[176:179], v5 offset:50176
	ds_read_b128 v[180:183], v5 offset:51200
	ds_read_b128 v[184:187], v5 offset:52224
	ds_read_b128 v[188:191], v5 offset:53248
	ds_read_b128 v[192:195], v5 offset:54272
	ds_read_b128 v[196:199], v5 offset:55296
	ds_read_b128 v[200:203], v5 offset:56320
	global_load_lds_dwordx4 v[204:205], off
	s_add_i32 m0, s30, 0x2000
	v_lshl_add_u64 v[204:205], s[28:29], 0, v[138:139]
	s_add_u32 s28, s28, 0x20000
	s_addc_u32 s29, s29, 0
	s_add_i32 s30, s35, s42
	global_load_lds_dwordx4 v[204:205], off
	v_lshl_add_u64 v[204:205], s[28:29], 0, v[134:135]
	s_mov_b32 m0, s30
	s_nop 0
	global_load_lds_dwordx4 v[204:205], off
	v_lshl_add_u64 v[204:205], s[28:29], 0, v[138:139]
	s_add_i32 m0, s30, 0x2000
	s_nop 0
	global_load_lds_dwordx4 v[204:205], off
	v_lshl_add_u64 v[204:205], s[26:27], 0, v[2:3]
	s_mov_b32 m0, s49
	s_nop 0
	global_load_lds_dwordx4 v[204:205], off
	v_lshl_add_u64 v[204:205], s[26:27], 0, v[136:137]
	s_mov_b32 m0, s50
	s_nop 0
	global_load_lds_dwordx4 v[204:205], off
	s_waitcnt vmcnt(8)
	s_waitcnt lgkmcnt(0)
	s_barrier
	s_setprio 1
	v_mfma_f32_16x16x32_bf16 v[66:69], v[140:143], v[172:175], v[66:69]
	v_mfma_f32_16x16x32_bf16 v[62:65], v[148:151], v[172:175], v[62:65]
	v_mfma_f32_16x16x32_bf16 v[50:53], v[140:143], v[180:183], v[50:53]
	v_mfma_f32_16x16x32_bf16 v[46:49], v[148:151], v[180:183], v[46:49]
	v_mfma_f32_16x16x32_bf16 v[34:37], v[140:143], v[188:191], v[34:37]
	v_mfma_f32_16x16x32_bf16 v[30:33], v[148:151], v[188:191], v[30:33]
	v_mfma_f32_16x16x32_bf16 v[18:21], v[140:143], v[196:199], v[18:21]
	v_mfma_f32_16x16x32_bf16 v[14:17], v[148:151], v[196:199], v[14:17]
	v_mfma_f32_16x16x32_bf16 v[66:69], v[144:147], v[176:179], v[66:69]
	v_mfma_f32_16x16x32_bf16 v[62:65], v[152:155], v[176:179], v[62:65]
	v_mfma_f32_16x16x32_bf16 v[50:53], v[144:147], v[184:187], v[50:53]
	v_mfma_f32_16x16x32_bf16 v[46:49], v[152:155], v[184:187], v[46:49]
	v_mfma_f32_16x16x32_bf16 v[34:37], v[144:147], v[192:195], v[34:37]
	v_mfma_f32_16x16x32_bf16 v[30:33], v[152:155], v[192:195], v[30:33]
	v_mfma_f32_16x16x32_bf16 v[18:21], v[144:147], v[200:203], v[18:21]
	v_mfma_f32_16x16x32_bf16 v[14:17], v[152:155], v[200:203], v[14:17]
	v_mfma_f32_16x16x32_bf16 v[58:61], v[156:159], v[172:175], v[58:61]
	v_mfma_f32_16x16x32_bf16 v[54:57], v[164:167], v[172:175], v[54:57]
	v_mfma_f32_16x16x32_bf16 v[42:45], v[156:159], v[180:183], v[42:45]
	v_mfma_f32_16x16x32_bf16 v[38:41], v[164:167], v[180:183], v[38:41]
	v_mfma_f32_16x16x32_bf16 v[26:29], v[156:159], v[188:191], v[26:29]
	v_mfma_f32_16x16x32_bf16 v[22:25], v[164:167], v[188:191], v[22:25]
	v_mfma_f32_16x16x32_bf16 v[10:13], v[156:159], v[196:199], v[10:13]
	v_mfma_f32_16x16x32_bf16 v[6:9], v[164:167], v[196:199], v[6:9]
	v_mfma_f32_16x16x32_bf16 v[58:61], v[160:163], v[176:179], v[58:61]
	v_mfma_f32_16x16x32_bf16 v[54:57], v[168:171], v[176:179], v[54:57]
	v_mfma_f32_16x16x32_bf16 v[42:45], v[160:163], v[184:187], v[42:45]
	v_mfma_f32_16x16x32_bf16 v[38:41], v[168:171], v[184:187], v[38:41]
	v_mfma_f32_16x16x32_bf16 v[26:29], v[160:163], v[192:195], v[26:29]
	v_mfma_f32_16x16x32_bf16 v[22:25], v[168:171], v[192:195], v[22:25]
	v_mfma_f32_16x16x32_bf16 v[10:13], v[160:163], v[200:203], v[10:13]
	v_mfma_f32_16x16x32_bf16 v[6:9], v[168:171], v[200:203], v[6:9]
	s_setprio 0
	s_barrier
	s_add_i32 s56, s56, 2
	s_add_u32 s52, s52, 0x100
	s_addc_u32 s53, s53, 0
	s_add_u32 s54, s54, 0x100
	s_addc_u32 s55, s55, 0
	s_cmp_gt_u32 s56, 5
	s_cbranch_scc0 .LBB0_480
	s_and_b64 vcc, exec, s[8:9]
	s_cbranch_vccz .LBB0_483
	s_barrier

.LBB0_536:
	s_add_u32 s48, s45, 0xffffff80
	s_addc_u32 s49, s46, -1
	s_cmp_eq_u32 s47, 4
	s_cselect_b32 s22, s41, s45
	s_cselect_b32 s23, s7, s46
	s_cselect_b32 s25, s9, s44
	s_cselect_b32 s24, s42, s43
	s_add_u32 s18, s22, 0x80
	s_addc_u32 s19, s23, 0
	s_add_u32 s20, s24, 0x80
	s_addc_u32 s21, s25, 0
	s_add_i32 s50, 0, 0x10000
	s_add_i32 s51, 0, 0x14000
	v_add_u32_e32 v152, s50, v1
	v_add_u32_e32 v168, s51, v1
	ds_read_b128 v[140:143], v152
	ds_read_b128 v[144:147], v152 offset:1024
	ds_read_b128 v[148:151], v152 offset:2048
	ds_read_b128 v[152:155], v152 offset:3072
	ds_read_b128 v[156:159], v168
	ds_read_b128 v[160:163], v168 offset:1024
	ds_read_b128 v[164:167], v168 offset:2048
	ds_read_b128 v[168:171], v168 offset:3072
	s_add_u32 s48, s48, 0x20000
	s_addc_u32 s49, s49, 0
	v_lshl_add_u64 v[204:205], s[48:49], 0, v[2:3]
	s_add_i32 m0, s15, 0xc000
	ds_read_b128 v[172:175], v5
	ds_read_b128 v[176:179], v5 offset:1024
	ds_read_b128 v[180:183], v5 offset:2048
	ds_read_b128 v[184:187], v5 offset:3072
	ds_read_b128 v[188:191], v5 offset:4096
	ds_read_b128 v[192:195], v5 offset:5120
	ds_read_b128 v[196:199], v5 offset:6144
	ds_read_b128 v[200:203], v5 offset:7168
	global_load_lds_dwordx4 v[204:205], off
	v_lshl_add_u64 v[204:205], s[48:49], 0, v[136:137]
	s_add_i32 m0, s15, 0xe000
	s_nop 0
	global_load_lds_dwordx4 v[204:205], off
	s_waitcnt vmcnt(8)
	s_waitcnt lgkmcnt(0)
	s_barrier
	s_setprio 1
	v_mfma_f32_16x16x32_bf16 v[130:133], v[140:143], v[172:175], v[130:133]
	v_mfma_f32_16x16x32_bf16 v[126:129], v[148:151], v[172:175], v[126:129]
	v_mfma_f32_16x16x32_bf16 v[122:125], v[140:143], v[180:183], v[122:125]
	v_mfma_f32_16x16x32_bf16 v[114:117], v[148:151], v[180:183], v[114:117]
	v_mfma_f32_16x16x32_bf16 v[106:109], v[140:143], v[188:191], v[106:109]
	v_mfma_f32_16x16x32_bf16 v[98:101], v[148:151], v[188:191], v[98:101]
	v_mfma_f32_16x16x32_bf16 v[90:93], v[140:143], v[196:199], v[90:93]
	v_mfma_f32_16x16x32_bf16 v[82:85], v[148:151], v[196:199], v[82:85]
	v_mfma_f32_16x16x32_bf16 v[130:133], v[144:147], v[176:179], v[130:133]
	v_mfma_f32_16x16x32_bf16 v[126:129], v[152:155], v[176:179], v[126:129]
	v_mfma_f32_16x16x32_bf16 v[122:125], v[144:147], v[184:187], v[122:125]
	v_mfma_f32_16x16x32_bf16 v[114:117], v[152:155], v[184:187], v[114:117]
	v_mfma_f32_16x16x32_bf16 v[106:109], v[144:147], v[192:195], v[106:109]
	v_mfma_f32_16x16x32_bf16 v[98:101], v[152:155], v[192:195], v[98:101]
	v_mfma_f32_16x16x32_bf16 v[90:93], v[144:147], v[200:203], v[90:93]
	v_mfma_f32_16x16x32_bf16 v[82:85], v[152:155], v[200:203], v[82:85]
	v_mfma_f32_16x16x32_bf16 v[118:121], v[156:159], v[172:175], v[118:121]
	v_mfma_f32_16x16x32_bf16 v[110:113], v[164:167], v[172:175], v[110:113]
	v_mfma_f32_16x16x32_bf16 v[102:105], v[156:159], v[180:183], v[102:105]
	v_mfma_f32_16x16x32_bf16 v[94:97], v[164:167], v[180:183], v[94:97]
	v_mfma_f32_16x16x32_bf16 v[86:89], v[156:159], v[188:191], v[86:89]
	v_mfma_f32_16x16x32_bf16 v[78:81], v[164:167], v[188:191], v[78:81]
	v_mfma_f32_16x16x32_bf16 v[74:77], v[156:159], v[196:199], v[74:77]
	v_mfma_f32_16x16x32_bf16 v[70:73], v[164:167], v[196:199], v[70:73]
	v_mfma_f32_16x16x32_bf16 v[118:121], v[160:163], v[176:179], v[118:121]
	v_mfma_f32_16x16x32_bf16 v[110:113], v[168:171], v[176:179], v[110:113]
	v_mfma_f32_16x16x32_bf16 v[102:105], v[160:163], v[184:187], v[102:105]
	v_mfma_f32_16x16x32_bf16 v[94:97], v[168:171], v[184:187], v[94:97]
	v_mfma_f32_16x16x32_bf16 v[86:89], v[160:163], v[192:195], v[86:89]
	v_mfma_f32_16x16x32_bf16 v[78:81], v[168:171], v[192:195], v[78:81]
	v_mfma_f32_16x16x32_bf16 v[74:77], v[160:163], v[200:203], v[74:77]
	v_mfma_f32_16x16x32_bf16 v[70:73], v[168:171], v[200:203], v[70:73]
	s_setprio 0
	s_barrier
	s_add_i32 s48, s50, s29
	v_lshl_add_u64 v[204:205], s[24:25], 0, v[134:135]
	s_mov_b32 m0, s48
	ds_read_b128 v[172:175], v5 offset:16384
	ds_read_b128 v[176:179], v5 offset:17408
	ds_read_b128 v[180:183], v5 offset:18432
	ds_read_b128 v[184:187], v5 offset:19456
	ds_read_b128 v[188:191], v5 offset:20480
	ds_read_b128 v[192:195], v5 offset:21504
	ds_read_b128 v[196:199], v5 offset:22528
	ds_read_b128 v[200:203], v5 offset:23552
	global_load_lds_dwordx4 v[204:205], off
	s_add_i32 m0, s48, 0x2000
	v_lshl_add_u64 v[204:205], s[24:25], 0, v[138:139]
	s_add_u32 s24, s24, 0x20000
	s_addc_u32 s25, s25, 0
	s_add_i32 s48, s51, s29
	global_load_lds_dwordx4 v[204:205], off
	v_lshl_add_u64 v[204:205], s[24:25], 0, v[134:135]
	s_mov_b32 m0, s48
	s_nop 0
	global_load_lds_dwordx4 v[204:205], off
	v_lshl_add_u64 v[204:205], s[24:25], 0, v[138:139]
	s_add_i32 m0, s48, 0x2000
	s_nop 0
	global_load_lds_dwordx4 v[204:205], off
	v_lshl_add_u64 v[204:205], s[22:23], 0, v[2:3]
	s_mov_b32 m0, s15
	s_nop 0
	global_load_lds_dwordx4 v[204:205], off
	v_lshl_add_u64 v[204:205], s[22:23], 0, v[136:137]
	s_mov_b32 m0, s17
	s_nop 0
	global_load_lds_dwordx4 v[204:205], off
	s_waitcnt vmcnt(8)
	s_waitcnt lgkmcnt(0)
	s_barrier
	s_setprio 1
	v_mfma_f32_16x16x32_bf16 v[66:69], v[140:143], v[172:175], v[66:69]
	v_mfma_f32_16x16x32_bf16 v[62:65], v[148:151], v[172:175], v[62:65]
	v_mfma_f32_16x16x32_bf16 v[58:61], v[140:143], v[180:183], v[58:61]
	v_mfma_f32_16x16x32_bf16 v[50:53], v[148:151], v[180:183], v[50:53]
	v_mfma_f32_16x16x32_bf16 v[42:45], v[140:143], v[188:191], v[42:45]
	v_mfma_f32_16x16x32_bf16 v[34:37], v[148:151], v[188:191], v[34:37]
	v_mfma_f32_16x16x32_bf16 v[26:29], v[140:143], v[196:199], v[26:29]
	v_mfma_f32_16x16x32_bf16 v[18:21], v[148:151], v[196:199], v[18:21]
	v_mfma_f32_16x16x32_bf16 v[66:69], v[144:147], v[176:179], v[66:69]
	v_mfma_f32_16x16x32_bf16 v[62:65], v[152:155], v[176:179], v[62:65]
	v_mfma_f32_16x16x32_bf16 v[58:61], v[144:147], v[184:187], v[58:61]
	v_mfma_f32_16x16x32_bf16 v[50:53], v[152:155], v[184:187], v[50:53]
	v_mfma_f32_16x16x32_bf16 v[42:45], v[144:147], v[192:195], v[42:45]
	v_mfma_f32_16x16x32_bf16 v[34:37], v[152:155], v[192:195], v[34:37]
	v_mfma_f32_16x16x32_bf16 v[26:29], v[144:147], v[200:203], v[26:29]
	v_mfma_f32_16x16x32_bf16 v[18:21], v[152:155], v[200:203], v[18:21]
	v_mfma_f32_16x16x32_bf16 v[54:57], v[156:159], v[172:175], v[54:57]
	v_mfma_f32_16x16x32_bf16 v[46:49], v[164:167], v[172:175], v[46:49]
	v_mfma_f32_16x16x32_bf16 v[38:41], v[156:159], v[180:183], v[38:41]
	v_mfma_f32_16x16x32_bf16 v[30:33], v[164:167], v[180:183], v[30:33]
	v_mfma_f32_16x16x32_bf16 v[22:25], v[156:159], v[188:191], v[22:25]
	v_mfma_f32_16x16x32_bf16 v[14:17], v[164:167], v[188:191], v[14:17]
	v_mfma_f32_16x16x32_bf16 v[10:13], v[156:159], v[196:199], v[10:13]
	v_mfma_f32_16x16x32_bf16 v[6:9], v[164:167], v[196:199], v[6:9]
	v_mfma_f32_16x16x32_bf16 v[54:57], v[160:163], v[176:179], v[54:57]
	v_mfma_f32_16x16x32_bf16 v[46:49], v[168:171], v[176:179], v[46:49]
	v_mfma_f32_16x16x32_bf16 v[38:41], v[160:163], v[184:187], v[38:41]
	v_mfma_f32_16x16x32_bf16 v[30:33], v[168:171], v[184:187], v[30:33]
	v_mfma_f32_16x16x32_bf16 v[22:25], v[160:163], v[192:195], v[22:25]
	v_mfma_f32_16x16x32_bf16 v[14:17], v[168:171], v[192:195], v[14:17]
	v_mfma_f32_16x16x32_bf16 v[10:13], v[160:163], v[200:203], v[10:13]
	v_mfma_f32_16x16x32_bf16 v[6:9], v[168:171], v[200:203], v[6:9]
	s_setprio 0
	s_barrier
	s_add_i32 s24, 0, 0x18000
	s_add_i32 s25, 0, 0x1c000
	v_add_u32_e32 v152, s24, v1
	v_add_u32_e32 v168, s25, v1
	ds_read_b128 v[140:143], v152
	ds_read_b128 v[144:147], v152 offset:1024
	ds_read_b128 v[148:151], v152 offset:2048
	ds_read_b128 v[152:155], v152 offset:3072
	ds_read_b128 v[156:159], v168
	ds_read_b128 v[160:163], v168 offset:1024
	ds_read_b128 v[164:167], v168 offset:2048
	ds_read_b128 v[168:171], v168 offset:3072
	s_add_u32 s22, s22, 0x20000
	s_addc_u32 s23, s23, 0
	s_mov_b32 m0, s31
	v_lshl_add_u64 v[204:205], s[22:23], 0, v[2:3]
	ds_read_b128 v[172:175], v5 offset:32768
	ds_read_b128 v[176:179], v5 offset:33792
	ds_read_b128 v[180:183], v5 offset:34816
	ds_read_b128 v[184:187], v5 offset:35840
	ds_read_b128 v[188:191], v5 offset:36864
	ds_read_b128 v[192:195], v5 offset:37888
	ds_read_b128 v[196:199], v5 offset:38912
	ds_read_b128 v[200:203], v5 offset:39936
	global_load_lds_dwordx4 v[204:205], off
	v_lshl_add_u64 v[204:205], s[22:23], 0, v[136:137]
	s_mov_b32 m0, s33
	s_nop 0
	global_load_lds_dwordx4 v[204:205], off
	s_waitcnt vmcnt(8)
	s_waitcnt lgkmcnt(0)
	s_barrier
	s_setprio 1
	v_mfma_f32_16x16x32_bf16 v[130:133], v[140:143], v[172:175], v[130:133]
	v_mfma_f32_16x16x32_bf16 v[126:129], v[148:151], v[172:175], v[126:129]
	v_mfma_f32_16x16x32_bf16 v[122:125], v[140:143], v[180:183], v[122:125]
	v_mfma_f32_16x16x32_bf16 v[114:117], v[148:151], v[180:183], v[114:117]
	v_mfma_f32_16x16x32_bf16 v[106:109], v[140:143], v[188:191], v[106:109]
	v_mfma_f32_16x16x32_bf16 v[98:101], v[148:151], v[188:191], v[98:101]
	v_mfma_f32_16x16x32_bf16 v[90:93], v[140:143], v[196:199], v[90:93]
	v_mfma_f32_16x16x32_bf16 v[82:85], v[148:151], v[196:199], v[82:85]
	v_mfma_f32_16x16x32_bf16 v[130:133], v[144:147], v[176:179], v[130:133]
	v_mfma_f32_16x16x32_bf16 v[126:129], v[152:155], v[176:179], v[126:129]
	v_mfma_f32_16x16x32_bf16 v[122:125], v[144:147], v[184:187], v[122:125]
	v_mfma_f32_16x16x32_bf16 v[114:117], v[152:155], v[184:187], v[114:117]
	v_mfma_f32_16x16x32_bf16 v[106:109], v[144:147], v[192:195], v[106:109]
	v_mfma_f32_16x16x32_bf16 v[98:101], v[152:155], v[192:195], v[98:101]
	v_mfma_f32_16x16x32_bf16 v[90:93], v[144:147], v[200:203], v[90:93]
	v_mfma_f32_16x16x32_bf16 v[82:85], v[152:155], v[200:203], v[82:85]
	v_mfma_f32_16x16x32_bf16 v[118:121], v[156:159], v[172:175], v[118:121]
	v_mfma_f32_16x16x32_bf16 v[110:113], v[164:167], v[172:175], v[110:113]
	v_mfma_f32_16x16x32_bf16 v[102:105], v[156:159], v[180:183], v[102:105]
	v_mfma_f32_16x16x32_bf16 v[94:97], v[164:167], v[180:183], v[94:97]
	v_mfma_f32_16x16x32_bf16 v[86:89], v[156:159], v[188:191], v[86:89]
	v_mfma_f32_16x16x32_bf16 v[78:81], v[164:167], v[188:191], v[78:81]
	v_mfma_f32_16x16x32_bf16 v[74:77], v[156:159], v[196:199], v[74:77]
	v_mfma_f32_16x16x32_bf16 v[70:73], v[164:167], v[196:199], v[70:73]
	v_mfma_f32_16x16x32_bf16 v[118:121], v[160:163], v[176:179], v[118:121]
	v_mfma_f32_16x16x32_bf16 v[110:113], v[168:171], v[176:179], v[110:113]
	v_mfma_f32_16x16x32_bf16 v[102:105], v[160:163], v[184:187], v[102:105]
	v_mfma_f32_16x16x32_bf16 v[94:97], v[168:171], v[184:187], v[94:97]
	v_mfma_f32_16x16x32_bf16 v[86:89], v[160:163], v[192:195], v[86:89]
	v_mfma_f32_16x16x32_bf16 v[78:81], v[168:171], v[192:195], v[78:81]
	v_mfma_f32_16x16x32_bf16 v[74:77], v[160:163], v[200:203], v[74:77]
	v_mfma_f32_16x16x32_bf16 v[70:73], v[168:171], v[200:203], v[70:73]
	s_setprio 0
	s_barrier
	s_add_i32 s22, s24, s29
	v_lshl_add_u64 v[204:205], s[20:21], 0, v[134:135]
	s_mov_b32 m0, s22
	ds_read_b128 v[172:175], v5 offset:49152
	ds_read_b128 v[176:179], v5 offset:50176
	ds_read_b128 v[180:183], v5 offset:51200
	ds_read_b128 v[184:187], v5 offset:52224
	ds_read_b128 v[188:191], v5 offset:53248
	ds_read_b128 v[192:195], v5 offset:54272
	ds_read_b128 v[196:199], v5 offset:55296
	ds_read_b128 v[200:203], v5 offset:56320
	global_load_lds_dwordx4 v[204:205], off
	s_add_i32 m0, s22, 0x2000
	v_lshl_add_u64 v[204:205], s[20:21], 0, v[138:139]
	s_add_u32 s20, s20, 0x20000
	s_addc_u32 s21, s21, 0
	s_add_i32 s22, s25, s29
	global_load_lds_dwordx4 v[204:205], off
	v_lshl_add_u64 v[204:205], s[20:21], 0, v[134:135]
	s_mov_b32 m0, s22
	s_nop 0
	global_load_lds_dwordx4 v[204:205], off
	v_lshl_add_u64 v[204:205], s[20:21], 0, v[138:139]
	s_add_i32 m0, s22, 0x2000
	s_nop 0
	global_load_lds_dwordx4 v[204:205], off
	v_lshl_add_u64 v[204:205], s[18:19], 0, v[2:3]
	s_mov_b32 m0, s38
	s_nop 0
	global_load_lds_dwordx4 v[204:205], off
	v_lshl_add_u64 v[204:205], s[18:19], 0, v[136:137]
	s_mov_b32 m0, s39
	s_nop 0
	global_load_lds_dwordx4 v[204:205], off
	s_waitcnt vmcnt(8)
	s_waitcnt lgkmcnt(0)
	s_barrier
	s_setprio 1
	v_mfma_f32_16x16x32_bf16 v[66:69], v[140:143], v[172:175], v[66:69]
	v_mfma_f32_16x16x32_bf16 v[62:65], v[148:151], v[172:175], v[62:65]
	v_mfma_f32_16x16x32_bf16 v[58:61], v[140:143], v[180:183], v[58:61]
	v_mfma_f32_16x16x32_bf16 v[50:53], v[148:151], v[180:183], v[50:53]
	v_mfma_f32_16x16x32_bf16 v[42:45], v[140:143], v[188:191], v[42:45]
	v_mfma_f32_16x16x32_bf16 v[34:37], v[148:151], v[188:191], v[34:37]
	v_mfma_f32_16x16x32_bf16 v[26:29], v[140:143], v[196:199], v[26:29]
	v_mfma_f32_16x16x32_bf16 v[18:21], v[148:151], v[196:199], v[18:21]
	v_mfma_f32_16x16x32_bf16 v[66:69], v[144:147], v[176:179], v[66:69]
	v_mfma_f32_16x16x32_bf16 v[62:65], v[152:155], v[176:179], v[62:65]
	v_mfma_f32_16x16x32_bf16 v[58:61], v[144:147], v[184:187], v[58:61]
	v_mfma_f32_16x16x32_bf16 v[50:53], v[152:155], v[184:187], v[50:53]
	v_mfma_f32_16x16x32_bf16 v[42:45], v[144:147], v[192:195], v[42:45]
	v_mfma_f32_16x16x32_bf16 v[34:37], v[152:155], v[192:195], v[34:37]
	v_mfma_f32_16x16x32_bf16 v[26:29], v[144:147], v[200:203], v[26:29]
	v_mfma_f32_16x16x32_bf16 v[18:21], v[152:155], v[200:203], v[18:21]
	v_mfma_f32_16x16x32_bf16 v[54:57], v[156:159], v[172:175], v[54:57]
	v_mfma_f32_16x16x32_bf16 v[46:49], v[164:167], v[172:175], v[46:49]
	v_mfma_f32_16x16x32_bf16 v[38:41], v[156:159], v[180:183], v[38:41]
	v_mfma_f32_16x16x32_bf16 v[30:33], v[164:167], v[180:183], v[30:33]
	v_mfma_f32_16x16x32_bf16 v[22:25], v[156:159], v[188:191], v[22:25]
	v_mfma_f32_16x16x32_bf16 v[14:17], v[164:167], v[188:191], v[14:17]
	v_mfma_f32_16x16x32_bf16 v[10:13], v[156:159], v[196:199], v[10:13]
	v_mfma_f32_16x16x32_bf16 v[6:9], v[164:167], v[196:199], v[6:9]
	v_mfma_f32_16x16x32_bf16 v[54:57], v[160:163], v[176:179], v[54:57]
	v_mfma_f32_16x16x32_bf16 v[46:49], v[168:171], v[176:179], v[46:49]
	v_mfma_f32_16x16x32_bf16 v[38:41], v[160:163], v[184:187], v[38:41]
	v_mfma_f32_16x16x32_bf16 v[30:33], v[168:171], v[184:187], v[30:33]
	v_mfma_f32_16x16x32_bf16 v[22:25], v[160:163], v[192:195], v[22:25]
	v_mfma_f32_16x16x32_bf16 v[14:17], v[168:171], v[192:195], v[14:17]
	v_mfma_f32_16x16x32_bf16 v[10:13], v[160:163], v[200:203], v[10:13]
	v_mfma_f32_16x16x32_bf16 v[6:9], v[168:171], v[200:203], v[6:9]
	s_setprio 0
	s_barrier
	s_add_i32 s47, s47, 2
	s_add_u32 s43, s43, 0x100
	s_addc_u32 s44, s44, 0
	s_add_u32 s45, s45, 0x100
	s_addc_u32 s46, s46, 0
	s_cmp_gt_u32 s47, 5
	s_cbranch_scc0 .LBB0_536
	s_lshl_b32 s20, s16, 8
	v_mov_b32_e32 v140, v0
	s_mov_b64 s[18:19], s[84:85]
	s_lshl_b32 s7, s14, 8
	s_ashr_i32 s21, s20, 31
	s_add_i32 s7, s7, s34
	s_lshl_b64 s[20:21], s[20:21], 1
	v_and_b32_e32 v142, 15, v140
	s_add_u32 s18, s18, s20
	v_or_b32_e32 v146, s7, v142
	v_lshrrev_b32_e32 v140, 1, v140
	s_addc_u32 s19, s19, s21
	s_ashr_i32 s9, s7, 11
	v_mov_b32_e32 v143, s7
	s_movk_i32 s7, 0x7cf
	v_and_or_b32 v140, v140, 24, s35
	s_mulk_i32 s9, 0x810
	v_bitop3_b32 v142, v142, s7, v143 bitop3:0xc8
	v_lshlrev_b32_e32 v140, 1, v140
	v_mov_b32_e32 v141, v4
	v_add_u32_e32 v142, s9, v142
	v_lshl_add_u64 v[140:141], s[18:19], 0, v[140:141]
	s_mov_b64 s[18:19], 0x2c900000
	v_ashrrev_i32_e32 v143, 31, v142
	v_lshl_add_u64 v[140:141], v[140:141], 0, s[18:19]
	v_lshlrev_b64 v[144:145], 13, v[142:143]
	v_lshl_add_u64 v[144:145], v[140:141], 0, v[144:145]
	v_cvt_pk_bf16_f32 v130, v130, v131
	v_cvt_pk_bf16_f32 v131, v132, v133
	v_cvt_pk_bf16_f32 v132, v126, v127
	v_cvt_pk_bf16_f32 v133, v128, v129
	global_store_dwordx4 v[144:145], v[130:133], off nt
	v_cvt_pk_bf16_f32 v118, v118, v119
	v_cvt_pk_bf16_f32 v119, v120, v121
	v_cvt_pk_bf16_f32 v120, v110, v111
	v_add_u32_e32 v110, 16, v142
	v_ashrrev_i32_e32 v111, 31, v110
	v_lshlrev_b64 v[110:111], 13, v[110:111]
	v_cvt_pk_bf16_f32 v121, v112, v113
	global_store_dwordx4 v[144:145], v[118:121], off offset:256 nt
	s_movk_i32 s7, 0x810
	s_and_b64 vcc, exec, s[0:1]
	v_lshl_add_u64 v[118:119], v[140:141], 0, v[110:111]
	v_cvt_pk_bf16_f32 v110, v122, v123
	v_cvt_pk_bf16_f32 v111, v124, v125
	v_cvt_pk_bf16_f32 v112, v114, v115
	v_cvt_pk_bf16_f32 v113, v116, v117
	global_store_dwordx4 v[118:119], v[110:113], off nt
	v_cvt_pk_bf16_f32 v102, v102, v103
	v_cvt_pk_bf16_f32 v103, v104, v105
	v_cvt_pk_bf16_f32 v104, v94, v95
	v_add_u32_e32 v94, 32, v142
	v_ashrrev_i32_e32 v95, 31, v94
	v_lshlrev_b64 v[94:95], 13, v[94:95]
	v_cvt_pk_bf16_f32 v105, v96, v97
	global_store_dwordx4 v[118:119], v[102:105], off offset:256 nt
	s_mov_b32 s16, s8
	s_mov_b32 s14, s6
	v_lshl_add_u64 v[102:103], v[140:141], 0, v[94:95]
	v_cvt_pk_bf16_f32 v94, v106, v107
	v_cvt_pk_bf16_f32 v95, v108, v109
	v_cvt_pk_bf16_f32 v96, v98, v99
	v_cvt_pk_bf16_f32 v97, v100, v101
	global_store_dwordx4 v[102:103], v[94:97], off nt
	v_cvt_pk_bf16_f32 v86, v86, v87
	v_cvt_pk_bf16_f32 v87, v88, v89
	v_cvt_pk_bf16_f32 v88, v78, v79
	v_add_u32_e32 v78, 48, v142
	v_ashrrev_i32_e32 v79, 31, v78
	v_lshlrev_b64 v[78:79], 13, v[78:79]
	v_cvt_pk_bf16_f32 v89, v80, v81
	global_store_dwordx4 v[102:103], v[86:89], off offset:256 nt
	s_mov_b64 s[20:21], s[10:11]
	s_mov_b64 s[18:19], s[12:13]
	v_lshl_add_u64 v[86:87], v[140:141], 0, v[78:79]
	v_cvt_pk_bf16_f32 v78, v90, v91
	v_cvt_pk_bf16_f32 v79, v92, v93
	v_cvt_pk_bf16_f32 v80, v82, v83
	v_cvt_pk_bf16_f32 v81, v84, v85
	global_store_dwordx4 v[86:87], v[78:81], off nt
	v_cvt_pk_bf16_f32 v74, v74, v75
	v_cvt_pk_bf16_f32 v75, v76, v77
	v_cvt_pk_bf16_f32 v76, v70, v71
	v_add_u32_e32 v70, 0x80, v146
	v_ashrrev_i32_e32 v71, 11, v70
	v_and_b32_e32 v70, 0x7cf, v70
	v_mad_i32_i24 v70, v71, s7, v70
	v_ashrrev_i32_e32 v71, 31, v70
	v_cvt_pk_bf16_f32 v77, v72, v73
	v_lshlrev_b64 v[72:73], 13, v[70:71]
	global_store_dwordx4 v[86:87], v[74:77], off offset:256 nt
	v_lshl_add_u64 v[72:73], v[140:141], 0, v[72:73]
	v_cvt_pk_bf16_f32 v66, v66, v67
	v_cvt_pk_bf16_f32 v67, v68, v69
	v_cvt_pk_bf16_f32 v68, v62, v63
	v_cvt_pk_bf16_f32 v69, v64, v65
	global_store_dwordx4 v[72:73], v[66:69], off nt
	v_cvt_pk_bf16_f32 v54, v54, v55
	v_cvt_pk_bf16_f32 v55, v56, v57
	v_cvt_pk_bf16_f32 v56, v46, v47
	v_add_u32_e32 v46, 16, v70
	v_ashrrev_i32_e32 v47, 31, v46
	v_lshlrev_b64 v[46:47], 13, v[46:47]
	v_cvt_pk_bf16_f32 v57, v48, v49
	global_store_dwordx4 v[72:73], v[54:57], off offset:256 nt
	s_mov_b32 s51, 0x40c000
	s_mov_b32 s47, 0x120000
	v_lshl_add_u64 v[54:55], v[140:141], 0, v[46:47]
	v_cvt_pk_bf16_f32 v46, v58, v59
	v_cvt_pk_bf16_f32 v47, v60, v61
	v_cvt_pk_bf16_f32 v48, v50, v51
	v_cvt_pk_bf16_f32 v49, v52, v53
	global_store_dwordx4 v[54:55], v[46:49], off nt
	v_cvt_pk_bf16_f32 v38, v38, v39
	v_cvt_pk_bf16_f32 v39, v40, v41
	v_cvt_pk_bf16_f32 v40, v30, v31
	v_add_u32_e32 v30, 32, v70
	v_ashrrev_i32_e32 v31, 31, v30
	v_lshlrev_b64 v[30:31], 13, v[30:31]
	v_cvt_pk_bf16_f32 v41, v32, v33
	global_store_dwordx4 v[54:55], v[38:41], off offset:256 nt
	s_mov_b64 s[48:49], 0x7ffff
	s_nop 0
	v_lshl_add_u64 v[38:39], v[140:141], 0, v[30:31]
	v_cvt_pk_bf16_f32 v30, v42, v43
	v_cvt_pk_bf16_f32 v31, v44, v45
	v_cvt_pk_bf16_f32 v32, v34, v35
	v_cvt_pk_bf16_f32 v33, v36, v37
	global_store_dwordx4 v[38:39], v[30:33], off nt
	v_cvt_pk_bf16_f32 v22, v22, v23
	v_cvt_pk_bf16_f32 v23, v24, v25
	v_cvt_pk_bf16_f32 v24, v14, v15
	v_add_u32_e32 v14, 48, v70
	v_ashrrev_i32_e32 v15, 31, v14
	v_lshlrev_b64 v[14:15], 13, v[14:15]
	v_cvt_pk_bf16_f32 v25, v16, v17
	global_store_dwordx4 v[38:39], v[22:25], off offset:256 nt
	s_nop 1
	v_lshl_add_u64 v[22:23], v[140:141], 0, v[14:15]
	v_cvt_pk_bf16_f32 v14, v26, v27
	v_cvt_pk_bf16_f32 v15, v28, v29
	v_cvt_pk_bf16_f32 v16, v18, v19
	v_cvt_pk_bf16_f32 v17, v20, v21
	global_store_dwordx4 v[22:23], v[14:17], off nt
	v_cvt_pk_bf16_f32 v10, v10, v11
	v_cvt_pk_bf16_f32 v11, v12, v13
	v_cvt_pk_bf16_f32 v12, v6, v7
	v_cvt_pk_bf16_f32 v13, v8, v9
	global_store_dwordx4 v[22:23], v[10:13], off offset:256 nt
	s_cbranch_vccz .LBB0_529
	s_waitcnt vmcnt(0)
	s_cmpk_gt_u32 s28, 0xff
	s_cbranch_scc1 .LBB0_540
	s_barrier

.LBB0_924:
	s_add_u32 s48, s45, 0xffffff80
	s_addc_u32 s49, s46, -1
	s_cmp_eq_u32 s47, 60
	s_cselect_b32 s22, s9, s45
	s_cselect_b32 s23, s7, s46
	s_cselect_b32 s25, s11, s44
	s_cselect_b32 s24, s13, s33
	s_add_u32 s18, s22, 0x80
	s_addc_u32 s19, s23, 0
	s_add_u32 s20, s24, 0x80
	s_addc_u32 s21, s25, 0
	s_add_i32 s50, 0, 0x10000
	s_add_i32 s51, 0, 0x14000
	v_add_u32_e32 v90, s50, v1
	v_add_u32_e32 v162, s51, v1
	ds_read_b128 v[78:81], v90
	ds_read_b128 v[82:85], v90 offset:1024
	ds_read_b128 v[86:89], v90 offset:2048
	ds_read_b128 v[90:93], v90 offset:3072
	ds_read_b128 v[142:145], v162
	ds_read_b128 v[146:149], v162 offset:1024
	ds_read_b128 v[158:161], v162 offset:2048
	ds_read_b128 v[162:165], v162 offset:3072
	s_add_u32 s48, s48, 0x100000
	s_addc_u32 s49, s49, 0
	v_lshl_add_u64 v[198:199], s[48:49], 0, v[2:3]
	s_add_i32 m0, s35, 0xc000
	ds_read_b128 v[166:169], v5
	ds_read_b128 v[170:173], v5 offset:1024
	ds_read_b128 v[174:177], v5 offset:2048
	ds_read_b128 v[178:181], v5 offset:3072
	ds_read_b128 v[182:185], v5 offset:4096
	ds_read_b128 v[186:189], v5 offset:5120
	ds_read_b128 v[190:193], v5 offset:6144
	ds_read_b128 v[194:197], v5 offset:7168
	global_load_lds_dwordx4 v[198:199], off
	v_lshl_add_u64 v[198:199], s[48:49], 0, v[218:219]
	s_add_i32 m0, s35, 0xe000
	s_nop 0
	global_load_lds_dwordx4 v[198:199], off
	s_waitcnt vmcnt(8)
	s_waitcnt lgkmcnt(0)
	s_barrier
	s_setprio 1
	v_mfma_f32_16x16x32_bf16 v[154:157], v[78:81], v[166:169], v[154:157]
	v_mfma_f32_16x16x32_bf16 v[150:153], v[86:89], v[166:169], v[150:153]
	v_mfma_f32_16x16x32_bf16 v[134:137], v[78:81], v[174:177], v[134:137]
	v_mfma_f32_16x16x32_bf16 v[126:129], v[86:89], v[174:177], v[126:129]
	v_mfma_f32_16x16x32_bf16 v[118:121], v[78:81], v[182:185], v[118:121]
	v_mfma_f32_16x16x32_bf16 v[110:113], v[86:89], v[182:185], v[110:113]
	v_mfma_f32_16x16x32_bf16 v[102:105], v[78:81], v[190:193], v[102:105]
	v_mfma_f32_16x16x32_bf16 v[94:97], v[86:89], v[190:193], v[94:97]
	v_mfma_f32_16x16x32_bf16 v[154:157], v[82:85], v[170:173], v[154:157]
	v_mfma_f32_16x16x32_bf16 v[150:153], v[90:93], v[170:173], v[150:153]
	v_mfma_f32_16x16x32_bf16 v[134:137], v[82:85], v[178:181], v[134:137]
	v_mfma_f32_16x16x32_bf16 v[126:129], v[90:93], v[178:181], v[126:129]
	v_mfma_f32_16x16x32_bf16 v[118:121], v[82:85], v[186:189], v[118:121]
	v_mfma_f32_16x16x32_bf16 v[110:113], v[90:93], v[186:189], v[110:113]
	v_mfma_f32_16x16x32_bf16 v[102:105], v[82:85], v[194:197], v[102:105]
	v_mfma_f32_16x16x32_bf16 v[94:97], v[90:93], v[194:197], v[94:97]
	v_mfma_f32_16x16x32_bf16 v[138:141], v[142:145], v[166:169], v[138:141]
	v_mfma_f32_16x16x32_bf16 v[130:133], v[158:161], v[166:169], v[130:133]
	v_mfma_f32_16x16x32_bf16 v[122:125], v[142:145], v[174:177], v[122:125]
	v_mfma_f32_16x16x32_bf16 v[114:117], v[158:161], v[174:177], v[114:117]
	v_mfma_f32_16x16x32_bf16 v[106:109], v[142:145], v[182:185], v[106:109]
	v_mfma_f32_16x16x32_bf16 v[98:101], v[158:161], v[182:185], v[98:101]
	v_mfma_f32_16x16x32_bf16 v[74:77], v[142:145], v[190:193], v[74:77]
	v_mfma_f32_16x16x32_bf16 v[70:73], v[158:161], v[190:193], v[70:73]
	v_mfma_f32_16x16x32_bf16 v[138:141], v[146:149], v[170:173], v[138:141]
	v_mfma_f32_16x16x32_bf16 v[130:133], v[162:165], v[170:173], v[130:133]
	v_mfma_f32_16x16x32_bf16 v[122:125], v[146:149], v[178:181], v[122:125]
	v_mfma_f32_16x16x32_bf16 v[114:117], v[162:165], v[178:181], v[114:117]
	v_mfma_f32_16x16x32_bf16 v[106:109], v[146:149], v[186:189], v[106:109]
	v_mfma_f32_16x16x32_bf16 v[98:101], v[162:165], v[186:189], v[98:101]
	v_mfma_f32_16x16x32_bf16 v[74:77], v[146:149], v[194:197], v[74:77]
	v_mfma_f32_16x16x32_bf16 v[70:73], v[162:165], v[194:197], v[70:73]
	s_setprio 0
	s_barrier
	s_add_i32 s48, s50, s29
	v_lshl_add_u64 v[198:199], s[24:25], 0, v[216:217]
	s_mov_b32 m0, s48
	ds_read_b128 v[166:169], v5 offset:16384
	ds_read_b128 v[170:173], v5 offset:17408
	ds_read_b128 v[174:177], v5 offset:18432
	ds_read_b128 v[178:181], v5 offset:19456
	ds_read_b128 v[182:185], v5 offset:20480
	ds_read_b128 v[186:189], v5 offset:21504
	ds_read_b128 v[190:193], v5 offset:22528
	ds_read_b128 v[194:197], v5 offset:23552
	global_load_lds_dwordx4 v[198:199], off
	s_add_i32 m0, s48, 0x2000
	v_lshl_add_u64 v[198:199], s[24:25], 0, v[220:221]
	s_add_u32 s24, s24, 0x100000
	s_addc_u32 s25, s25, 0
	s_add_i32 s48, s51, s29
	global_load_lds_dwordx4 v[198:199], off
	v_lshl_add_u64 v[198:199], s[24:25], 0, v[216:217]
	s_mov_b32 m0, s48
	s_nop 0
	global_load_lds_dwordx4 v[198:199], off
	v_lshl_add_u64 v[198:199], s[24:25], 0, v[220:221]
	s_add_i32 m0, s48, 0x2000
	s_nop 0
	global_load_lds_dwordx4 v[198:199], off
	v_lshl_add_u64 v[198:199], s[22:23], 0, v[2:3]
	s_mov_b32 m0, s35
	s_nop 0
	global_load_lds_dwordx4 v[198:199], off
	v_lshl_add_u64 v[198:199], s[22:23], 0, v[218:219]
	s_mov_b32 m0, s36
	s_nop 0
	global_load_lds_dwordx4 v[198:199], off
	s_waitcnt vmcnt(8)
	s_waitcnt lgkmcnt(0)
	s_barrier
	s_setprio 1
	v_mfma_f32_16x16x32_bf16 v[66:69], v[78:81], v[166:169], v[66:69]
	v_mfma_f32_16x16x32_bf16 v[62:65], v[86:89], v[166:169], v[62:65]
	v_mfma_f32_16x16x32_bf16 v[54:57], v[78:81], v[174:177], v[54:57]
	v_mfma_f32_16x16x32_bf16 v[46:49], v[86:89], v[174:177], v[46:49]
	v_mfma_f32_16x16x32_bf16 v[38:41], v[78:81], v[182:185], v[38:41]
	v_mfma_f32_16x16x32_bf16 v[30:33], v[86:89], v[182:185], v[30:33]
	v_mfma_f32_16x16x32_bf16 v[22:25], v[78:81], v[190:193], v[22:25]
	v_mfma_f32_16x16x32_bf16 v[14:17], v[86:89], v[190:193], v[14:17]
	v_mfma_f32_16x16x32_bf16 v[66:69], v[82:85], v[170:173], v[66:69]
	v_mfma_f32_16x16x32_bf16 v[62:65], v[90:93], v[170:173], v[62:65]
	v_mfma_f32_16x16x32_bf16 v[54:57], v[82:85], v[178:181], v[54:57]
	v_mfma_f32_16x16x32_bf16 v[46:49], v[90:93], v[178:181], v[46:49]
	v_mfma_f32_16x16x32_bf16 v[38:41], v[82:85], v[186:189], v[38:41]
	v_mfma_f32_16x16x32_bf16 v[30:33], v[90:93], v[186:189], v[30:33]
	v_mfma_f32_16x16x32_bf16 v[22:25], v[82:85], v[194:197], v[22:25]
	v_mfma_f32_16x16x32_bf16 v[14:17], v[90:93], v[194:197], v[14:17]
	v_mfma_f32_16x16x32_bf16 v[58:61], v[142:145], v[166:169], v[58:61]
	v_mfma_f32_16x16x32_bf16 v[50:53], v[158:161], v[166:169], v[50:53]
	v_mfma_f32_16x16x32_bf16 v[42:45], v[142:145], v[174:177], v[42:45]
	v_mfma_f32_16x16x32_bf16 v[34:37], v[158:161], v[174:177], v[34:37]
	v_mfma_f32_16x16x32_bf16 v[26:29], v[142:145], v[182:185], v[26:29]
	v_mfma_f32_16x16x32_bf16 v[18:21], v[158:161], v[182:185], v[18:21]
	v_mfma_f32_16x16x32_bf16 v[10:13], v[142:145], v[190:193], v[10:13]
	v_mfma_f32_16x16x32_bf16 v[6:9], v[158:161], v[190:193], v[6:9]
	v_mfma_f32_16x16x32_bf16 v[58:61], v[146:149], v[170:173], v[58:61]
	v_mfma_f32_16x16x32_bf16 v[50:53], v[162:165], v[170:173], v[50:53]
	v_mfma_f32_16x16x32_bf16 v[42:45], v[146:149], v[178:181], v[42:45]
	v_mfma_f32_16x16x32_bf16 v[34:37], v[162:165], v[178:181], v[34:37]
	v_mfma_f32_16x16x32_bf16 v[26:29], v[146:149], v[186:189], v[26:29]
	v_mfma_f32_16x16x32_bf16 v[18:21], v[162:165], v[186:189], v[18:21]
	v_mfma_f32_16x16x32_bf16 v[10:13], v[146:149], v[194:197], v[10:13]
	v_mfma_f32_16x16x32_bf16 v[6:9], v[162:165], v[194:197], v[6:9]
	s_setprio 0
	s_barrier
	s_add_i32 s24, 0, 0x18000
	s_add_i32 s25, 0, 0x1c000
	v_add_u32_e32 v90, s24, v1
	v_add_u32_e32 v162, s25, v1
	ds_read_b128 v[78:81], v90
	ds_read_b128 v[82:85], v90 offset:1024
	ds_read_b128 v[86:89], v90 offset:2048
	ds_read_b128 v[90:93], v90 offset:3072
	ds_read_b128 v[142:145], v162
	ds_read_b128 v[146:149], v162 offset:1024
	ds_read_b128 v[158:161], v162 offset:2048
	ds_read_b128 v[162:165], v162 offset:3072
	s_add_u32 s22, s22, 0x100000
	s_addc_u32 s23, s23, 0
	s_mov_b32 m0, s37
	v_lshl_add_u64 v[198:199], s[22:23], 0, v[2:3]
	ds_read_b128 v[166:169], v5 offset:32768
	ds_read_b128 v[170:173], v5 offset:33792
	ds_read_b128 v[174:177], v5 offset:34816
	ds_read_b128 v[178:181], v5 offset:35840
	ds_read_b128 v[182:185], v5 offset:36864
	ds_read_b128 v[186:189], v5 offset:37888
	ds_read_b128 v[190:193], v5 offset:38912
	ds_read_b128 v[194:197], v5 offset:39936
	global_load_lds_dwordx4 v[198:199], off
	v_lshl_add_u64 v[198:199], s[22:23], 0, v[218:219]
	s_mov_b32 m0, s38
	s_nop 0
	global_load_lds_dwordx4 v[198:199], off
	s_waitcnt vmcnt(8)
	s_waitcnt lgkmcnt(0)
	s_barrier
	s_setprio 1
	v_mfma_f32_16x16x32_bf16 v[154:157], v[78:81], v[166:169], v[154:157]
	v_mfma_f32_16x16x32_bf16 v[150:153], v[86:89], v[166:169], v[150:153]
	v_mfma_f32_16x16x32_bf16 v[134:137], v[78:81], v[174:177], v[134:137]
	v_mfma_f32_16x16x32_bf16 v[126:129], v[86:89], v[174:177], v[126:129]
	v_mfma_f32_16x16x32_bf16 v[118:121], v[78:81], v[182:185], v[118:121]
	v_mfma_f32_16x16x32_bf16 v[110:113], v[86:89], v[182:185], v[110:113]
	v_mfma_f32_16x16x32_bf16 v[102:105], v[78:81], v[190:193], v[102:105]
	v_mfma_f32_16x16x32_bf16 v[94:97], v[86:89], v[190:193], v[94:97]
	v_mfma_f32_16x16x32_bf16 v[154:157], v[82:85], v[170:173], v[154:157]
	v_mfma_f32_16x16x32_bf16 v[150:153], v[90:93], v[170:173], v[150:153]
	v_mfma_f32_16x16x32_bf16 v[134:137], v[82:85], v[178:181], v[134:137]
	v_mfma_f32_16x16x32_bf16 v[126:129], v[90:93], v[178:181], v[126:129]
	v_mfma_f32_16x16x32_bf16 v[118:121], v[82:85], v[186:189], v[118:121]
	v_mfma_f32_16x16x32_bf16 v[110:113], v[90:93], v[186:189], v[110:113]
	v_mfma_f32_16x16x32_bf16 v[102:105], v[82:85], v[194:197], v[102:105]
	v_mfma_f32_16x16x32_bf16 v[94:97], v[90:93], v[194:197], v[94:97]
	v_mfma_f32_16x16x32_bf16 v[138:141], v[142:145], v[166:169], v[138:141]
	v_mfma_f32_16x16x32_bf16 v[130:133], v[158:161], v[166:169], v[130:133]
	v_mfma_f32_16x16x32_bf16 v[122:125], v[142:145], v[174:177], v[122:125]
	v_mfma_f32_16x16x32_bf16 v[114:117], v[158:161], v[174:177], v[114:117]
	v_mfma_f32_16x16x32_bf16 v[106:109], v[142:145], v[182:185], v[106:109]
	v_mfma_f32_16x16x32_bf16 v[98:101], v[158:161], v[182:185], v[98:101]
	v_mfma_f32_16x16x32_bf16 v[74:77], v[142:145], v[190:193], v[74:77]
	v_mfma_f32_16x16x32_bf16 v[70:73], v[158:161], v[190:193], v[70:73]
	v_mfma_f32_16x16x32_bf16 v[138:141], v[146:149], v[170:173], v[138:141]
	v_mfma_f32_16x16x32_bf16 v[130:133], v[162:165], v[170:173], v[130:133]
	v_mfma_f32_16x16x32_bf16 v[122:125], v[146:149], v[178:181], v[122:125]
	v_mfma_f32_16x16x32_bf16 v[114:117], v[162:165], v[178:181], v[114:117]
	v_mfma_f32_16x16x32_bf16 v[106:109], v[146:149], v[186:189], v[106:109]
	v_mfma_f32_16x16x32_bf16 v[98:101], v[162:165], v[186:189], v[98:101]
	v_mfma_f32_16x16x32_bf16 v[74:77], v[146:149], v[194:197], v[74:77]
	v_mfma_f32_16x16x32_bf16 v[70:73], v[162:165], v[194:197], v[70:73]
	s_setprio 0
	s_barrier
	s_add_i32 s22, s24, s29
	v_lshl_add_u64 v[198:199], s[20:21], 0, v[216:217]
	s_mov_b32 m0, s22
	ds_read_b128 v[166:169], v5 offset:49152
	ds_read_b128 v[170:173], v5 offset:50176
	ds_read_b128 v[174:177], v5 offset:51200
	ds_read_b128 v[178:181], v5 offset:52224
	ds_read_b128 v[182:185], v5 offset:53248
	ds_read_b128 v[186:189], v5 offset:54272
	ds_read_b128 v[190:193], v5 offset:55296
	ds_read_b128 v[194:197], v5 offset:56320
	global_load_lds_dwordx4 v[198:199], off
	s_add_i32 m0, s22, 0x2000
	v_lshl_add_u64 v[198:199], s[20:21], 0, v[220:221]
	s_add_u32 s20, s20, 0x100000
	s_addc_u32 s21, s21, 0
	s_add_i32 s22, s25, s29
	global_load_lds_dwordx4 v[198:199], off
	v_lshl_add_u64 v[198:199], s[20:21], 0, v[216:217]
	s_mov_b32 m0, s22
	s_nop 0
	global_load_lds_dwordx4 v[198:199], off
	v_lshl_add_u64 v[198:199], s[20:21], 0, v[220:221]
	s_add_i32 m0, s22, 0x2000
	s_nop 0
	global_load_lds_dwordx4 v[198:199], off
	v_lshl_add_u64 v[198:199], s[18:19], 0, v[2:3]
	s_mov_b32 m0, s41
	s_nop 0
	global_load_lds_dwordx4 v[198:199], off
	v_lshl_add_u64 v[198:199], s[18:19], 0, v[218:219]
	s_mov_b32 m0, s42
	s_nop 0
	global_load_lds_dwordx4 v[198:199], off
	s_waitcnt vmcnt(8)
	s_waitcnt lgkmcnt(0)
	s_barrier
	s_setprio 1
	v_mfma_f32_16x16x32_bf16 v[66:69], v[78:81], v[166:169], v[66:69]
	v_mfma_f32_16x16x32_bf16 v[62:65], v[86:89], v[166:169], v[62:65]
	v_mfma_f32_16x16x32_bf16 v[54:57], v[78:81], v[174:177], v[54:57]
	v_mfma_f32_16x16x32_bf16 v[46:49], v[86:89], v[174:177], v[46:49]
	v_mfma_f32_16x16x32_bf16 v[38:41], v[78:81], v[182:185], v[38:41]
	v_mfma_f32_16x16x32_bf16 v[30:33], v[86:89], v[182:185], v[30:33]
	v_mfma_f32_16x16x32_bf16 v[22:25], v[78:81], v[190:193], v[22:25]
	v_mfma_f32_16x16x32_bf16 v[14:17], v[86:89], v[190:193], v[14:17]
	v_mfma_f32_16x16x32_bf16 v[66:69], v[82:85], v[170:173], v[66:69]
	v_mfma_f32_16x16x32_bf16 v[62:65], v[90:93], v[170:173], v[62:65]
	v_mfma_f32_16x16x32_bf16 v[54:57], v[82:85], v[178:181], v[54:57]
	v_mfma_f32_16x16x32_bf16 v[46:49], v[90:93], v[178:181], v[46:49]
	v_mfma_f32_16x16x32_bf16 v[38:41], v[82:85], v[186:189], v[38:41]
	v_mfma_f32_16x16x32_bf16 v[30:33], v[90:93], v[186:189], v[30:33]
	v_mfma_f32_16x16x32_bf16 v[22:25], v[82:85], v[194:197], v[22:25]
	v_mfma_f32_16x16x32_bf16 v[14:17], v[90:93], v[194:197], v[14:17]
	v_mfma_f32_16x16x32_bf16 v[58:61], v[142:145], v[166:169], v[58:61]
	v_mfma_f32_16x16x32_bf16 v[50:53], v[158:161], v[166:169], v[50:53]
	v_mfma_f32_16x16x32_bf16 v[42:45], v[142:145], v[174:177], v[42:45]
	v_mfma_f32_16x16x32_bf16 v[34:37], v[158:161], v[174:177], v[34:37]
	v_mfma_f32_16x16x32_bf16 v[26:29], v[142:145], v[182:185], v[26:29]
	v_mfma_f32_16x16x32_bf16 v[18:21], v[158:161], v[182:185], v[18:21]
	v_mfma_f32_16x16x32_bf16 v[10:13], v[142:145], v[190:193], v[10:13]
	v_mfma_f32_16x16x32_bf16 v[6:9], v[158:161], v[190:193], v[6:9]
	v_mfma_f32_16x16x32_bf16 v[58:61], v[146:149], v[170:173], v[58:61]
	v_mfma_f32_16x16x32_bf16 v[50:53], v[162:165], v[170:173], v[50:53]
	v_mfma_f32_16x16x32_bf16 v[42:45], v[146:149], v[178:181], v[42:45]
	v_mfma_f32_16x16x32_bf16 v[34:37], v[162:165], v[178:181], v[34:37]
	v_mfma_f32_16x16x32_bf16 v[26:29], v[146:149], v[186:189], v[26:29]
	v_mfma_f32_16x16x32_bf16 v[18:21], v[162:165], v[186:189], v[18:21]
	v_mfma_f32_16x16x32_bf16 v[10:13], v[146:149], v[194:197], v[10:13]
	v_mfma_f32_16x16x32_bf16 v[6:9], v[162:165], v[194:197], v[6:9]
	s_setprio 0
	s_barrier
	s_add_i32 s47, s47, 2
	s_add_u32 s33, s33, 0x100
	s_addc_u32 s44, s44, 0
	s_add_u32 s45, s45, 0x100
	s_addc_u32 s46, s46, 0
	s_cmp_gt_u32 s47, 61
	s_cbranch_scc0 .LBB0_924
	v_mov_b32_e32 v142, v0
	s_mov_b64 s[20:21], s[84:85]
	s_add_u32 s7, s20, 0x4179c000
	v_readlane_b32 s18, v254, 26
	s_addc_u32 s9, s21, 0
	v_readlane_b32 s19, v254, 27
	v_readlane_b32 s44, v253, 35
	s_and_b64 s[18:19], s[18:19], exec
	v_readlane_b32 s45, v253, 36
	v_bfe_u32 v144, v142, 4, 2
	s_cselect_b32 s23, s9, s45
	s_cselect_b32 s22, s7, s44
	s_cselect_b32 s19, s83, s9
	s_cselect_b32 s18, s82, s7
	s_lshl_b32 s7, s8, 8
	s_lshl_b32 s6, s6, 8
	v_lshl_or_b32 v78, v144, 3, s7
	s_add_i32 s6, s6, s39
	v_or_b32_e32 v226, s40, v78
	v_ashrrev_i32_e32 v227, 31, v226
	v_readlane_b32 s8, v254, 9
	v_and_or_b32 v230, v142, 15, s6
	v_lshlrev_b64 v[244:245], 2, v[226:227]
	v_readlane_b32 s9, v254, 10
	v_lshl_add_u64 v[142:143], v[226:227], 1, s[20:21]
	s_mov_b64 s[6:7], 0x10f80000
	v_ashrrev_i32_e32 v231, 31, v230
	v_or_b32_e32 v240, 16, v230
	v_lshl_add_u64 v[82:83], s[8:9], 0, v[244:245]
	v_lshl_add_u64 v[228:229], s[22:23], 0, v[244:245]
	v_lshl_add_u64 v[224:225], v[142:143], 0, s[6:7]
	v_lshl_add_u64 v[142:143], v[230:231], 2, s[20:21]
	s_mov_b64 s[8:9], 0x18400
	v_lshlrev_b64 v[248:249], 14, v[230:231]
	v_ashrrev_i32_e32 v241, 31, v240
	v_or_b32_e32 v236, 32, v230
	v_or_b32_e32 v232, 48, v230
	v_lshl_add_u64 v[222:223], v[142:143], 0, s[8:9]
	v_lshl_add_u64 v[142:143], v[228:229], 0, v[248:249]
	v_lshlrev_b64 v[242:243], 14, v[240:241]
	v_ashrrev_i32_e32 v237, 31, v236
	v_ashrrev_i32_e32 v233, 31, v232
	global_load_dwordx4 v[86:89], v[82:83], off offset:16
	global_load_dwordx4 v[90:93], v[82:83], off
	global_load_dwordx4 v[78:81], v[82:83], off offset:528
	s_nop 0
	global_load_dwordx4 v[82:85], v[82:83], off offset:512
	s_nop 0
	global_load_dwordx4 v[206:209], v[142:143], off offset:16
	global_load_dwordx4 v[210:213], v[142:143], off
	global_load_dwordx4 v[198:201], v[142:143], off offset:528
	global_load_dwordx4 v[202:205], v[142:143], off offset:512
	v_lshl_add_u64 v[142:143], v[228:229], 0, v[242:243]
	v_lshlrev_b64 v[238:239], 14, v[236:237]
	v_lshlrev_b64 v[234:235], 14, v[232:233]
	global_load_dwordx4 v[190:193], v[142:143], off offset:16
	global_load_dwordx4 v[194:197], v[142:143], off
	global_load_dwordx4 v[182:185], v[142:143], off offset:528
	global_load_dwordx4 v[186:189], v[142:143], off offset:512
	v_lshl_add_u64 v[142:143], v[228:229], 0, v[238:239]
	v_lshl_add_u64 v[146:147], v[228:229], 0, v[234:235]
	v_cmp_eq_u32_e64 s[6:7], 0, v144
	global_load_dwordx4 v[174:177], v[142:143], off offset:16
	global_load_dwordx4 v[178:181], v[142:143], off
	global_load_dwordx4 v[166:169], v[142:143], off offset:528
	global_load_dwordx4 v[170:173], v[142:143], off offset:512
	global_load_dwordx4 v[158:161], v[146:147], off offset:16
	global_load_dwordx4 v[162:165], v[146:147], off
	s_nop 0
	global_load_dwordx4 v[142:145], v[146:147], off offset:528
	s_nop 0
	global_load_dwordx4 v[146:149], v[146:147], off offset:512
	v_lshl_add_u64 v[248:249], s[18:19], 0, v[248:249]
	v_lshl_add_u64 v[244:245], v[248:249], 0, v[244:245]
	s_mov_b64 s[20:21], -1
	s_andn2_b64 vcc, exec, s[60:61]
	v_readlane_b32 s46, v253, 37
	v_readlane_b32 s47, v253, 38
	v_readlane_b32 s48, v253, 39
	v_readlane_b32 s49, v253, 40
	v_readlane_b32 s50, v253, 41
	v_readlane_b32 s51, v253, 42
	v_readlane_b32 s52, v253, 43
	v_readlane_b32 s53, v253, 44
	v_readlane_b32 s54, v253, 45
	v_readlane_b32 s55, v253, 46
	v_readlane_b32 s56, v253, 47
	v_readlane_b32 s57, v253, 48
	v_readlane_b32 s58, v253, 49
	v_readlane_b32 s59, v253, 50
	s_waitcnt vmcnt(0)
	v_pk_add_f32 v[206:207], v[150:151], v[206:207]
	v_cndmask_b32_e64 v150, 0, 1, s[60:61]
	v_pk_add_f32 v[212:213], v[156:157], v[212:213]
	v_pk_add_f32 v[210:211], v[154:155], v[210:211]
	v_pk_add_f32 v[208:209], v[152:153], v[208:209]
	v_cmp_ne_u32_e64 s[8:9], 1, v150
	v_pk_add_f32 v[150:151], v[138:139], v[202:203]
	v_pk_add_f32 v[154:155], v[130:131], v[198:199]
	global_store_dwordx4 v[244:245], v[210:213], off
	global_store_dwordx4 v[244:245], v[206:209], off offset:16
	s_cbranch_vccnz .LBB0_929
	v_mul_f32_e32 v138, v211, v211
	v_mul_f32_e32 v139, v213, v213
	v_fmac_f32_e32 v138, v210, v210
	v_fmac_f32_e32 v139, v212, v212
	v_add_f32_e32 v138, v138, v139
	v_mul_f32_e32 v139, v207, v207
	v_fmac_f32_e32 v139, v206, v206
	v_add_f32_e32 v138, v138, v139
	v_mul_f32_e32 v139, v209, v209
	v_lshlrev_b64 v[130:131], 12, v[230:231]
	v_fmac_f32_e32 v139, v208, v208
	v_pk_mul_f32 v[152:153], v[90:91], v[210:211]
	v_pk_mul_f32 v[156:157], v[88:89], v[208:209]
	v_lshl_add_u64 v[130:131], v[130:131], 1, v[224:225]
	v_add_f32_e32 v231, v139, v138
	v_pk_mul_f32 v[138:139], v[92:93], v[212:213]
	v_pk_mul_f32 v[198:199], v[86:87], v[206:207]
	v_cvt_pk_bf16_f32 v206, v152, v153
	v_cvt_pk_bf16_f32 v207, v138, v139
	v_pk_add_f32 v[152:153], v[140:141], v[204:205]
	v_cvt_pk_bf16_f32 v208, v198, v199
	v_cvt_pk_bf16_f32 v209, v156, v157
	v_pk_add_f32 v[156:157], v[132:133], v[200:201]
	global_store_dwordx4 v[130:131], v[206:209], off
	global_store_dwordx4 v[244:245], v[150:153], off offset:512
	global_store_dwordx4 v[244:245], v[154:157], off offset:528
	v_pk_mul_f32 v[202:203], v[80:81], v[156:157]
	v_pk_mul_f32 v[138:139], v[84:85], v[152:153]
	v_mul_f32_e32 v157, v157, v157
	v_fmac_f32_e32 v157, v156, v156
	v_mul_f32_e32 v156, v151, v151
	v_mul_f32_e32 v153, v153, v153
	v_fmac_f32_e32 v156, v150, v150
	v_fmac_f32_e32 v153, v152, v152
	v_add_f32_e32 v152, v156, v153
	v_mul_f32_e32 v153, v155, v155
	v_fmac_f32_e32 v153, v154, v154
	v_add_f32_e32 v152, v152, v153
	v_add_f32_e32 v152, v157, v152
	v_add_f32_e32 v152, v231, v152
	ds_swizzle_b32 v153, v152 offset:swizzle(SWAP,16)
	v_pk_mul_f32 v[208:209], v[78:79], v[154:155]
	v_pk_mul_f32 v[198:199], v[82:83], v[150:151]
	s_nop 0
	v_cvt_pk_bf16_f32 v206, v198, v199
	v_cvt_pk_bf16_f32 v207, v138, v139
	v_cvt_pk_bf16_f32 v208, v208, v209
	v_cvt_pk_bf16_f32 v209, v202, v203
	global_store_dwordx4 v[130:131], v[206:209], off offset:256
	s_waitcnt lgkmcnt(0)
	v_add_f32_e32 v130, v152, v153
	v_mov_b32_e32 v131, v130
	s_nop 1
	v_permlane32_swap_b32_e32 v130, v131
	s_and_saveexec_b64 s[20:21], s[6:7]
	s_cbranch_execz .LBB0_928
	v_add_f32_e32 v130, v130, v131
	global_atomic_add_f32 v[222:223], v130, off
